# speedup vs baseline: 1.0354x; 1.0352x over previous
; __device__ __forceinline__ void phase_peer_v(const Params& p, int layer, int xs, int wid0, int wstride, bool last, char* smraw) {
;   const int tid = tid_opaque(), w = tid >> 6, l = tid & 63, g = l >> 3, j = l & 7;
;   const int wid = wid0 + w;
;   const int sl = xs >> 1, par = xs & 1;
;   constexpr int TH = T / 2;
;   float* red = (float*)smraw + w * 2048;
;   const unsigned char* Vq = p.Vq + (size_t)(layer * 4 + sl) * NEXP * 128;
;   const unsigned joff = j * 16;
;   u32x4 ni[4]; f32x4 nc[4];
;   auto load_idx = [&](int tt) {
;     const unsigned o = (unsigned)(2 * tt + par) * 512u + (unsigned)g * 64u;
;     const u32x4* ip = (const u32x4*)((const char*)p.sel_idx + o);
;     const f32x4* cp = (const f32x4*)((const char*)p.coef + o);
; #pragma unroll
;     for (int q4 = 0; q4 < 4; ++q4) { ni[q4] = ip[q4]; nc[q4] = cp[q4]; }
;   };
;   u32x4 qA[8];
;   float acc[32];
;   auto half_fma = [&](const u32x4 (&q)[8], const f32x4& c0, const f32x4& c1) {
; #pragma unroll
;     for (int i = 0; i < 8; ++i) {
;       const float ci = i < 4 ? c0[i & 3] : c1[i & 3];
; #pragma unroll
;       for (int m = 0; m < 4; ++m) {
;         unsigned dw = q[i][m];
;         asm volatile("" : "+v"(dw) : "v"(acc[(8 * m + 31) & 31]));
;         const f32x2 e0 = __builtin_amdgcn_cvt_scalef32_pk_f32_fp4(dw, 1.0f, 0), e1 = __builtin_amdgcn_cvt_scalef32_pk_f32_fp4(dw, 1.0f, 1);
;         const f32x2 e2 = __builtin_amdgcn_cvt_scalef32_pk_f32_fp4(dw, 1.0f, 2), e3 = __builtin_amdgcn_cvt_scalef32_pk_f32_fp4(dw, 1.0f, 3);
;         acc[8 * m + 0] += ci * e0[0]; acc[8 * m + 1] += ci * e0[1]; acc[8 * m + 2] += ci * e1[0]; acc[8 * m + 3] += ci * e1[1];
;         acc[8 * m + 4] += ci * e2[0]; acc[8 * m + 5] += ci * e2[1]; acc[8 * m + 6] += ci * e3[0]; acc[8 * m + 7] += ci * e3[1];
;       }
;     }
;   };
;   int tt = wid;
;   if (tt < TH) load_idx(tt);
;   while (tt < TH) {
;     const int tn = tt + wstride;
;     const int t = 2 * tt + par;
; #pragma unroll
;     for (int i = 0; i < 8; ++i) qA[i] = *(const u32x4*)(Vq + (ni[i >> 2][i & 3] * 128u + joff));
;     float* hq = hrow(p, t) + sl * 256 + 4 * l;
;     f32x4 hv = *(const f32x4*)hq;
;     const f32x4 c0 = nc[0], c1 = nc[1], c2 = nc[2], c3 = nc[3];
;     ...
;     for (int q4 = 0; q4 < 8; ++q4) *(f32x4*)(red + g * 256 + j * 32 + q4 * 4) = f32x4{acc[q4 * 4], acc[q4 * 4 + 1], acc[q4 * 4 + 2], acc[q4 * 4 + 3]};
.LBB0_782:
	s_or_b64 exec, exec, s[6:7]
	v_mov_b32_e32 v25, v189
	s_barrier
	v_and_b32_e32 v6, 63, v189
	v_lshrrev_b32_e32 v7, 6, v189
	v_lshlrev_b32_e32 v0, 4, v6
	v_and_b32_e32 v1, 7, v6
	v_lshlrev_b32_e32 v1, 4, v1
	v_lshrrev_b32_e32 v8, 3, v6
	v_readfirstlane_b32 s0, v7
	s_lshl_b32 s1, s28, 9
	v_lshl_add_u32 v2, v8, 6, s1
	v_lshlrev_b32_e32 v3, 13, v7
	v_xor_b32_e32 v4, v6, v8
	v_lshl_add_u32 v4, v4, 4, v3
	v_lshl_add_u32 v3, v8, 10, v3
	v_lshl_add_u32 v3, v1, 3, v3
	v_xor_b32_e32 v240, 0, v1
	v_xor_b32_e32 v241, 16, v1
	v_xor_b32_e32 v242, 32, v1
	v_xor_b32_e32 v243, 48, v1
	v_xor_b32_e32 v244, 64, v1
	v_xor_b32_e32 v245, 80, v1
	v_xor_b32_e32 v246, 96, v1
	v_xor_b32_e32 v247, 112, v1
	v_add_u32_e32 v240, v240, v3
	v_add_u32_e32 v241, v241, v3
	v_add_u32_e32 v242, v242, v3
	v_add_u32_e32 v243, v243, v3
	v_add_u32_e32 v244, v244, v3
	v_add_u32_e32 v245, v245, v3
	v_add_u32_e32 v246, v246, v3
	v_add_u32_e32 v247, v247, v3
	v_lshlrev_b32_e32 v5, 3, v6
	s_add_u32 s36, s92, s0
	s_movk_i32 s38, 0x4020
	s_cmp_ge_u32 s36, s38
	s_cbranch_scc1 .Lmy_pv0_done
	s_lshl_b32 s0, s14, 21
	s_add_u32 s40, s90, s0
	s_addc_u32 s41, s91, 0
	v_readlane_b32 s42, v254, 6
	v_readlane_b32 s43, v254, 7
	v_readlane_b32 s10, v254, 30
	v_readlane_b32 s11, v254, 31
	v_readlane_b32 s12, v254, 32
	v_readlane_b32 s13, v254, 33
	s_lshl_b32 s39, s14, 10
	s_mov_b32 s49, 0x7fc02
	s_sub_u32 s10, s10, 0x10000
	s_subb_u32 s11, s11, 0
	s_lshl_b32 s0, s36, 10
	v_add_u32_e32 v9, s0, v2
	global_load_dwordx4 v[10:13], v9, s[52:53]
	global_load_dwordx4 v[14:17], v9, s[52:53] offset:16
	global_load_dwordx4 v[18:21], v9, s[52:53] offset:32
	global_load_dwordx4 v[22:25], v9, s[52:53] offset:48
	s_waitcnt vmcnt(0)
	v_lshl_add_u32 v6, v10, 7, v1
	global_load_dwordx4 v[106:109], v6, s[40:41]
	v_lshl_add_u32 v7, v11, 7, v1
	global_load_dwordx4 v[110:113], v7, s[40:41]
	v_lshl_add_u32 v6, v12, 7, v1
	global_load_dwordx4 v[114:117], v6, s[40:41]
	v_lshl_add_u32 v7, v13, 7, v1
	global_load_dwordx4 v[118:121], v7, s[40:41]
	v_lshl_add_u32 v6, v14, 7, v1
	global_load_dwordx4 v[122:125], v6, s[40:41]
	v_lshl_add_u32 v7, v15, 7, v1
	global_load_dwordx4 v[126:129], v7, s[40:41]
	v_lshl_add_u32 v6, v16, 7, v1
	global_load_dwordx4 v[130:133], v6, s[40:41]
	v_lshl_add_u32 v7, v17, 7, v1
	global_load_dwordx4 v[134:137], v7, s[40:41]
	v_lshl_add_u32 v6, v18, 7, v1
	global_load_dwordx4 v[138:141], v6, s[40:41]
	v_lshl_add_u32 v7, v19, 7, v1
	global_load_dwordx4 v[142:145], v7, s[40:41]
	v_lshl_add_u32 v6, v20, 7, v1
	global_load_dwordx4 v[146:149], v6, s[40:41]
	v_lshl_add_u32 v7, v21, 7, v1
	global_load_dwordx4 v[150:153], v7, s[40:41]
	v_lshl_add_u32 v6, v22, 7, v1
	global_load_dwordx4 v[154:157], v6, s[40:41]
	v_lshl_add_u32 v7, v23, 7, v1
	global_load_dwordx4 v[158:161], v7, s[40:41]
	v_lshl_add_u32 v6, v24, 7, v1
	global_load_dwordx4 v[162:165], v6, s[40:41]
	v_lshl_add_u32 v7, v25, 7, v1
	global_load_dwordx4 v[166:169], v7, s[40:41]
	s_lshl_b32 s0, s36, 1
	s_add_u32 s0, s0, s28
	s_mul_hi_u32 s1, s0, s49
	s_mul_i32 s3, s1, 0x2010
	s_sub_u32 s3, s0, s3
	s_lshl_b32 s6, s1, 13
	s_add_u32 s6, s6, s3
	s_lshl_b32 s7, s1, 4
	s_add_u32 s7, s7, s3
	s_cmp_lt_u32 s3, 16
	s_cselect_b32 s6, s7, s6
	s_cselect_b32 s7, s12, s10
	s_cselect_b32 s8, s13, s11
	s_lshl_b32 s6, s6, 12
	s_add_u32 s6, s6, s39
	s_add_u32 s44, s7, s6
	s_addc_u32 s45, s8, 0
	global_load_dwordx4 v[58:61], v0, s[44:45]
	s_lshl_b32 s0, s36, 10
	v_add_u32_e32 v8, s0, v2
	global_load_dwordx4 v[26:29], v8, s[42:43]
	global_load_dwordx4 v[30:33], v8, s[42:43] offset:16
	global_load_dwordx4 v[34:37], v8, s[42:43] offset:32
	global_load_dwordx4 v[38:41], v8, s[42:43] offset:48
	s_add_u32 s51, s36, s33
	s_cmp_ge_u32 s51, s38
	s_cbranch_scc1 .Lmy_pv0_pro1
	s_lshl_b32 s0, s51, 10
	v_add_u32_e32 v9, s0, v2
	global_load_dwordx4 v[10:13], v9, s[52:53]
	global_load_dwordx4 v[14:17], v9, s[52:53] offset:16
	global_load_dwordx4 v[18:21], v9, s[52:53] offset:32
	global_load_dwordx4 v[22:25], v9, s[52:53] offset:48

; __device__ __forceinline__ void phase_peer_v(const Params& p, int layer, int xs, int wid0, int wstride, bool last, char* smraw) {
;     ...
;   auto half_fma = [&](const u32x4 (&q)[8], const f32x4& c0, const f32x4& c1) {
; #pragma unroll
;     for (int i = 0; i < 8; ++i) {
;       const float ci = i < 4 ? c0[i & 3] : c1[i & 3];
; #pragma unroll
;       for (int m = 0; m < 4; ++m) {
;         unsigned dw = q[i][m];
;         asm volatile("" : "+v"(dw) : "v"(acc[(8 * m + 31) & 31]));
;         const f32x2 e0 = __builtin_amdgcn_cvt_scalef32_pk_f32_fp4(dw, 1.0f, 0), e1 = __builtin_amdgcn_cvt_scalef32_pk_f32_fp4(dw, 1.0f, 1);
;         const f32x2 e2 = __builtin_amdgcn_cvt_scalef32_pk_f32_fp4(dw, 1.0f, 2), e3 = __builtin_amdgcn_cvt_scalef32_pk_f32_fp4(dw, 1.0f, 3);
;         acc[8 * m + 0] += ci * e0[0]; acc[8 * m + 1] += ci * e0[1]; acc[8 * m + 2] += ci * e1[0]; acc[8 * m + 3] += ci * e1[1];
;         acc[8 * m + 4] += ci * e2[0]; acc[8 * m + 5] += ci * e2[1]; acc[8 * m + 6] += ci * e3[0]; acc[8 * m + 7] += ci * e3[1];
;       }
;     }
;   };
.Lmy_pv0_noissueA:
	v_cvt_scalef32_pk_f32_fp4 v[98:99], v106, 1.0
	v_cvt_scalef32_pk_f32_fp4 v[100:101], v106, 1.0 op_sel:[1,0,0]
	v_cvt_scalef32_pk_f32_fp4 v[102:103], v106, 1.0 op_sel:[0,1,0]
	v_cvt_scalef32_pk_f32_fp4 v[104:105], v106, 1.0 op_sel:[1,1,0]
	v_pk_fma_f32 v[66:67], v[26:27], v[98:99], 0 op_sel_hi:[0,1,0]
	v_pk_fma_f32 v[68:69], v[26:27], v[100:101], 0 op_sel_hi:[0,1,0]
	v_pk_fma_f32 v[70:71], v[26:27], v[102:103], 0 op_sel_hi:[0,1,0]
	v_pk_fma_f32 v[72:73], v[26:27], v[104:105], 0 op_sel_hi:[0,1,0]
	v_cvt_scalef32_pk_f32_fp4 v[98:99], v107, 1.0
	v_cvt_scalef32_pk_f32_fp4 v[100:101], v107, 1.0 op_sel:[1,0,0]
	v_cvt_scalef32_pk_f32_fp4 v[102:103], v107, 1.0 op_sel:[0,1,0]
	v_cvt_scalef32_pk_f32_fp4 v[104:105], v107, 1.0 op_sel:[1,1,0]
	v_pk_fma_f32 v[74:75], v[26:27], v[98:99], 0 op_sel_hi:[0,1,0]
	v_pk_fma_f32 v[76:77], v[26:27], v[100:101], 0 op_sel_hi:[0,1,0]
	v_pk_fma_f32 v[78:79], v[26:27], v[102:103], 0 op_sel_hi:[0,1,0]
	v_pk_fma_f32 v[80:81], v[26:27], v[104:105], 0 op_sel_hi:[0,1,0]
	v_cvt_scalef32_pk_f32_fp4 v[98:99], v108, 1.0
	v_cvt_scalef32_pk_f32_fp4 v[100:101], v108, 1.0 op_sel:[1,0,0]
	v_cvt_scalef32_pk_f32_fp4 v[102:103], v108, 1.0 op_sel:[0,1,0]
	v_cvt_scalef32_pk_f32_fp4 v[104:105], v108, 1.0 op_sel:[1,1,0]
	v_pk_fma_f32 v[82:83], v[26:27], v[98:99], 0 op_sel_hi:[0,1,0]
	v_pk_fma_f32 v[84:85], v[26:27], v[100:101], 0 op_sel_hi:[0,1,0]
	v_pk_fma_f32 v[86:87], v[26:27], v[102:103], 0 op_sel_hi:[0,1,0]
	v_pk_fma_f32 v[88:89], v[26:27], v[104:105], 0 op_sel_hi:[0,1,0]
	v_cvt_scalef32_pk_f32_fp4 v[98:99], v109, 1.0
	v_cvt_scalef32_pk_f32_fp4 v[100:101], v109, 1.0 op_sel:[1,0,0]
	v_cvt_scalef32_pk_f32_fp4 v[102:103], v109, 1.0 op_sel:[0,1,0]
	v_cvt_scalef32_pk_f32_fp4 v[104:105], v109, 1.0 op_sel:[1,1,0]
	v_pk_fma_f32 v[90:91], v[26:27], v[98:99], 0 op_sel_hi:[0,1,0]
	v_pk_fma_f32 v[92:93], v[26:27], v[100:101], 0 op_sel_hi:[0,1,0]
	v_pk_fma_f32 v[94:95], v[26:27], v[102:103], 0 op_sel_hi:[0,1,0]
	v_pk_fma_f32 v[96:97], v[26:27], v[104:105], 0 op_sel_hi:[0,1,0]
	v_cvt_scalef32_pk_f32_fp4 v[98:99], v110, 1.0
	v_cvt_scalef32_pk_f32_fp4 v[100:101], v110, 1.0 op_sel:[1,0,0]
	v_cvt_scalef32_pk_f32_fp4 v[102:103], v110, 1.0 op_sel:[0,1,0]
	v_cvt_scalef32_pk_f32_fp4 v[104:105], v110, 1.0 op_sel:[1,1,0]
	v_pk_fma_f32 v[66:67], v[26:27], v[98:99], v[66:67] op_sel:[1,0,0] op_sel_hi:[1,1,1]
	v_pk_fma_f32 v[68:69], v[26:27], v[100:101], v[68:69] op_sel:[1,0,0] op_sel_hi:[1,1,1]
	v_pk_fma_f32 v[70:71], v[26:27], v[102:103], v[70:71] op_sel:[1,0,0] op_sel_hi:[1,1,1]
	v_pk_fma_f32 v[72:73], v[26:27], v[104:105], v[72:73] op_sel:[1,0,0] op_sel_hi:[1,1,1]
	v_cvt_scalef32_pk_f32_fp4 v[98:99], v111, 1.0
	v_cvt_scalef32_pk_f32_fp4 v[100:101], v111, 1.0 op_sel:[1,0,0]
	v_cvt_scalef32_pk_f32_fp4 v[102:103], v111, 1.0 op_sel:[0,1,0]
	v_cvt_scalef32_pk_f32_fp4 v[104:105], v111, 1.0 op_sel:[1,1,0]
	v_pk_fma_f32 v[74:75], v[26:27], v[98:99], v[74:75] op_sel:[1,0,0] op_sel_hi:[1,1,1]
	v_pk_fma_f32 v[76:77], v[26:27], v[100:101], v[76:77] op_sel:[1,0,0] op_sel_hi:[1,1,1]
	v_pk_fma_f32 v[78:79], v[26:27], v[102:103], v[78:79] op_sel:[1,0,0] op_sel_hi:[1,1,1]
	v_pk_fma_f32 v[80:81], v[26:27], v[104:105], v[80:81] op_sel:[1,0,0] op_sel_hi:[1,1,1]
	v_cvt_scalef32_pk_f32_fp4 v[98:99], v112, 1.0
	v_cvt_scalef32_pk_f32_fp4 v[100:101], v112, 1.0 op_sel:[1,0,0]
	v_cvt_scalef32_pk_f32_fp4 v[102:103], v112, 1.0 op_sel:[0,1,0]
	v_cvt_scalef32_pk_f32_fp4 v[104:105], v112, 1.0 op_sel:[1,1,0]
	v_pk_fma_f32 v[82:83], v[26:27], v[98:99], v[82:83] op_sel:[1,0,0] op_sel_hi:[1,1,1]
	v_pk_fma_f32 v[84:85], v[26:27], v[100:101], v[84:85] op_sel:[1,0,0] op_sel_hi:[1,1,1]
	v_pk_fma_f32 v[86:87], v[26:27], v[102:103], v[86:87] op_sel:[1,0,0] op_sel_hi:[1,1,1]
	v_pk_fma_f32 v[88:89], v[26:27], v[104:105], v[88:89] op_sel:[1,0,0] op_sel_hi:[1,1,1]
	v_cvt_scalef32_pk_f32_fp4 v[98:99], v113, 1.0
	v_cvt_scalef32_pk_f32_fp4 v[100:101], v113, 1.0 op_sel:[1,0,0]
	v_cvt_scalef32_pk_f32_fp4 v[102:103], v113, 1.0 op_sel:[0,1,0]
	v_cvt_scalef32_pk_f32_fp4 v[104:105], v113, 1.0 op_sel:[1,1,0]
	v_pk_fma_f32 v[90:91], v[26:27], v[98:99], v[90:91] op_sel:[1,0,0] op_sel_hi:[1,1,1]
	v_pk_fma_f32 v[92:93], v[26:27], v[100:101], v[92:93] op_sel:[1,0,0] op_sel_hi:[1,1,1]
	v_pk_fma_f32 v[94:95], v[26:27], v[102:103], v[94:95] op_sel:[1,0,0] op_sel_hi:[1,1,1]
	v_pk_fma_f32 v[96:97], v[26:27], v[104:105], v[96:97] op_sel:[1,0,0] op_sel_hi:[1,1,1]
	v_cvt_scalef32_pk_f32_fp4 v[98:99], v114, 1.0
	v_cvt_scalef32_pk_f32_fp4 v[100:101], v114, 1.0 op_sel:[1,0,0]
	v_cvt_scalef32_pk_f32_fp4 v[102:103], v114, 1.0 op_sel:[0,1,0]
	v_cvt_scalef32_pk_f32_fp4 v[104:105], v114, 1.0 op_sel:[1,1,0]
	v_pk_fma_f32 v[66:67], v[28:29], v[98:99], v[66:67] op_sel_hi:[0,1,1]
	v_pk_fma_f32 v[68:69], v[28:29], v[100:101], v[68:69] op_sel_hi:[0,1,1]
	v_pk_fma_f32 v[70:71], v[28:29], v[102:103], v[70:71] op_sel_hi:[0,1,1]
	v_pk_fma_f32 v[72:73], v[28:29], v[104:105], v[72:73] op_sel_hi:[0,1,1]
	v_cvt_scalef32_pk_f32_fp4 v[98:99], v115, 1.0
	v_cvt_scalef32_pk_f32_fp4 v[100:101], v115, 1.0 op_sel:[1,0,0]
	v_cvt_scalef32_pk_f32_fp4 v[102:103], v115, 1.0 op_sel:[0,1,0]
	v_cvt_scalef32_pk_f32_fp4 v[104:105], v115, 1.0 op_sel:[1,1,0]
	v_pk_fma_f32 v[74:75], v[28:29], v[98:99], v[74:75] op_sel_hi:[0,1,1]
	v_pk_fma_f32 v[76:77], v[28:29], v[100:101], v[76:77] op_sel_hi:[0,1,1]
	v_pk_fma_f32 v[78:79], v[28:29], v[102:103], v[78:79] op_sel_hi:[0,1,1]
	v_pk_fma_f32 v[80:81], v[28:29], v[104:105], v[80:81] op_sel_hi:[0,1,1]
	v_cvt_scalef32_pk_f32_fp4 v[98:99], v116, 1.0
	v_cvt_scalef32_pk_f32_fp4 v[100:101], v116, 1.0 op_sel:[1,0,0]
	v_cvt_scalef32_pk_f32_fp4 v[102:103], v116, 1.0 op_sel:[0,1,0]
; __device__ __forceinline__ void phase_peer_v(const Params& p, int layer, int xs, int wid0, int wstride, bool last, char* smraw) {
;     ...
;   auto half_fma = [&](const u32x4 (&q)[8], const f32x4& c0, const f32x4& c1) {
; #pragma unroll
;     for (int i = 0; i < 8; ++i) {
;       const float ci = i < 4 ? c0[i & 3] : c1[i & 3];
; #pragma unroll
;       for (int m = 0; m < 4; ++m) {
;         unsigned dw = q[i][m];
;         asm volatile("" : "+v"(dw) : "v"(acc[(8 * m + 31) & 31]));
;         const f32x2 e0 = __builtin_amdgcn_cvt_scalef32_pk_f32_fp4(dw, 1.0f, 0), e1 = __builtin_amdgcn_cvt_scalef32_pk_f32_fp4(dw, 1.0f, 1);
;         const f32x2 e2 = __builtin_amdgcn_cvt_scalef32_pk_f32_fp4(dw, 1.0f, 2), e3 = __builtin_amdgcn_cvt_scalef32_pk_f32_fp4(dw, 1.0f, 3);
;         acc[8 * m + 0] += ci * e0[0]; acc[8 * m + 1] += ci * e0[1]; acc[8 * m + 2] += ci * e1[0]; acc[8 * m + 3] += ci * e1[1];
;         acc[8 * m + 4] += ci * e2[0]; acc[8 * m + 5] += ci * e2[1]; acc[8 * m + 6] += ci * e3[0]; acc[8 * m + 7] += ci * e3[1];
;       }
;     }
;   };
	v_cvt_scalef32_pk_f32_fp4 v[104:105], v116, 1.0 op_sel:[1,1,0]
	v_pk_fma_f32 v[82:83], v[28:29], v[98:99], v[82:83] op_sel_hi:[0,1,1]
	v_pk_fma_f32 v[84:85], v[28:29], v[100:101], v[84:85] op_sel_hi:[0,1,1]
	v_pk_fma_f32 v[86:87], v[28:29], v[102:103], v[86:87] op_sel_hi:[0,1,1]
	v_pk_fma_f32 v[88:89], v[28:29], v[104:105], v[88:89] op_sel_hi:[0,1,1]
	v_cvt_scalef32_pk_f32_fp4 v[98:99], v117, 1.0
	v_cvt_scalef32_pk_f32_fp4 v[100:101], v117, 1.0 op_sel:[1,0,0]
	v_cvt_scalef32_pk_f32_fp4 v[102:103], v117, 1.0 op_sel:[0,1,0]
	v_cvt_scalef32_pk_f32_fp4 v[104:105], v117, 1.0 op_sel:[1,1,0]
	v_pk_fma_f32 v[90:91], v[28:29], v[98:99], v[90:91] op_sel_hi:[0,1,1]
	v_pk_fma_f32 v[92:93], v[28:29], v[100:101], v[92:93] op_sel_hi:[0,1,1]
	v_pk_fma_f32 v[94:95], v[28:29], v[102:103], v[94:95] op_sel_hi:[0,1,1]
	v_pk_fma_f32 v[96:97], v[28:29], v[104:105], v[96:97] op_sel_hi:[0,1,1]
	v_cvt_scalef32_pk_f32_fp4 v[98:99], v118, 1.0
	v_cvt_scalef32_pk_f32_fp4 v[100:101], v118, 1.0 op_sel:[1,0,0]
	v_cvt_scalef32_pk_f32_fp4 v[102:103], v118, 1.0 op_sel:[0,1,0]
	v_cvt_scalef32_pk_f32_fp4 v[104:105], v118, 1.0 op_sel:[1,1,0]
	v_pk_fma_f32 v[66:67], v[28:29], v[98:99], v[66:67] op_sel:[1,0,0] op_sel_hi:[1,1,1]
	v_pk_fma_f32 v[68:69], v[28:29], v[100:101], v[68:69] op_sel:[1,0,0] op_sel_hi:[1,1,1]
	v_pk_fma_f32 v[70:71], v[28:29], v[102:103], v[70:71] op_sel:[1,0,0] op_sel_hi:[1,1,1]
	v_pk_fma_f32 v[72:73], v[28:29], v[104:105], v[72:73] op_sel:[1,0,0] op_sel_hi:[1,1,1]
	v_cvt_scalef32_pk_f32_fp4 v[98:99], v119, 1.0
	v_cvt_scalef32_pk_f32_fp4 v[100:101], v119, 1.0 op_sel:[1,0,0]
	v_cvt_scalef32_pk_f32_fp4 v[102:103], v119, 1.0 op_sel:[0,1,0]
	v_cvt_scalef32_pk_f32_fp4 v[104:105], v119, 1.0 op_sel:[1,1,0]
	v_pk_fma_f32 v[74:75], v[28:29], v[98:99], v[74:75] op_sel:[1,0,0] op_sel_hi:[1,1,1]
	v_pk_fma_f32 v[76:77], v[28:29], v[100:101], v[76:77] op_sel:[1,0,0] op_sel_hi:[1,1,1]
	v_pk_fma_f32 v[78:79], v[28:29], v[102:103], v[78:79] op_sel:[1,0,0] op_sel_hi:[1,1,1]
	v_pk_fma_f32 v[80:81], v[28:29], v[104:105], v[80:81] op_sel:[1,0,0] op_sel_hi:[1,1,1]
	v_cvt_scalef32_pk_f32_fp4 v[98:99], v120, 1.0
	v_cvt_scalef32_pk_f32_fp4 v[100:101], v120, 1.0 op_sel:[1,0,0]
	v_cvt_scalef32_pk_f32_fp4 v[102:103], v120, 1.0 op_sel:[0,1,0]
	v_cvt_scalef32_pk_f32_fp4 v[104:105], v120, 1.0 op_sel:[1,1,0]
	v_pk_fma_f32 v[82:83], v[28:29], v[98:99], v[82:83] op_sel:[1,0,0] op_sel_hi:[1,1,1]
	v_pk_fma_f32 v[84:85], v[28:29], v[100:101], v[84:85] op_sel:[1,0,0] op_sel_hi:[1,1,1]
	v_pk_fma_f32 v[86:87], v[28:29], v[102:103], v[86:87] op_sel:[1,0,0] op_sel_hi:[1,1,1]
	v_pk_fma_f32 v[88:89], v[28:29], v[104:105], v[88:89] op_sel:[1,0,0] op_sel_hi:[1,1,1]
	v_cvt_scalef32_pk_f32_fp4 v[98:99], v121, 1.0
	v_cvt_scalef32_pk_f32_fp4 v[100:101], v121, 1.0 op_sel:[1,0,0]
	v_cvt_scalef32_pk_f32_fp4 v[102:103], v121, 1.0 op_sel:[0,1,0]
	v_cvt_scalef32_pk_f32_fp4 v[104:105], v121, 1.0 op_sel:[1,1,0]
	v_pk_fma_f32 v[90:91], v[28:29], v[98:99], v[90:91] op_sel:[1,0,0] op_sel_hi:[1,1,1]
	v_pk_fma_f32 v[92:93], v[28:29], v[100:101], v[92:93] op_sel:[1,0,0] op_sel_hi:[1,1,1]
	v_pk_fma_f32 v[94:95], v[28:29], v[102:103], v[94:95] op_sel:[1,0,0] op_sel_hi:[1,1,1]
	v_pk_fma_f32 v[96:97], v[28:29], v[104:105], v[96:97] op_sel:[1,0,0] op_sel_hi:[1,1,1]
	v_cvt_scalef32_pk_f32_fp4 v[98:99], v122, 1.0
	v_cvt_scalef32_pk_f32_fp4 v[100:101], v122, 1.0 op_sel:[1,0,0]
	v_cvt_scalef32_pk_f32_fp4 v[102:103], v122, 1.0 op_sel:[0,1,0]
	v_cvt_scalef32_pk_f32_fp4 v[104:105], v122, 1.0 op_sel:[1,1,0]
	v_pk_fma_f32 v[66:67], v[30:31], v[98:99], v[66:67] op_sel_hi:[0,1,1]
	v_pk_fma_f32 v[68:69], v[30:31], v[100:101], v[68:69] op_sel_hi:[0,1,1]
	v_pk_fma_f32 v[70:71], v[30:31], v[102:103], v[70:71] op_sel_hi:[0,1,1]
	v_pk_fma_f32 v[72:73], v[30:31], v[104:105], v[72:73] op_sel_hi:[0,1,1]
	v_cvt_scalef32_pk_f32_fp4 v[98:99], v123, 1.0
	v_cvt_scalef32_pk_f32_fp4 v[100:101], v123, 1.0 op_sel:[1,0,0]
	v_cvt_scalef32_pk_f32_fp4 v[102:103], v123, 1.0 op_sel:[0,1,0]
	v_cvt_scalef32_pk_f32_fp4 v[104:105], v123, 1.0 op_sel:[1,1,0]
	v_pk_fma_f32 v[74:75], v[30:31], v[98:99], v[74:75] op_sel_hi:[0,1,1]
	v_pk_fma_f32 v[76:77], v[30:31], v[100:101], v[76:77] op_sel_hi:[0,1,1]
	v_pk_fma_f32 v[78:79], v[30:31], v[102:103], v[78:79] op_sel_hi:[0,1,1]
	v_pk_fma_f32 v[80:81], v[30:31], v[104:105], v[80:81] op_sel_hi:[0,1,1]
	v_cvt_scalef32_pk_f32_fp4 v[98:99], v124, 1.0
	v_cvt_scalef32_pk_f32_fp4 v[100:101], v124, 1.0 op_sel:[1,0,0]
	v_cvt_scalef32_pk_f32_fp4 v[102:103], v124, 1.0 op_sel:[0,1,0]
	v_cvt_scalef32_pk_f32_fp4 v[104:105], v124, 1.0 op_sel:[1,1,0]
	v_pk_fma_f32 v[82:83], v[30:31], v[98:99], v[82:83] op_sel_hi:[0,1,1]
	v_pk_fma_f32 v[84:85], v[30:31], v[100:101], v[84:85] op_sel_hi:[0,1,1]
	v_pk_fma_f32 v[86:87], v[30:31], v[102:103], v[86:87] op_sel_hi:[0,1,1]
	v_pk_fma_f32 v[88:89], v[30:31], v[104:105], v[88:89] op_sel_hi:[0,1,1]
	v_cvt_scalef32_pk_f32_fp4 v[98:99], v125, 1.0
	v_cvt_scalef32_pk_f32_fp4 v[100:101], v125, 1.0 op_sel:[1,0,0]
	v_cvt_scalef32_pk_f32_fp4 v[102:103], v125, 1.0 op_sel:[0,1,0]
	v_cvt_scalef32_pk_f32_fp4 v[104:105], v125, 1.0 op_sel:[1,1,0]
	v_pk_fma_f32 v[90:91], v[30:31], v[98:99], v[90:91] op_sel_hi:[0,1,1]
	v_pk_fma_f32 v[92:93], v[30:31], v[100:101], v[92:93] op_sel_hi:[0,1,1]
	v_pk_fma_f32 v[94:95], v[30:31], v[102:103], v[94:95] op_sel_hi:[0,1,1]
	v_pk_fma_f32 v[96:97], v[30:31], v[104:105], v[96:97] op_sel_hi:[0,1,1]
	v_cvt_scalef32_pk_f32_fp4 v[98:99], v126, 1.0
	v_cvt_scalef32_pk_f32_fp4 v[100:101], v126, 1.0 op_sel:[1,0,0]
	v_cvt_scalef32_pk_f32_fp4 v[102:103], v126, 1.0 op_sel:[0,1,0]
	v_cvt_scalef32_pk_f32_fp4 v[104:105], v126, 1.0 op_sel:[1,1,0]
	v_pk_fma_f32 v[66:67], v[30:31], v[98:99], v[66:67] op_sel:[1,0,0] op_sel_hi:[1,1,1]
; __device__ __forceinline__ void phase_peer_v(const Params& p, int layer, int xs, int wid0, int wstride, bool last, char* smraw) {
;     ...
;   auto half_fma = [&](const u32x4 (&q)[8], const f32x4& c0, const f32x4& c1) {
; #pragma unroll
;     for (int i = 0; i < 8; ++i) {
;       const float ci = i < 4 ? c0[i & 3] : c1[i & 3];
; #pragma unroll
;       for (int m = 0; m < 4; ++m) {
;         unsigned dw = q[i][m];
;         asm volatile("" : "+v"(dw) : "v"(acc[(8 * m + 31) & 31]));
;         const f32x2 e0 = __builtin_amdgcn_cvt_scalef32_pk_f32_fp4(dw, 1.0f, 0), e1 = __builtin_amdgcn_cvt_scalef32_pk_f32_fp4(dw, 1.0f, 1);
;         const f32x2 e2 = __builtin_amdgcn_cvt_scalef32_pk_f32_fp4(dw, 1.0f, 2), e3 = __builtin_amdgcn_cvt_scalef32_pk_f32_fp4(dw, 1.0f, 3);
;         acc[8 * m + 0] += ci * e0[0]; acc[8 * m + 1] += ci * e0[1]; acc[8 * m + 2] += ci * e1[0]; acc[8 * m + 3] += ci * e1[1];
;         acc[8 * m + 4] += ci * e2[0]; acc[8 * m + 5] += ci * e2[1]; acc[8 * m + 6] += ci * e3[0]; acc[8 * m + 7] += ci * e3[1];
;       }
;     }
;   };
	v_pk_fma_f32 v[68:69], v[30:31], v[100:101], v[68:69] op_sel:[1,0,0] op_sel_hi:[1,1,1]
	v_pk_fma_f32 v[70:71], v[30:31], v[102:103], v[70:71] op_sel:[1,0,0] op_sel_hi:[1,1,1]
	v_pk_fma_f32 v[72:73], v[30:31], v[104:105], v[72:73] op_sel:[1,0,0] op_sel_hi:[1,1,1]
	v_cvt_scalef32_pk_f32_fp4 v[98:99], v127, 1.0
	v_cvt_scalef32_pk_f32_fp4 v[100:101], v127, 1.0 op_sel:[1,0,0]
	v_cvt_scalef32_pk_f32_fp4 v[102:103], v127, 1.0 op_sel:[0,1,0]
	v_cvt_scalef32_pk_f32_fp4 v[104:105], v127, 1.0 op_sel:[1,1,0]
	v_pk_fma_f32 v[74:75], v[30:31], v[98:99], v[74:75] op_sel:[1,0,0] op_sel_hi:[1,1,1]
	v_pk_fma_f32 v[76:77], v[30:31], v[100:101], v[76:77] op_sel:[1,0,0] op_sel_hi:[1,1,1]
	v_pk_fma_f32 v[78:79], v[30:31], v[102:103], v[78:79] op_sel:[1,0,0] op_sel_hi:[1,1,1]
	v_pk_fma_f32 v[80:81], v[30:31], v[104:105], v[80:81] op_sel:[1,0,0] op_sel_hi:[1,1,1]
	v_cvt_scalef32_pk_f32_fp4 v[98:99], v128, 1.0
	v_cvt_scalef32_pk_f32_fp4 v[100:101], v128, 1.0 op_sel:[1,0,0]
	v_cvt_scalef32_pk_f32_fp4 v[102:103], v128, 1.0 op_sel:[0,1,0]
	v_cvt_scalef32_pk_f32_fp4 v[104:105], v128, 1.0 op_sel:[1,1,0]
	v_pk_fma_f32 v[82:83], v[30:31], v[98:99], v[82:83] op_sel:[1,0,0] op_sel_hi:[1,1,1]
	v_pk_fma_f32 v[84:85], v[30:31], v[100:101], v[84:85] op_sel:[1,0,0] op_sel_hi:[1,1,1]
	v_pk_fma_f32 v[86:87], v[30:31], v[102:103], v[86:87] op_sel:[1,0,0] op_sel_hi:[1,1,1]
	v_pk_fma_f32 v[88:89], v[30:31], v[104:105], v[88:89] op_sel:[1,0,0] op_sel_hi:[1,1,1]
	v_cvt_scalef32_pk_f32_fp4 v[98:99], v129, 1.0
	v_cvt_scalef32_pk_f32_fp4 v[100:101], v129, 1.0 op_sel:[1,0,0]
	v_cvt_scalef32_pk_f32_fp4 v[102:103], v129, 1.0 op_sel:[0,1,0]
	v_cvt_scalef32_pk_f32_fp4 v[104:105], v129, 1.0 op_sel:[1,1,0]
	v_pk_fma_f32 v[90:91], v[30:31], v[98:99], v[90:91] op_sel:[1,0,0] op_sel_hi:[1,1,1]
	v_pk_fma_f32 v[92:93], v[30:31], v[100:101], v[92:93] op_sel:[1,0,0] op_sel_hi:[1,1,1]
	v_pk_fma_f32 v[94:95], v[30:31], v[102:103], v[94:95] op_sel:[1,0,0] op_sel_hi:[1,1,1]
	v_pk_fma_f32 v[96:97], v[30:31], v[104:105], v[96:97] op_sel:[1,0,0] op_sel_hi:[1,1,1]
	v_cvt_scalef32_pk_f32_fp4 v[98:99], v130, 1.0
	v_cvt_scalef32_pk_f32_fp4 v[100:101], v130, 1.0 op_sel:[1,0,0]
	v_cvt_scalef32_pk_f32_fp4 v[102:103], v130, 1.0 op_sel:[0,1,0]
	v_cvt_scalef32_pk_f32_fp4 v[104:105], v130, 1.0 op_sel:[1,1,0]
	v_pk_fma_f32 v[66:67], v[32:33], v[98:99], v[66:67] op_sel_hi:[0,1,1]
	v_pk_fma_f32 v[68:69], v[32:33], v[100:101], v[68:69] op_sel_hi:[0,1,1]
	v_pk_fma_f32 v[70:71], v[32:33], v[102:103], v[70:71] op_sel_hi:[0,1,1]
	v_pk_fma_f32 v[72:73], v[32:33], v[104:105], v[72:73] op_sel_hi:[0,1,1]
	v_cvt_scalef32_pk_f32_fp4 v[98:99], v131, 1.0
	v_cvt_scalef32_pk_f32_fp4 v[100:101], v131, 1.0 op_sel:[1,0,0]
	v_cvt_scalef32_pk_f32_fp4 v[102:103], v131, 1.0 op_sel:[0,1,0]
	v_cvt_scalef32_pk_f32_fp4 v[104:105], v131, 1.0 op_sel:[1,1,0]
	v_pk_fma_f32 v[74:75], v[32:33], v[98:99], v[74:75] op_sel_hi:[0,1,1]
	v_pk_fma_f32 v[76:77], v[32:33], v[100:101], v[76:77] op_sel_hi:[0,1,1]
	v_pk_fma_f32 v[78:79], v[32:33], v[102:103], v[78:79] op_sel_hi:[0,1,1]
	v_pk_fma_f32 v[80:81], v[32:33], v[104:105], v[80:81] op_sel_hi:[0,1,1]
	v_cvt_scalef32_pk_f32_fp4 v[98:99], v132, 1.0
	v_cvt_scalef32_pk_f32_fp4 v[100:101], v132, 1.0 op_sel:[1,0,0]
	v_cvt_scalef32_pk_f32_fp4 v[102:103], v132, 1.0 op_sel:[0,1,0]
	v_cvt_scalef32_pk_f32_fp4 v[104:105], v132, 1.0 op_sel:[1,1,0]
	v_pk_fma_f32 v[82:83], v[32:33], v[98:99], v[82:83] op_sel_hi:[0,1,1]
	v_pk_fma_f32 v[84:85], v[32:33], v[100:101], v[84:85] op_sel_hi:[0,1,1]
	v_pk_fma_f32 v[86:87], v[32:33], v[102:103], v[86:87] op_sel_hi:[0,1,1]
	v_pk_fma_f32 v[88:89], v[32:33], v[104:105], v[88:89] op_sel_hi:[0,1,1]
	v_cvt_scalef32_pk_f32_fp4 v[98:99], v133, 1.0
	v_cvt_scalef32_pk_f32_fp4 v[100:101], v133, 1.0 op_sel:[1,0,0]
	v_cvt_scalef32_pk_f32_fp4 v[102:103], v133, 1.0 op_sel:[0,1,0]
	v_cvt_scalef32_pk_f32_fp4 v[104:105], v133, 1.0 op_sel:[1,1,0]
	v_pk_fma_f32 v[90:91], v[32:33], v[98:99], v[90:91] op_sel_hi:[0,1,1]
	v_pk_fma_f32 v[92:93], v[32:33], v[100:101], v[92:93] op_sel_hi:[0,1,1]
	v_pk_fma_f32 v[94:95], v[32:33], v[102:103], v[94:95] op_sel_hi:[0,1,1]
	v_pk_fma_f32 v[96:97], v[32:33], v[104:105], v[96:97] op_sel_hi:[0,1,1]
	v_cvt_scalef32_pk_f32_fp4 v[98:99], v134, 1.0
	v_cvt_scalef32_pk_f32_fp4 v[100:101], v134, 1.0 op_sel:[1,0,0]
	v_cvt_scalef32_pk_f32_fp4 v[102:103], v134, 1.0 op_sel:[0,1,0]
	v_cvt_scalef32_pk_f32_fp4 v[104:105], v134, 1.0 op_sel:[1,1,0]
	v_pk_fma_f32 v[66:67], v[32:33], v[98:99], v[66:67] op_sel:[1,0,0] op_sel_hi:[1,1,1]
	v_pk_fma_f32 v[68:69], v[32:33], v[100:101], v[68:69] op_sel:[1,0,0] op_sel_hi:[1,1,1]
	v_pk_fma_f32 v[70:71], v[32:33], v[102:103], v[70:71] op_sel:[1,0,0] op_sel_hi:[1,1,1]
	v_pk_fma_f32 v[72:73], v[32:33], v[104:105], v[72:73] op_sel:[1,0,0] op_sel_hi:[1,1,1]
	v_cvt_scalef32_pk_f32_fp4 v[98:99], v135, 1.0
	v_cvt_scalef32_pk_f32_fp4 v[100:101], v135, 1.0 op_sel:[1,0,0]
	v_cvt_scalef32_pk_f32_fp4 v[102:103], v135, 1.0 op_sel:[0,1,0]
	v_cvt_scalef32_pk_f32_fp4 v[104:105], v135, 1.0 op_sel:[1,1,0]
	v_pk_fma_f32 v[74:75], v[32:33], v[98:99], v[74:75] op_sel:[1,0,0] op_sel_hi:[1,1,1]
	v_pk_fma_f32 v[76:77], v[32:33], v[100:101], v[76:77] op_sel:[1,0,0] op_sel_hi:[1,1,1]
	v_pk_fma_f32 v[78:79], v[32:33], v[102:103], v[78:79] op_sel:[1,0,0] op_sel_hi:[1,1,1]
	v_pk_fma_f32 v[80:81], v[32:33], v[104:105], v[80:81] op_sel:[1,0,0] op_sel_hi:[1,1,1]
	v_cvt_scalef32_pk_f32_fp4 v[98:99], v136, 1.0
	v_cvt_scalef32_pk_f32_fp4 v[100:101], v136, 1.0 op_sel:[1,0,0]
	v_cvt_scalef32_pk_f32_fp4 v[102:103], v136, 1.0 op_sel:[0,1,0]
	v_cvt_scalef32_pk_f32_fp4 v[104:105], v136, 1.0 op_sel:[1,1,0]
	v_pk_fma_f32 v[82:83], v[32:33], v[98:99], v[82:83] op_sel:[1,0,0] op_sel_hi:[1,1,1]
; __device__ __forceinline__ void phase_peer_v(const Params& p, int layer, int xs, int wid0, int wstride, bool last, char* smraw) {
;     ...
;   auto half_fma = [&](const u32x4 (&q)[8], const f32x4& c0, const f32x4& c1) {
; #pragma unroll
;     for (int i = 0; i < 8; ++i) {
;       const float ci = i < 4 ? c0[i & 3] : c1[i & 3];
; #pragma unroll
;       for (int m = 0; m < 4; ++m) {
;         unsigned dw = q[i][m];
;         asm volatile("" : "+v"(dw) : "v"(acc[(8 * m + 31) & 31]));
;         const f32x2 e0 = __builtin_amdgcn_cvt_scalef32_pk_f32_fp4(dw, 1.0f, 0), e1 = __builtin_amdgcn_cvt_scalef32_pk_f32_fp4(dw, 1.0f, 1);
;         const f32x2 e2 = __builtin_amdgcn_cvt_scalef32_pk_f32_fp4(dw, 1.0f, 2), e3 = __builtin_amdgcn_cvt_scalef32_pk_f32_fp4(dw, 1.0f, 3);
;         acc[8 * m + 0] += ci * e0[0]; acc[8 * m + 1] += ci * e0[1]; acc[8 * m + 2] += ci * e1[0]; acc[8 * m + 3] += ci * e1[1];
;         acc[8 * m + 4] += ci * e2[0]; acc[8 * m + 5] += ci * e2[1]; acc[8 * m + 6] += ci * e3[0]; acc[8 * m + 7] += ci * e3[1];
;       }
;     }
;   };
	v_pk_fma_f32 v[84:85], v[32:33], v[100:101], v[84:85] op_sel:[1,0,0] op_sel_hi:[1,1,1]
	v_pk_fma_f32 v[86:87], v[32:33], v[102:103], v[86:87] op_sel:[1,0,0] op_sel_hi:[1,1,1]
	v_pk_fma_f32 v[88:89], v[32:33], v[104:105], v[88:89] op_sel:[1,0,0] op_sel_hi:[1,1,1]
	v_cvt_scalef32_pk_f32_fp4 v[98:99], v137, 1.0
	v_cvt_scalef32_pk_f32_fp4 v[100:101], v137, 1.0 op_sel:[1,0,0]
	v_cvt_scalef32_pk_f32_fp4 v[102:103], v137, 1.0 op_sel:[0,1,0]
	v_cvt_scalef32_pk_f32_fp4 v[104:105], v137, 1.0 op_sel:[1,1,0]
	v_pk_fma_f32 v[90:91], v[32:33], v[98:99], v[90:91] op_sel:[1,0,0] op_sel_hi:[1,1,1]
	v_pk_fma_f32 v[92:93], v[32:33], v[100:101], v[92:93] op_sel:[1,0,0] op_sel_hi:[1,1,1]
	v_pk_fma_f32 v[94:95], v[32:33], v[102:103], v[94:95] op_sel:[1,0,0] op_sel_hi:[1,1,1]
	v_pk_fma_f32 v[96:97], v[32:33], v[104:105], v[96:97] op_sel:[1,0,0] op_sel_hi:[1,1,1]
	v_cvt_scalef32_pk_f32_fp4 v[98:99], v138, 1.0
	v_cvt_scalef32_pk_f32_fp4 v[100:101], v138, 1.0 op_sel:[1,0,0]
	v_cvt_scalef32_pk_f32_fp4 v[102:103], v138, 1.0 op_sel:[0,1,0]
	v_cvt_scalef32_pk_f32_fp4 v[104:105], v138, 1.0 op_sel:[1,1,0]
	v_pk_fma_f32 v[66:67], v[34:35], v[98:99], v[66:67] op_sel_hi:[0,1,1]
	v_pk_fma_f32 v[68:69], v[34:35], v[100:101], v[68:69] op_sel_hi:[0,1,1]
	v_pk_fma_f32 v[70:71], v[34:35], v[102:103], v[70:71] op_sel_hi:[0,1,1]
	v_pk_fma_f32 v[72:73], v[34:35], v[104:105], v[72:73] op_sel_hi:[0,1,1]
	v_cvt_scalef32_pk_f32_fp4 v[98:99], v139, 1.0
	v_cvt_scalef32_pk_f32_fp4 v[100:101], v139, 1.0 op_sel:[1,0,0]
	v_cvt_scalef32_pk_f32_fp4 v[102:103], v139, 1.0 op_sel:[0,1,0]
	v_cvt_scalef32_pk_f32_fp4 v[104:105], v139, 1.0 op_sel:[1,1,0]
	v_pk_fma_f32 v[74:75], v[34:35], v[98:99], v[74:75] op_sel_hi:[0,1,1]
	v_pk_fma_f32 v[76:77], v[34:35], v[100:101], v[76:77] op_sel_hi:[0,1,1]
	v_pk_fma_f32 v[78:79], v[34:35], v[102:103], v[78:79] op_sel_hi:[0,1,1]
	v_pk_fma_f32 v[80:81], v[34:35], v[104:105], v[80:81] op_sel_hi:[0,1,1]
	v_cvt_scalef32_pk_f32_fp4 v[98:99], v140, 1.0
	v_cvt_scalef32_pk_f32_fp4 v[100:101], v140, 1.0 op_sel:[1,0,0]
	v_cvt_scalef32_pk_f32_fp4 v[102:103], v140, 1.0 op_sel:[0,1,0]
	v_cvt_scalef32_pk_f32_fp4 v[104:105], v140, 1.0 op_sel:[1,1,0]
	v_pk_fma_f32 v[82:83], v[34:35], v[98:99], v[82:83] op_sel_hi:[0,1,1]
	v_pk_fma_f32 v[84:85], v[34:35], v[100:101], v[84:85] op_sel_hi:[0,1,1]
	v_pk_fma_f32 v[86:87], v[34:35], v[102:103], v[86:87] op_sel_hi:[0,1,1]
	v_pk_fma_f32 v[88:89], v[34:35], v[104:105], v[88:89] op_sel_hi:[0,1,1]
	v_cvt_scalef32_pk_f32_fp4 v[98:99], v141, 1.0
	v_cvt_scalef32_pk_f32_fp4 v[100:101], v141, 1.0 op_sel:[1,0,0]
	v_cvt_scalef32_pk_f32_fp4 v[102:103], v141, 1.0 op_sel:[0,1,0]
	v_cvt_scalef32_pk_f32_fp4 v[104:105], v141, 1.0 op_sel:[1,1,0]
	v_pk_fma_f32 v[90:91], v[34:35], v[98:99], v[90:91] op_sel_hi:[0,1,1]
	v_pk_fma_f32 v[92:93], v[34:35], v[100:101], v[92:93] op_sel_hi:[0,1,1]
	v_pk_fma_f32 v[94:95], v[34:35], v[102:103], v[94:95] op_sel_hi:[0,1,1]
	v_pk_fma_f32 v[96:97], v[34:35], v[104:105], v[96:97] op_sel_hi:[0,1,1]
	v_cvt_scalef32_pk_f32_fp4 v[98:99], v142, 1.0
	v_cvt_scalef32_pk_f32_fp4 v[100:101], v142, 1.0 op_sel:[1,0,0]
	v_cvt_scalef32_pk_f32_fp4 v[102:103], v142, 1.0 op_sel:[0,1,0]
	v_cvt_scalef32_pk_f32_fp4 v[104:105], v142, 1.0 op_sel:[1,1,0]
	v_pk_fma_f32 v[66:67], v[34:35], v[98:99], v[66:67] op_sel:[1,0,0] op_sel_hi:[1,1,1]
	v_pk_fma_f32 v[68:69], v[34:35], v[100:101], v[68:69] op_sel:[1,0,0] op_sel_hi:[1,1,1]
	v_pk_fma_f32 v[70:71], v[34:35], v[102:103], v[70:71] op_sel:[1,0,0] op_sel_hi:[1,1,1]
	v_pk_fma_f32 v[72:73], v[34:35], v[104:105], v[72:73] op_sel:[1,0,0] op_sel_hi:[1,1,1]
	v_cvt_scalef32_pk_f32_fp4 v[98:99], v143, 1.0
	v_cvt_scalef32_pk_f32_fp4 v[100:101], v143, 1.0 op_sel:[1,0,0]
	v_cvt_scalef32_pk_f32_fp4 v[102:103], v143, 1.0 op_sel:[0,1,0]
	v_cvt_scalef32_pk_f32_fp4 v[104:105], v143, 1.0 op_sel:[1,1,0]
	v_pk_fma_f32 v[74:75], v[34:35], v[98:99], v[74:75] op_sel:[1,0,0] op_sel_hi:[1,1,1]
	v_pk_fma_f32 v[76:77], v[34:35], v[100:101], v[76:77] op_sel:[1,0,0] op_sel_hi:[1,1,1]
	v_pk_fma_f32 v[78:79], v[34:35], v[102:103], v[78:79] op_sel:[1,0,0] op_sel_hi:[1,1,1]
	v_pk_fma_f32 v[80:81], v[34:35], v[104:105], v[80:81] op_sel:[1,0,0] op_sel_hi:[1,1,1]
	v_cvt_scalef32_pk_f32_fp4 v[98:99], v144, 1.0
	v_cvt_scalef32_pk_f32_fp4 v[100:101], v144, 1.0 op_sel:[1,0,0]
	v_cvt_scalef32_pk_f32_fp4 v[102:103], v144, 1.0 op_sel:[0,1,0]
	v_cvt_scalef32_pk_f32_fp4 v[104:105], v144, 1.0 op_sel:[1,1,0]
	v_pk_fma_f32 v[82:83], v[34:35], v[98:99], v[82:83] op_sel:[1,0,0] op_sel_hi:[1,1,1]
	v_pk_fma_f32 v[84:85], v[34:35], v[100:101], v[84:85] op_sel:[1,0,0] op_sel_hi:[1,1,1]
	v_pk_fma_f32 v[86:87], v[34:35], v[102:103], v[86:87] op_sel:[1,0,0] op_sel_hi:[1,1,1]
	v_pk_fma_f32 v[88:89], v[34:35], v[104:105], v[88:89] op_sel:[1,0,0] op_sel_hi:[1,1,1]
	v_cvt_scalef32_pk_f32_fp4 v[98:99], v145, 1.0
	v_cvt_scalef32_pk_f32_fp4 v[100:101], v145, 1.0 op_sel:[1,0,0]
	v_cvt_scalef32_pk_f32_fp4 v[102:103], v145, 1.0 op_sel:[0,1,0]
	v_cvt_scalef32_pk_f32_fp4 v[104:105], v145, 1.0 op_sel:[1,1,0]
	v_pk_fma_f32 v[90:91], v[34:35], v[98:99], v[90:91] op_sel:[1,0,0] op_sel_hi:[1,1,1]
	v_pk_fma_f32 v[92:93], v[34:35], v[100:101], v[92:93] op_sel:[1,0,0] op_sel_hi:[1,1,1]
	v_pk_fma_f32 v[94:95], v[34:35], v[102:103], v[94:95] op_sel:[1,0,0] op_sel_hi:[1,1,1]
	v_pk_fma_f32 v[96:97], v[34:35], v[104:105], v[96:97] op_sel:[1,0,0] op_sel_hi:[1,1,1]
	v_cvt_scalef32_pk_f32_fp4 v[98:99], v146, 1.0
	v_cvt_scalef32_pk_f32_fp4 v[100:101], v146, 1.0 op_sel:[1,0,0]
	v_cvt_scalef32_pk_f32_fp4 v[102:103], v146, 1.0 op_sel:[0,1,0]
	v_cvt_scalef32_pk_f32_fp4 v[104:105], v146, 1.0 op_sel:[1,1,0]
	v_pk_fma_f32 v[66:67], v[36:37], v[98:99], v[66:67] op_sel_hi:[0,1,1]
; __device__ __forceinline__ void phase_peer_v(const Params& p, int layer, int xs, int wid0, int wstride, bool last, char* smraw) {
;     ...
;   auto half_fma = [&](const u32x4 (&q)[8], const f32x4& c0, const f32x4& c1) {
; #pragma unroll
;     for (int i = 0; i < 8; ++i) {
;       const float ci = i < 4 ? c0[i & 3] : c1[i & 3];
; #pragma unroll
;       for (int m = 0; m < 4; ++m) {
;         unsigned dw = q[i][m];
;         asm volatile("" : "+v"(dw) : "v"(acc[(8 * m + 31) & 31]));
;         const f32x2 e0 = __builtin_amdgcn_cvt_scalef32_pk_f32_fp4(dw, 1.0f, 0), e1 = __builtin_amdgcn_cvt_scalef32_pk_f32_fp4(dw, 1.0f, 1);
;         const f32x2 e2 = __builtin_amdgcn_cvt_scalef32_pk_f32_fp4(dw, 1.0f, 2), e3 = __builtin_amdgcn_cvt_scalef32_pk_f32_fp4(dw, 1.0f, 3);
;         acc[8 * m + 0] += ci * e0[0]; acc[8 * m + 1] += ci * e0[1]; acc[8 * m + 2] += ci * e1[0]; acc[8 * m + 3] += ci * e1[1];
;         acc[8 * m + 4] += ci * e2[0]; acc[8 * m + 5] += ci * e2[1]; acc[8 * m + 6] += ci * e3[0]; acc[8 * m + 7] += ci * e3[1];
;       }
;     }
;   };
;     ...
;     for (int i = 0; i < 8; ++i) qA[i] = *(const u32x4*)(Vq + (ni[2 + (i >> 2)][i & 3] * 128u + joff));
;     if (tn < TH) load_idx(tn);
;     half_fma(qA, c2, c3);
	v_pk_fma_f32 v[68:69], v[36:37], v[100:101], v[68:69] op_sel_hi:[0,1,1]
	v_pk_fma_f32 v[70:71], v[36:37], v[102:103], v[70:71] op_sel_hi:[0,1,1]
	v_pk_fma_f32 v[72:73], v[36:37], v[104:105], v[72:73] op_sel_hi:[0,1,1]
	v_cvt_scalef32_pk_f32_fp4 v[98:99], v147, 1.0
	v_cvt_scalef32_pk_f32_fp4 v[100:101], v147, 1.0 op_sel:[1,0,0]
	v_cvt_scalef32_pk_f32_fp4 v[102:103], v147, 1.0 op_sel:[0,1,0]
	v_cvt_scalef32_pk_f32_fp4 v[104:105], v147, 1.0 op_sel:[1,1,0]
	v_pk_fma_f32 v[74:75], v[36:37], v[98:99], v[74:75] op_sel_hi:[0,1,1]
	v_pk_fma_f32 v[76:77], v[36:37], v[100:101], v[76:77] op_sel_hi:[0,1,1]
	v_pk_fma_f32 v[78:79], v[36:37], v[102:103], v[78:79] op_sel_hi:[0,1,1]
	v_pk_fma_f32 v[80:81], v[36:37], v[104:105], v[80:81] op_sel_hi:[0,1,1]
	v_cvt_scalef32_pk_f32_fp4 v[98:99], v148, 1.0
	v_cvt_scalef32_pk_f32_fp4 v[100:101], v148, 1.0 op_sel:[1,0,0]
	v_cvt_scalef32_pk_f32_fp4 v[102:103], v148, 1.0 op_sel:[0,1,0]
	v_cvt_scalef32_pk_f32_fp4 v[104:105], v148, 1.0 op_sel:[1,1,0]
	v_pk_fma_f32 v[82:83], v[36:37], v[98:99], v[82:83] op_sel_hi:[0,1,1]
	v_pk_fma_f32 v[84:85], v[36:37], v[100:101], v[84:85] op_sel_hi:[0,1,1]
	v_pk_fma_f32 v[86:87], v[36:37], v[102:103], v[86:87] op_sel_hi:[0,1,1]
	v_pk_fma_f32 v[88:89], v[36:37], v[104:105], v[88:89] op_sel_hi:[0,1,1]
	v_cvt_scalef32_pk_f32_fp4 v[98:99], v149, 1.0
	v_cvt_scalef32_pk_f32_fp4 v[100:101], v149, 1.0 op_sel:[1,0,0]
	v_cvt_scalef32_pk_f32_fp4 v[102:103], v149, 1.0 op_sel:[0,1,0]
	v_cvt_scalef32_pk_f32_fp4 v[104:105], v149, 1.0 op_sel:[1,1,0]
	v_pk_fma_f32 v[90:91], v[36:37], v[98:99], v[90:91] op_sel_hi:[0,1,1]
	v_pk_fma_f32 v[92:93], v[36:37], v[100:101], v[92:93] op_sel_hi:[0,1,1]
	v_pk_fma_f32 v[94:95], v[36:37], v[102:103], v[94:95] op_sel_hi:[0,1,1]
	v_pk_fma_f32 v[96:97], v[36:37], v[104:105], v[96:97] op_sel_hi:[0,1,1]
	v_cvt_scalef32_pk_f32_fp4 v[98:99], v150, 1.0
	v_cvt_scalef32_pk_f32_fp4 v[100:101], v150, 1.0 op_sel:[1,0,0]
	v_cvt_scalef32_pk_f32_fp4 v[102:103], v150, 1.0 op_sel:[0,1,0]
	v_cvt_scalef32_pk_f32_fp4 v[104:105], v150, 1.0 op_sel:[1,1,0]
	v_pk_fma_f32 v[66:67], v[36:37], v[98:99], v[66:67] op_sel:[1,0,0] op_sel_hi:[1,1,1]
	v_pk_fma_f32 v[68:69], v[36:37], v[100:101], v[68:69] op_sel:[1,0,0] op_sel_hi:[1,1,1]
	v_pk_fma_f32 v[70:71], v[36:37], v[102:103], v[70:71] op_sel:[1,0,0] op_sel_hi:[1,1,1]
	v_pk_fma_f32 v[72:73], v[36:37], v[104:105], v[72:73] op_sel:[1,0,0] op_sel_hi:[1,1,1]
	v_cvt_scalef32_pk_f32_fp4 v[98:99], v151, 1.0
	v_cvt_scalef32_pk_f32_fp4 v[100:101], v151, 1.0 op_sel:[1,0,0]
	v_cvt_scalef32_pk_f32_fp4 v[102:103], v151, 1.0 op_sel:[0,1,0]
	v_cvt_scalef32_pk_f32_fp4 v[104:105], v151, 1.0 op_sel:[1,1,0]
	v_pk_fma_f32 v[74:75], v[36:37], v[98:99], v[74:75] op_sel:[1,0,0] op_sel_hi:[1,1,1]
	v_pk_fma_f32 v[76:77], v[36:37], v[100:101], v[76:77] op_sel:[1,0,0] op_sel_hi:[1,1,1]
	v_pk_fma_f32 v[78:79], v[36:37], v[102:103], v[78:79] op_sel:[1,0,0] op_sel_hi:[1,1,1]
	v_pk_fma_f32 v[80:81], v[36:37], v[104:105], v[80:81] op_sel:[1,0,0] op_sel_hi:[1,1,1]
	v_cvt_scalef32_pk_f32_fp4 v[98:99], v152, 1.0
	v_cvt_scalef32_pk_f32_fp4 v[100:101], v152, 1.0 op_sel:[1,0,0]
	v_cvt_scalef32_pk_f32_fp4 v[102:103], v152, 1.0 op_sel:[0,1,0]
	v_cvt_scalef32_pk_f32_fp4 v[104:105], v152, 1.0 op_sel:[1,1,0]
	v_pk_fma_f32 v[82:83], v[36:37], v[98:99], v[82:83] op_sel:[1,0,0] op_sel_hi:[1,1,1]
	v_pk_fma_f32 v[84:85], v[36:37], v[100:101], v[84:85] op_sel:[1,0,0] op_sel_hi:[1,1,1]
	v_pk_fma_f32 v[86:87], v[36:37], v[102:103], v[86:87] op_sel:[1,0,0] op_sel_hi:[1,1,1]
	v_pk_fma_f32 v[88:89], v[36:37], v[104:105], v[88:89] op_sel:[1,0,0] op_sel_hi:[1,1,1]
	v_cvt_scalef32_pk_f32_fp4 v[98:99], v153, 1.0
	v_cvt_scalef32_pk_f32_fp4 v[100:101], v153, 1.0 op_sel:[1,0,0]
	v_cvt_scalef32_pk_f32_fp4 v[102:103], v153, 1.0 op_sel:[0,1,0]
	v_cvt_scalef32_pk_f32_fp4 v[104:105], v153, 1.0 op_sel:[1,1,0]
	v_pk_fma_f32 v[90:91], v[36:37], v[98:99], v[90:91] op_sel:[1,0,0] op_sel_hi:[1,1,1]
	v_pk_fma_f32 v[92:93], v[36:37], v[100:101], v[92:93] op_sel:[1,0,0] op_sel_hi:[1,1,1]
	v_pk_fma_f32 v[94:95], v[36:37], v[102:103], v[94:95] op_sel:[1,0,0] op_sel_hi:[1,1,1]
	v_pk_fma_f32 v[96:97], v[36:37], v[104:105], v[96:97] op_sel:[1,0,0] op_sel_hi:[1,1,1]
	v_cvt_scalef32_pk_f32_fp4 v[98:99], v154, 1.0
	v_cvt_scalef32_pk_f32_fp4 v[100:101], v154, 1.0 op_sel:[1,0,0]
	v_cvt_scalef32_pk_f32_fp4 v[102:103], v154, 1.0 op_sel:[0,1,0]
	v_cvt_scalef32_pk_f32_fp4 v[104:105], v154, 1.0 op_sel:[1,1,0]
	v_pk_fma_f32 v[66:67], v[38:39], v[98:99], v[66:67] op_sel_hi:[0,1,1]
	v_pk_fma_f32 v[68:69], v[38:39], v[100:101], v[68:69] op_sel_hi:[0,1,1]
	v_pk_fma_f32 v[70:71], v[38:39], v[102:103], v[70:71] op_sel_hi:[0,1,1]
	v_pk_fma_f32 v[72:73], v[38:39], v[104:105], v[72:73] op_sel_hi:[0,1,1]
	v_cvt_scalef32_pk_f32_fp4 v[98:99], v155, 1.0
	v_cvt_scalef32_pk_f32_fp4 v[100:101], v155, 1.0 op_sel:[1,0,0]
	v_cvt_scalef32_pk_f32_fp4 v[102:103], v155, 1.0 op_sel:[0,1,0]
	v_cvt_scalef32_pk_f32_fp4 v[104:105], v155, 1.0 op_sel:[1,1,0]
	v_pk_fma_f32 v[74:75], v[38:39], v[98:99], v[74:75] op_sel_hi:[0,1,1]
	v_pk_fma_f32 v[76:77], v[38:39], v[100:101], v[76:77] op_sel_hi:[0,1,1]
	v_pk_fma_f32 v[78:79], v[38:39], v[102:103], v[78:79] op_sel_hi:[0,1,1]
	v_pk_fma_f32 v[80:81], v[38:39], v[104:105], v[80:81] op_sel_hi:[0,1,1]
	v_cvt_scalef32_pk_f32_fp4 v[98:99], v156, 1.0
	v_cvt_scalef32_pk_f32_fp4 v[100:101], v156, 1.0 op_sel:[1,0,0]
	v_cvt_scalef32_pk_f32_fp4 v[102:103], v156, 1.0 op_sel:[0,1,0]
	v_cvt_scalef32_pk_f32_fp4 v[104:105], v156, 1.0 op_sel:[1,1,0]
	v_pk_fma_f32 v[82:83], v[38:39], v[98:99], v[82:83] op_sel_hi:[0,1,1]
	v_pk_fma_f32 v[84:85], v[38:39], v[100:101], v[84:85] op_sel_hi:[0,1,1]
	v_pk_fma_f32 v[86:87], v[38:39], v[102:103], v[86:87] op_sel_hi:[0,1,1]
; __device__ __forceinline__ void phase_peer_v(const Params& p, int layer, int xs, int wid0, int wstride, bool last, char* smraw) {
;     ...
;   auto half_fma = [&](const u32x4 (&q)[8], const f32x4& c0, const f32x4& c1) {
; #pragma unroll
;     for (int i = 0; i < 8; ++i) {
;       const float ci = i < 4 ? c0[i & 3] : c1[i & 3];
; #pragma unroll
;       for (int m = 0; m < 4; ++m) {
;         unsigned dw = q[i][m];
;         asm volatile("" : "+v"(dw) : "v"(acc[(8 * m + 31) & 31]));
;         const f32x2 e0 = __builtin_amdgcn_cvt_scalef32_pk_f32_fp4(dw, 1.0f, 0), e1 = __builtin_amdgcn_cvt_scalef32_pk_f32_fp4(dw, 1.0f, 1);
;         const f32x2 e2 = __builtin_amdgcn_cvt_scalef32_pk_f32_fp4(dw, 1.0f, 2), e3 = __builtin_amdgcn_cvt_scalef32_pk_f32_fp4(dw, 1.0f, 3);
;         acc[8 * m + 0] += ci * e0[0]; acc[8 * m + 1] += ci * e0[1]; acc[8 * m + 2] += ci * e1[0]; acc[8 * m + 3] += ci * e1[1];
;         acc[8 * m + 4] += ci * e2[0]; acc[8 * m + 5] += ci * e2[1]; acc[8 * m + 6] += ci * e3[0]; acc[8 * m + 7] += ci * e3[1];
;       }
;     }
;   };
	v_pk_fma_f32 v[88:89], v[38:39], v[104:105], v[88:89] op_sel_hi:[0,1,1]
	v_cvt_scalef32_pk_f32_fp4 v[98:99], v157, 1.0
	v_cvt_scalef32_pk_f32_fp4 v[100:101], v157, 1.0 op_sel:[1,0,0]
	v_cvt_scalef32_pk_f32_fp4 v[102:103], v157, 1.0 op_sel:[0,1,0]
	v_cvt_scalef32_pk_f32_fp4 v[104:105], v157, 1.0 op_sel:[1,1,0]
	v_pk_fma_f32 v[90:91], v[38:39], v[98:99], v[90:91] op_sel_hi:[0,1,1]
	v_pk_fma_f32 v[92:93], v[38:39], v[100:101], v[92:93] op_sel_hi:[0,1,1]
	v_pk_fma_f32 v[94:95], v[38:39], v[102:103], v[94:95] op_sel_hi:[0,1,1]
	v_pk_fma_f32 v[96:97], v[38:39], v[104:105], v[96:97] op_sel_hi:[0,1,1]
	v_cvt_scalef32_pk_f32_fp4 v[98:99], v158, 1.0
	v_cvt_scalef32_pk_f32_fp4 v[100:101], v158, 1.0 op_sel:[1,0,0]
	v_cvt_scalef32_pk_f32_fp4 v[102:103], v158, 1.0 op_sel:[0,1,0]
	v_cvt_scalef32_pk_f32_fp4 v[104:105], v158, 1.0 op_sel:[1,1,0]
	v_pk_fma_f32 v[66:67], v[38:39], v[98:99], v[66:67] op_sel:[1,0,0] op_sel_hi:[1,1,1]
	v_pk_fma_f32 v[68:69], v[38:39], v[100:101], v[68:69] op_sel:[1,0,0] op_sel_hi:[1,1,1]
	v_pk_fma_f32 v[70:71], v[38:39], v[102:103], v[70:71] op_sel:[1,0,0] op_sel_hi:[1,1,1]
	v_pk_fma_f32 v[72:73], v[38:39], v[104:105], v[72:73] op_sel:[1,0,0] op_sel_hi:[1,1,1]
	v_cvt_scalef32_pk_f32_fp4 v[98:99], v159, 1.0
	v_cvt_scalef32_pk_f32_fp4 v[100:101], v159, 1.0 op_sel:[1,0,0]
	v_cvt_scalef32_pk_f32_fp4 v[102:103], v159, 1.0 op_sel:[0,1,0]
	v_cvt_scalef32_pk_f32_fp4 v[104:105], v159, 1.0 op_sel:[1,1,0]
	v_pk_fma_f32 v[74:75], v[38:39], v[98:99], v[74:75] op_sel:[1,0,0] op_sel_hi:[1,1,1]
	v_pk_fma_f32 v[76:77], v[38:39], v[100:101], v[76:77] op_sel:[1,0,0] op_sel_hi:[1,1,1]
	v_pk_fma_f32 v[78:79], v[38:39], v[102:103], v[78:79] op_sel:[1,0,0] op_sel_hi:[1,1,1]
	v_pk_fma_f32 v[80:81], v[38:39], v[104:105], v[80:81] op_sel:[1,0,0] op_sel_hi:[1,1,1]
	v_cvt_scalef32_pk_f32_fp4 v[98:99], v160, 1.0
	v_cvt_scalef32_pk_f32_fp4 v[100:101], v160, 1.0 op_sel:[1,0,0]
	v_cvt_scalef32_pk_f32_fp4 v[102:103], v160, 1.0 op_sel:[0,1,0]
	v_cvt_scalef32_pk_f32_fp4 v[104:105], v160, 1.0 op_sel:[1,1,0]
	v_pk_fma_f32 v[82:83], v[38:39], v[98:99], v[82:83] op_sel:[1,0,0] op_sel_hi:[1,1,1]
	v_pk_fma_f32 v[84:85], v[38:39], v[100:101], v[84:85] op_sel:[1,0,0] op_sel_hi:[1,1,1]
	v_pk_fma_f32 v[86:87], v[38:39], v[102:103], v[86:87] op_sel:[1,0,0] op_sel_hi:[1,1,1]
	v_pk_fma_f32 v[88:89], v[38:39], v[104:105], v[88:89] op_sel:[1,0,0] op_sel_hi:[1,1,1]
	v_cvt_scalef32_pk_f32_fp4 v[98:99], v161, 1.0
	v_cvt_scalef32_pk_f32_fp4 v[100:101], v161, 1.0 op_sel:[1,0,0]
	v_cvt_scalef32_pk_f32_fp4 v[102:103], v161, 1.0 op_sel:[0,1,0]
	v_cvt_scalef32_pk_f32_fp4 v[104:105], v161, 1.0 op_sel:[1,1,0]
	v_pk_fma_f32 v[90:91], v[38:39], v[98:99], v[90:91] op_sel:[1,0,0] op_sel_hi:[1,1,1]
	v_pk_fma_f32 v[92:93], v[38:39], v[100:101], v[92:93] op_sel:[1,0,0] op_sel_hi:[1,1,1]
	v_pk_fma_f32 v[94:95], v[38:39], v[102:103], v[94:95] op_sel:[1,0,0] op_sel_hi:[1,1,1]
	v_pk_fma_f32 v[96:97], v[38:39], v[104:105], v[96:97] op_sel:[1,0,0] op_sel_hi:[1,1,1]
	v_cvt_scalef32_pk_f32_fp4 v[98:99], v162, 1.0
	v_cvt_scalef32_pk_f32_fp4 v[100:101], v162, 1.0 op_sel:[1,0,0]
	v_cvt_scalef32_pk_f32_fp4 v[102:103], v162, 1.0 op_sel:[0,1,0]
	v_cvt_scalef32_pk_f32_fp4 v[104:105], v162, 1.0 op_sel:[1,1,0]
	v_pk_fma_f32 v[66:67], v[40:41], v[98:99], v[66:67] op_sel_hi:[0,1,1]
	v_pk_fma_f32 v[68:69], v[40:41], v[100:101], v[68:69] op_sel_hi:[0,1,1]
	v_pk_fma_f32 v[70:71], v[40:41], v[102:103], v[70:71] op_sel_hi:[0,1,1]
	v_pk_fma_f32 v[72:73], v[40:41], v[104:105], v[72:73] op_sel_hi:[0,1,1]
	v_cvt_scalef32_pk_f32_fp4 v[98:99], v163, 1.0
	v_cvt_scalef32_pk_f32_fp4 v[100:101], v163, 1.0 op_sel:[1,0,0]
	v_cvt_scalef32_pk_f32_fp4 v[102:103], v163, 1.0 op_sel:[0,1,0]
	v_cvt_scalef32_pk_f32_fp4 v[104:105], v163, 1.0 op_sel:[1,1,0]
	v_pk_fma_f32 v[74:75], v[40:41], v[98:99], v[74:75] op_sel_hi:[0,1,1]
	v_pk_fma_f32 v[76:77], v[40:41], v[100:101], v[76:77] op_sel_hi:[0,1,1]
	v_pk_fma_f32 v[78:79], v[40:41], v[102:103], v[78:79] op_sel_hi:[0,1,1]
	v_pk_fma_f32 v[80:81], v[40:41], v[104:105], v[80:81] op_sel_hi:[0,1,1]
	v_cvt_scalef32_pk_f32_fp4 v[98:99], v164, 1.0
	v_cvt_scalef32_pk_f32_fp4 v[100:101], v164, 1.0 op_sel:[1,0,0]
	v_cvt_scalef32_pk_f32_fp4 v[102:103], v164, 1.0 op_sel:[0,1,0]
	v_cvt_scalef32_pk_f32_fp4 v[104:105], v164, 1.0 op_sel:[1,1,0]
	v_pk_fma_f32 v[82:83], v[40:41], v[98:99], v[82:83] op_sel_hi:[0,1,1]
	v_pk_fma_f32 v[84:85], v[40:41], v[100:101], v[84:85] op_sel_hi:[0,1,1]
	v_pk_fma_f32 v[86:87], v[40:41], v[102:103], v[86:87] op_sel_hi:[0,1,1]
	v_pk_fma_f32 v[88:89], v[40:41], v[104:105], v[88:89] op_sel_hi:[0,1,1]
	v_cvt_scalef32_pk_f32_fp4 v[98:99], v165, 1.0
; __device__ __forceinline__ void phase_peer_v(const Params& p, int layer, int xs, int wid0, int wstride, bool last, char* smraw) {
;     ...
;     half_fma(qA, c2, c3);
; #pragma unroll
;     for (int q4 = 0; q4 < 8; ++q4) *(f32x4*)(red + g * 256 + j * 32 + q4 * 4) = f32x4{acc[q4 * 4], acc[q4 * 4 + 1], acc[q4 * 4 + 2], acc[q4 * 4 + 3]};
;     __builtin_amdgcn_fence(__ATOMIC_RELEASE, "wavefront");
;     __builtin_amdgcn_wave_barrier();
;     __builtin_amdgcn_fence(__ATOMIC_ACQUIRE, "wavefront");
;     f32x4 r = {0.f, 0.f, 0.f, 0.f};
; #pragma unroll
;     for (int gg = 0; gg < 8; ++gg) { f32x4 v = *(const f32x4*)(red + gg * 256 + 4 * l); r += v; }
;     asm volatile("" ::: "memory");
;     __builtin_amdgcn_wave_barrier();
;     {
;       hv += r;
;       *(f32x4*)hq = hv;
;       if (!last) { u32x2 o; o[0] = cvtpk(hv[0], hv[1]); o[1] = cvtpk(hv[2], hv[3]); *(u32x2*)((char*)p.hb + ((unsigned)t * 2048u + (unsigned)(sl * 512 + l * 8))) = o; }
;     }
;     tt = tn;
	v_cvt_scalef32_pk_f32_fp4 v[100:101], v165, 1.0 op_sel:[1,0,0]
	v_cvt_scalef32_pk_f32_fp4 v[102:103], v165, 1.0 op_sel:[0,1,0]
	v_cvt_scalef32_pk_f32_fp4 v[104:105], v165, 1.0 op_sel:[1,1,0]
	v_pk_fma_f32 v[90:91], v[40:41], v[98:99], v[90:91] op_sel_hi:[0,1,1]
	v_pk_fma_f32 v[92:93], v[40:41], v[100:101], v[92:93] op_sel_hi:[0,1,1]
	v_pk_fma_f32 v[94:95], v[40:41], v[102:103], v[94:95] op_sel_hi:[0,1,1]
	v_pk_fma_f32 v[96:97], v[40:41], v[104:105], v[96:97] op_sel_hi:[0,1,1]
	v_cvt_scalef32_pk_f32_fp4 v[98:99], v166, 1.0
	v_cvt_scalef32_pk_f32_fp4 v[100:101], v166, 1.0 op_sel:[1,0,0]
	v_cvt_scalef32_pk_f32_fp4 v[102:103], v166, 1.0 op_sel:[0,1,0]
	v_cvt_scalef32_pk_f32_fp4 v[104:105], v166, 1.0 op_sel:[1,1,0]
	v_pk_fma_f32 v[66:67], v[40:41], v[98:99], v[66:67] op_sel:[1,0,0] op_sel_hi:[1,1,1]
	v_pk_fma_f32 v[68:69], v[40:41], v[100:101], v[68:69] op_sel:[1,0,0] op_sel_hi:[1,1,1]
	v_pk_fma_f32 v[70:71], v[40:41], v[102:103], v[70:71] op_sel:[1,0,0] op_sel_hi:[1,1,1]
	v_pk_fma_f32 v[72:73], v[40:41], v[104:105], v[72:73] op_sel:[1,0,0] op_sel_hi:[1,1,1]
	v_cvt_scalef32_pk_f32_fp4 v[98:99], v167, 1.0
	v_cvt_scalef32_pk_f32_fp4 v[100:101], v167, 1.0 op_sel:[1,0,0]
	v_cvt_scalef32_pk_f32_fp4 v[102:103], v167, 1.0 op_sel:[0,1,0]
	v_cvt_scalef32_pk_f32_fp4 v[104:105], v167, 1.0 op_sel:[1,1,0]
	v_pk_fma_f32 v[74:75], v[40:41], v[98:99], v[74:75] op_sel:[1,0,0] op_sel_hi:[1,1,1]
	v_pk_fma_f32 v[76:77], v[40:41], v[100:101], v[76:77] op_sel:[1,0,0] op_sel_hi:[1,1,1]
	v_pk_fma_f32 v[78:79], v[40:41], v[102:103], v[78:79] op_sel:[1,0,0] op_sel_hi:[1,1,1]
	v_pk_fma_f32 v[80:81], v[40:41], v[104:105], v[80:81] op_sel:[1,0,0] op_sel_hi:[1,1,1]
	v_cvt_scalef32_pk_f32_fp4 v[98:99], v168, 1.0
	v_cvt_scalef32_pk_f32_fp4 v[100:101], v168, 1.0 op_sel:[1,0,0]
	v_cvt_scalef32_pk_f32_fp4 v[102:103], v168, 1.0 op_sel:[0,1,0]
	v_cvt_scalef32_pk_f32_fp4 v[104:105], v168, 1.0 op_sel:[1,1,0]
	v_pk_fma_f32 v[82:83], v[40:41], v[98:99], v[82:83] op_sel:[1,0,0] op_sel_hi:[1,1,1]
	v_pk_fma_f32 v[84:85], v[40:41], v[100:101], v[84:85] op_sel:[1,0,0] op_sel_hi:[1,1,1]
	v_pk_fma_f32 v[86:87], v[40:41], v[102:103], v[86:87] op_sel:[1,0,0] op_sel_hi:[1,1,1]
	v_pk_fma_f32 v[88:89], v[40:41], v[104:105], v[88:89] op_sel:[1,0,0] op_sel_hi:[1,1,1]
	v_cvt_scalef32_pk_f32_fp4 v[98:99], v169, 1.0
	v_cvt_scalef32_pk_f32_fp4 v[100:101], v169, 1.0 op_sel:[1,0,0]
	v_cvt_scalef32_pk_f32_fp4 v[102:103], v169, 1.0 op_sel:[0,1,0]
	v_cvt_scalef32_pk_f32_fp4 v[104:105], v169, 1.0 op_sel:[1,1,0]
	v_pk_fma_f32 v[90:91], v[40:41], v[98:99], v[90:91] op_sel:[1,0,0] op_sel_hi:[1,1,1]
	v_pk_fma_f32 v[92:93], v[40:41], v[100:101], v[92:93] op_sel:[1,0,0] op_sel_hi:[1,1,1]
	v_pk_fma_f32 v[94:95], v[40:41], v[102:103], v[94:95] op_sel:[1,0,0] op_sel_hi:[1,1,1]
	v_pk_fma_f32 v[96:97], v[40:41], v[104:105], v[96:97] op_sel:[1,0,0] op_sel_hi:[1,1,1]
	ds_write_b128 v240, v[66:69]
	ds_write_b128 v241, v[70:73]
	ds_write_b128 v242, v[74:77]
	ds_write_b128 v243, v[78:81]
	ds_write_b128 v244, v[82:85]
	ds_write_b128 v245, v[86:89]
	ds_write_b128 v246, v[90:93]
	ds_write_b128 v247, v[94:97]
	s_waitcnt lgkmcnt(0)
	ds_read_b128 v[66:69], v4
	ds_read_b128 v[70:73], v4 offset:1024
	ds_read_b128 v[74:77], v4 offset:2048
	ds_read_b128 v[78:81], v4 offset:3072
	ds_read_b128 v[82:85], v4 offset:4096
	ds_read_b128 v[86:89], v4 offset:5120
	ds_read_b128 v[90:93], v4 offset:6144
	ds_read_b128 v[94:97], v4 offset:7168
	s_waitcnt lgkmcnt(6)
	v_pk_add_f32 v[66:67], v[66:67], v[70:71]
	v_pk_add_f32 v[68:69], v[68:69], v[72:73]
	s_waitcnt lgkmcnt(5)
	v_pk_add_f32 v[66:67], v[66:67], v[74:75]
	v_pk_add_f32 v[68:69], v[68:69], v[76:77]
	s_waitcnt lgkmcnt(4)
	v_pk_add_f32 v[66:67], v[66:67], v[78:79]
	v_pk_add_f32 v[68:69], v[68:69], v[80:81]
	s_waitcnt lgkmcnt(3)
	v_pk_add_f32 v[66:67], v[66:67], v[82:83]
	v_pk_add_f32 v[68:69], v[68:69], v[84:85]
	s_waitcnt lgkmcnt(2)
	v_pk_add_f32 v[66:67], v[66:67], v[86:87]
	v_pk_add_f32 v[68:69], v[68:69], v[88:89]
	s_waitcnt lgkmcnt(1)
	v_pk_add_f32 v[66:67], v[66:67], v[90:91]
	v_pk_add_f32 v[68:69], v[68:69], v[92:93]
	s_waitcnt lgkmcnt(0)
	v_pk_add_f32 v[66:67], v[66:67], v[94:95]
	v_pk_add_f32 v[68:69], v[68:69], v[96:97]
	v_pk_add_f32 v[58:59], v[58:59], v[66:67]
	v_pk_add_f32 v[60:61], v[60:61], v[68:69]
	global_store_dwordx4 v0, v[58:61], s[44:45]
	v_cvt_pk_bf16_f32 v98, v58, v59
	v_cvt_pk_bf16_f32 v99, v60, v61
	s_lshl_b32 s0, s36, 1
	s_add_u32 s0, s0, s28
	s_lshl_b32 s0, s0, 11
	s_lshl_b32 s1, s14, 9
	s_add_u32 s0, s0, s1
	v_add_u32_e32 v6, s0, v5
	global_store_dwordx2 v6, v[98:99], s[76:77]
	s_mov_b32 s36, s51
	s_cmp_lt_u32 s36, s38
	s_cbranch_scc0 .Lmy_pv0_done

; __device__ __forceinline__ void phase_peer_v(const Params& p, int layer, int xs, int wid0, int wstride, bool last, char* smraw) {
;     ...
;   auto half_fma = [&](const u32x4 (&q)[8], const f32x4& c0, const f32x4& c1) {
; #pragma unroll
;     for (int i = 0; i < 8; ++i) {
;       const float ci = i < 4 ? c0[i & 3] : c1[i & 3];
; #pragma unroll
;       for (int m = 0; m < 4; ++m) {
;         unsigned dw = q[i][m];
;         asm volatile("" : "+v"(dw) : "v"(acc[(8 * m + 31) & 31]));
;         const f32x2 e0 = __builtin_amdgcn_cvt_scalef32_pk_f32_fp4(dw, 1.0f, 0), e1 = __builtin_amdgcn_cvt_scalef32_pk_f32_fp4(dw, 1.0f, 1);
;         const f32x2 e2 = __builtin_amdgcn_cvt_scalef32_pk_f32_fp4(dw, 1.0f, 2), e3 = __builtin_amdgcn_cvt_scalef32_pk_f32_fp4(dw, 1.0f, 3);
;         acc[8 * m + 0] += ci * e0[0]; acc[8 * m + 1] += ci * e0[1]; acc[8 * m + 2] += ci * e1[0]; acc[8 * m + 3] += ci * e1[1];
;         acc[8 * m + 4] += ci * e2[0]; acc[8 * m + 5] += ci * e2[1]; acc[8 * m + 6] += ci * e3[0]; acc[8 * m + 7] += ci * e3[1];
;       }
;     }
;   };
.Lmy_pv0_noissueB:
	v_cvt_scalef32_pk_f32_fp4 v[98:99], v170, 1.0
	v_cvt_scalef32_pk_f32_fp4 v[100:101], v170, 1.0 op_sel:[1,0,0]
	v_cvt_scalef32_pk_f32_fp4 v[102:103], v170, 1.0 op_sel:[0,1,0]
	v_cvt_scalef32_pk_f32_fp4 v[104:105], v170, 1.0 op_sel:[1,1,0]
	v_pk_fma_f32 v[66:67], v[42:43], v[98:99], 0 op_sel_hi:[0,1,0]
	v_pk_fma_f32 v[68:69], v[42:43], v[100:101], 0 op_sel_hi:[0,1,0]
	v_pk_fma_f32 v[70:71], v[42:43], v[102:103], 0 op_sel_hi:[0,1,0]
	v_pk_fma_f32 v[72:73], v[42:43], v[104:105], 0 op_sel_hi:[0,1,0]
	v_cvt_scalef32_pk_f32_fp4 v[98:99], v171, 1.0
	v_cvt_scalef32_pk_f32_fp4 v[100:101], v171, 1.0 op_sel:[1,0,0]
	v_cvt_scalef32_pk_f32_fp4 v[102:103], v171, 1.0 op_sel:[0,1,0]
	v_cvt_scalef32_pk_f32_fp4 v[104:105], v171, 1.0 op_sel:[1,1,0]
	v_pk_fma_f32 v[74:75], v[42:43], v[98:99], 0 op_sel_hi:[0,1,0]
	v_pk_fma_f32 v[76:77], v[42:43], v[100:101], 0 op_sel_hi:[0,1,0]
	v_pk_fma_f32 v[78:79], v[42:43], v[102:103], 0 op_sel_hi:[0,1,0]
	v_pk_fma_f32 v[80:81], v[42:43], v[104:105], 0 op_sel_hi:[0,1,0]
	v_cvt_scalef32_pk_f32_fp4 v[98:99], v172, 1.0
	v_cvt_scalef32_pk_f32_fp4 v[100:101], v172, 1.0 op_sel:[1,0,0]
	v_cvt_scalef32_pk_f32_fp4 v[102:103], v172, 1.0 op_sel:[0,1,0]
	v_cvt_scalef32_pk_f32_fp4 v[104:105], v172, 1.0 op_sel:[1,1,0]
	v_pk_fma_f32 v[82:83], v[42:43], v[98:99], 0 op_sel_hi:[0,1,0]
	v_pk_fma_f32 v[84:85], v[42:43], v[100:101], 0 op_sel_hi:[0,1,0]
	v_pk_fma_f32 v[86:87], v[42:43], v[102:103], 0 op_sel_hi:[0,1,0]
	v_pk_fma_f32 v[88:89], v[42:43], v[104:105], 0 op_sel_hi:[0,1,0]
	v_cvt_scalef32_pk_f32_fp4 v[98:99], v173, 1.0
	v_cvt_scalef32_pk_f32_fp4 v[100:101], v173, 1.0 op_sel:[1,0,0]
	v_cvt_scalef32_pk_f32_fp4 v[102:103], v173, 1.0 op_sel:[0,1,0]
	v_cvt_scalef32_pk_f32_fp4 v[104:105], v173, 1.0 op_sel:[1,1,0]
	v_pk_fma_f32 v[90:91], v[42:43], v[98:99], 0 op_sel_hi:[0,1,0]
	v_pk_fma_f32 v[92:93], v[42:43], v[100:101], 0 op_sel_hi:[0,1,0]
	v_pk_fma_f32 v[94:95], v[42:43], v[102:103], 0 op_sel_hi:[0,1,0]
	v_pk_fma_f32 v[96:97], v[42:43], v[104:105], 0 op_sel_hi:[0,1,0]
	v_cvt_scalef32_pk_f32_fp4 v[98:99], v174, 1.0
	v_cvt_scalef32_pk_f32_fp4 v[100:101], v174, 1.0 op_sel:[1,0,0]
	v_cvt_scalef32_pk_f32_fp4 v[102:103], v174, 1.0 op_sel:[0,1,0]
	v_cvt_scalef32_pk_f32_fp4 v[104:105], v174, 1.0 op_sel:[1,1,0]
	v_pk_fma_f32 v[66:67], v[42:43], v[98:99], v[66:67] op_sel:[1,0,0] op_sel_hi:[1,1,1]
	v_pk_fma_f32 v[68:69], v[42:43], v[100:101], v[68:69] op_sel:[1,0,0] op_sel_hi:[1,1,1]
	v_pk_fma_f32 v[70:71], v[42:43], v[102:103], v[70:71] op_sel:[1,0,0] op_sel_hi:[1,1,1]
	v_pk_fma_f32 v[72:73], v[42:43], v[104:105], v[72:73] op_sel:[1,0,0] op_sel_hi:[1,1,1]
	v_cvt_scalef32_pk_f32_fp4 v[98:99], v175, 1.0
	v_cvt_scalef32_pk_f32_fp4 v[100:101], v175, 1.0 op_sel:[1,0,0]
	v_cvt_scalef32_pk_f32_fp4 v[102:103], v175, 1.0 op_sel:[0,1,0]
	v_cvt_scalef32_pk_f32_fp4 v[104:105], v175, 1.0 op_sel:[1,1,0]
	v_pk_fma_f32 v[74:75], v[42:43], v[98:99], v[74:75] op_sel:[1,0,0] op_sel_hi:[1,1,1]
	v_pk_fma_f32 v[76:77], v[42:43], v[100:101], v[76:77] op_sel:[1,0,0] op_sel_hi:[1,1,1]
	v_pk_fma_f32 v[78:79], v[42:43], v[102:103], v[78:79] op_sel:[1,0,0] op_sel_hi:[1,1,1]
	v_pk_fma_f32 v[80:81], v[42:43], v[104:105], v[80:81] op_sel:[1,0,0] op_sel_hi:[1,1,1]
	v_cvt_scalef32_pk_f32_fp4 v[98:99], v176, 1.0
	v_cvt_scalef32_pk_f32_fp4 v[100:101], v176, 1.0 op_sel:[1,0,0]
	v_cvt_scalef32_pk_f32_fp4 v[102:103], v176, 1.0 op_sel:[0,1,0]
	v_cvt_scalef32_pk_f32_fp4 v[104:105], v176, 1.0 op_sel:[1,1,0]
	v_pk_fma_f32 v[82:83], v[42:43], v[98:99], v[82:83] op_sel:[1,0,0] op_sel_hi:[1,1,1]
	v_pk_fma_f32 v[84:85], v[42:43], v[100:101], v[84:85] op_sel:[1,0,0] op_sel_hi:[1,1,1]
	v_pk_fma_f32 v[86:87], v[42:43], v[102:103], v[86:87] op_sel:[1,0,0] op_sel_hi:[1,1,1]
	v_pk_fma_f32 v[88:89], v[42:43], v[104:105], v[88:89] op_sel:[1,0,0] op_sel_hi:[1,1,1]
	v_cvt_scalef32_pk_f32_fp4 v[98:99], v177, 1.0
	v_cvt_scalef32_pk_f32_fp4 v[100:101], v177, 1.0 op_sel:[1,0,0]
	v_cvt_scalef32_pk_f32_fp4 v[102:103], v177, 1.0 op_sel:[0,1,0]
	v_cvt_scalef32_pk_f32_fp4 v[104:105], v177, 1.0 op_sel:[1,1,0]
	v_pk_fma_f32 v[90:91], v[42:43], v[98:99], v[90:91] op_sel:[1,0,0] op_sel_hi:[1,1,1]
	v_pk_fma_f32 v[92:93], v[42:43], v[100:101], v[92:93] op_sel:[1,0,0] op_sel_hi:[1,1,1]
	v_pk_fma_f32 v[94:95], v[42:43], v[102:103], v[94:95] op_sel:[1,0,0] op_sel_hi:[1,1,1]
	v_pk_fma_f32 v[96:97], v[42:43], v[104:105], v[96:97] op_sel:[1,0,0] op_sel_hi:[1,1,1]
	v_cvt_scalef32_pk_f32_fp4 v[98:99], v178, 1.0
	v_cvt_scalef32_pk_f32_fp4 v[100:101], v178, 1.0 op_sel:[1,0,0]
	v_cvt_scalef32_pk_f32_fp4 v[102:103], v178, 1.0 op_sel:[0,1,0]
	v_cvt_scalef32_pk_f32_fp4 v[104:105], v178, 1.0 op_sel:[1,1,0]
	v_pk_fma_f32 v[66:67], v[44:45], v[98:99], v[66:67] op_sel_hi:[0,1,1]
	v_pk_fma_f32 v[68:69], v[44:45], v[100:101], v[68:69] op_sel_hi:[0,1,1]
	v_pk_fma_f32 v[70:71], v[44:45], v[102:103], v[70:71] op_sel_hi:[0,1,1]
	v_pk_fma_f32 v[72:73], v[44:45], v[104:105], v[72:73] op_sel_hi:[0,1,1]
	v_cvt_scalef32_pk_f32_fp4 v[98:99], v179, 1.0
	v_cvt_scalef32_pk_f32_fp4 v[100:101], v179, 1.0 op_sel:[1,0,0]
	v_cvt_scalef32_pk_f32_fp4 v[102:103], v179, 1.0 op_sel:[0,1,0]
	v_cvt_scalef32_pk_f32_fp4 v[104:105], v179, 1.0 op_sel:[1,1,0]
	v_pk_fma_f32 v[74:75], v[44:45], v[98:99], v[74:75] op_sel_hi:[0,1,1]
	v_pk_fma_f32 v[76:77], v[44:45], v[100:101], v[76:77] op_sel_hi:[0,1,1]
	v_pk_fma_f32 v[78:79], v[44:45], v[102:103], v[78:79] op_sel_hi:[0,1,1]
	v_pk_fma_f32 v[80:81], v[44:45], v[104:105], v[80:81] op_sel_hi:[0,1,1]
	v_cvt_scalef32_pk_f32_fp4 v[98:99], v180, 1.0
	v_cvt_scalef32_pk_f32_fp4 v[100:101], v180, 1.0 op_sel:[1,0,0]
	v_cvt_scalef32_pk_f32_fp4 v[102:103], v180, 1.0 op_sel:[0,1,0]
; __device__ __forceinline__ void phase_peer_v(const Params& p, int layer, int xs, int wid0, int wstride, bool last, char* smraw) {
;     ...
;   auto half_fma = [&](const u32x4 (&q)[8], const f32x4& c0, const f32x4& c1) {
; #pragma unroll
;     for (int i = 0; i < 8; ++i) {
;       const float ci = i < 4 ? c0[i & 3] : c1[i & 3];
; #pragma unroll
;       for (int m = 0; m < 4; ++m) {
;         unsigned dw = q[i][m];
;         asm volatile("" : "+v"(dw) : "v"(acc[(8 * m + 31) & 31]));
;         const f32x2 e0 = __builtin_amdgcn_cvt_scalef32_pk_f32_fp4(dw, 1.0f, 0), e1 = __builtin_amdgcn_cvt_scalef32_pk_f32_fp4(dw, 1.0f, 1);
;         const f32x2 e2 = __builtin_amdgcn_cvt_scalef32_pk_f32_fp4(dw, 1.0f, 2), e3 = __builtin_amdgcn_cvt_scalef32_pk_f32_fp4(dw, 1.0f, 3);
;         acc[8 * m + 0] += ci * e0[0]; acc[8 * m + 1] += ci * e0[1]; acc[8 * m + 2] += ci * e1[0]; acc[8 * m + 3] += ci * e1[1];
;         acc[8 * m + 4] += ci * e2[0]; acc[8 * m + 5] += ci * e2[1]; acc[8 * m + 6] += ci * e3[0]; acc[8 * m + 7] += ci * e3[1];
;       }
;     }
;   };
	v_cvt_scalef32_pk_f32_fp4 v[104:105], v180, 1.0 op_sel:[1,1,0]
	v_pk_fma_f32 v[82:83], v[44:45], v[98:99], v[82:83] op_sel_hi:[0,1,1]
	v_pk_fma_f32 v[84:85], v[44:45], v[100:101], v[84:85] op_sel_hi:[0,1,1]
	v_pk_fma_f32 v[86:87], v[44:45], v[102:103], v[86:87] op_sel_hi:[0,1,1]
	v_pk_fma_f32 v[88:89], v[44:45], v[104:105], v[88:89] op_sel_hi:[0,1,1]
	v_cvt_scalef32_pk_f32_fp4 v[98:99], v181, 1.0
	v_cvt_scalef32_pk_f32_fp4 v[100:101], v181, 1.0 op_sel:[1,0,0]
	v_cvt_scalef32_pk_f32_fp4 v[102:103], v181, 1.0 op_sel:[0,1,0]
	v_cvt_scalef32_pk_f32_fp4 v[104:105], v181, 1.0 op_sel:[1,1,0]
	v_pk_fma_f32 v[90:91], v[44:45], v[98:99], v[90:91] op_sel_hi:[0,1,1]
	v_pk_fma_f32 v[92:93], v[44:45], v[100:101], v[92:93] op_sel_hi:[0,1,1]
	v_pk_fma_f32 v[94:95], v[44:45], v[102:103], v[94:95] op_sel_hi:[0,1,1]
	v_pk_fma_f32 v[96:97], v[44:45], v[104:105], v[96:97] op_sel_hi:[0,1,1]
	v_cvt_scalef32_pk_f32_fp4 v[98:99], v182, 1.0
	v_cvt_scalef32_pk_f32_fp4 v[100:101], v182, 1.0 op_sel:[1,0,0]
	v_cvt_scalef32_pk_f32_fp4 v[102:103], v182, 1.0 op_sel:[0,1,0]
	v_cvt_scalef32_pk_f32_fp4 v[104:105], v182, 1.0 op_sel:[1,1,0]
	v_pk_fma_f32 v[66:67], v[44:45], v[98:99], v[66:67] op_sel:[1,0,0] op_sel_hi:[1,1,1]
	v_pk_fma_f32 v[68:69], v[44:45], v[100:101], v[68:69] op_sel:[1,0,0] op_sel_hi:[1,1,1]
	v_pk_fma_f32 v[70:71], v[44:45], v[102:103], v[70:71] op_sel:[1,0,0] op_sel_hi:[1,1,1]
	v_pk_fma_f32 v[72:73], v[44:45], v[104:105], v[72:73] op_sel:[1,0,0] op_sel_hi:[1,1,1]
	v_cvt_scalef32_pk_f32_fp4 v[98:99], v183, 1.0
	v_cvt_scalef32_pk_f32_fp4 v[100:101], v183, 1.0 op_sel:[1,0,0]
	v_cvt_scalef32_pk_f32_fp4 v[102:103], v183, 1.0 op_sel:[0,1,0]
	v_cvt_scalef32_pk_f32_fp4 v[104:105], v183, 1.0 op_sel:[1,1,0]
	v_pk_fma_f32 v[74:75], v[44:45], v[98:99], v[74:75] op_sel:[1,0,0] op_sel_hi:[1,1,1]
	v_pk_fma_f32 v[76:77], v[44:45], v[100:101], v[76:77] op_sel:[1,0,0] op_sel_hi:[1,1,1]
	v_pk_fma_f32 v[78:79], v[44:45], v[102:103], v[78:79] op_sel:[1,0,0] op_sel_hi:[1,1,1]
	v_pk_fma_f32 v[80:81], v[44:45], v[104:105], v[80:81] op_sel:[1,0,0] op_sel_hi:[1,1,1]
	v_cvt_scalef32_pk_f32_fp4 v[98:99], v184, 1.0
	v_cvt_scalef32_pk_f32_fp4 v[100:101], v184, 1.0 op_sel:[1,0,0]
	v_cvt_scalef32_pk_f32_fp4 v[102:103], v184, 1.0 op_sel:[0,1,0]
	v_cvt_scalef32_pk_f32_fp4 v[104:105], v184, 1.0 op_sel:[1,1,0]
	v_pk_fma_f32 v[82:83], v[44:45], v[98:99], v[82:83] op_sel:[1,0,0] op_sel_hi:[1,1,1]
	v_pk_fma_f32 v[84:85], v[44:45], v[100:101], v[84:85] op_sel:[1,0,0] op_sel_hi:[1,1,1]
	v_pk_fma_f32 v[86:87], v[44:45], v[102:103], v[86:87] op_sel:[1,0,0] op_sel_hi:[1,1,1]
	v_pk_fma_f32 v[88:89], v[44:45], v[104:105], v[88:89] op_sel:[1,0,0] op_sel_hi:[1,1,1]
	v_cvt_scalef32_pk_f32_fp4 v[98:99], v185, 1.0
	v_cvt_scalef32_pk_f32_fp4 v[100:101], v185, 1.0 op_sel:[1,0,0]
	v_cvt_scalef32_pk_f32_fp4 v[102:103], v185, 1.0 op_sel:[0,1,0]
	v_cvt_scalef32_pk_f32_fp4 v[104:105], v185, 1.0 op_sel:[1,1,0]
	v_pk_fma_f32 v[90:91], v[44:45], v[98:99], v[90:91] op_sel:[1,0,0] op_sel_hi:[1,1,1]
	v_pk_fma_f32 v[92:93], v[44:45], v[100:101], v[92:93] op_sel:[1,0,0] op_sel_hi:[1,1,1]
	v_pk_fma_f32 v[94:95], v[44:45], v[102:103], v[94:95] op_sel:[1,0,0] op_sel_hi:[1,1,1]
	v_pk_fma_f32 v[96:97], v[44:45], v[104:105], v[96:97] op_sel:[1,0,0] op_sel_hi:[1,1,1]
	v_cvt_scalef32_pk_f32_fp4 v[98:99], v192, 1.0
	v_cvt_scalef32_pk_f32_fp4 v[100:101], v192, 1.0 op_sel:[1,0,0]
	v_cvt_scalef32_pk_f32_fp4 v[102:103], v192, 1.0 op_sel:[0,1,0]
	v_cvt_scalef32_pk_f32_fp4 v[104:105], v192, 1.0 op_sel:[1,1,0]
	v_pk_fma_f32 v[66:67], v[46:47], v[98:99], v[66:67] op_sel_hi:[0,1,1]
	v_pk_fma_f32 v[68:69], v[46:47], v[100:101], v[68:69] op_sel_hi:[0,1,1]
	v_pk_fma_f32 v[70:71], v[46:47], v[102:103], v[70:71] op_sel_hi:[0,1,1]
	v_pk_fma_f32 v[72:73], v[46:47], v[104:105], v[72:73] op_sel_hi:[0,1,1]
	v_cvt_scalef32_pk_f32_fp4 v[98:99], v193, 1.0
	v_cvt_scalef32_pk_f32_fp4 v[100:101], v193, 1.0 op_sel:[1,0,0]
	v_cvt_scalef32_pk_f32_fp4 v[102:103], v193, 1.0 op_sel:[0,1,0]
	v_cvt_scalef32_pk_f32_fp4 v[104:105], v193, 1.0 op_sel:[1,1,0]
	v_pk_fma_f32 v[74:75], v[46:47], v[98:99], v[74:75] op_sel_hi:[0,1,1]
	v_pk_fma_f32 v[76:77], v[46:47], v[100:101], v[76:77] op_sel_hi:[0,1,1]
	v_pk_fma_f32 v[78:79], v[46:47], v[102:103], v[78:79] op_sel_hi:[0,1,1]
	v_pk_fma_f32 v[80:81], v[46:47], v[104:105], v[80:81] op_sel_hi:[0,1,1]
	v_cvt_scalef32_pk_f32_fp4 v[98:99], v194, 1.0
	v_cvt_scalef32_pk_f32_fp4 v[100:101], v194, 1.0 op_sel:[1,0,0]
	v_cvt_scalef32_pk_f32_fp4 v[102:103], v194, 1.0 op_sel:[0,1,0]
	v_cvt_scalef32_pk_f32_fp4 v[104:105], v194, 1.0 op_sel:[1,1,0]
	v_pk_fma_f32 v[82:83], v[46:47], v[98:99], v[82:83] op_sel_hi:[0,1,1]
	v_pk_fma_f32 v[84:85], v[46:47], v[100:101], v[84:85] op_sel_hi:[0,1,1]
	v_pk_fma_f32 v[86:87], v[46:47], v[102:103], v[86:87] op_sel_hi:[0,1,1]
	v_pk_fma_f32 v[88:89], v[46:47], v[104:105], v[88:89] op_sel_hi:[0,1,1]
	v_cvt_scalef32_pk_f32_fp4 v[98:99], v195, 1.0
	v_cvt_scalef32_pk_f32_fp4 v[100:101], v195, 1.0 op_sel:[1,0,0]
	v_cvt_scalef32_pk_f32_fp4 v[102:103], v195, 1.0 op_sel:[0,1,0]
	v_cvt_scalef32_pk_f32_fp4 v[104:105], v195, 1.0 op_sel:[1,1,0]
	v_pk_fma_f32 v[90:91], v[46:47], v[98:99], v[90:91] op_sel_hi:[0,1,1]
	v_pk_fma_f32 v[92:93], v[46:47], v[100:101], v[92:93] op_sel_hi:[0,1,1]
	v_pk_fma_f32 v[94:95], v[46:47], v[102:103], v[94:95] op_sel_hi:[0,1,1]
	v_pk_fma_f32 v[96:97], v[46:47], v[104:105], v[96:97] op_sel_hi:[0,1,1]
	v_cvt_scalef32_pk_f32_fp4 v[98:99], v196, 1.0
	v_cvt_scalef32_pk_f32_fp4 v[100:101], v196, 1.0 op_sel:[1,0,0]
	v_cvt_scalef32_pk_f32_fp4 v[102:103], v196, 1.0 op_sel:[0,1,0]
	v_cvt_scalef32_pk_f32_fp4 v[104:105], v196, 1.0 op_sel:[1,1,0]
	v_pk_fma_f32 v[66:67], v[46:47], v[98:99], v[66:67] op_sel:[1,0,0] op_sel_hi:[1,1,1]
; __device__ __forceinline__ void phase_peer_v(const Params& p, int layer, int xs, int wid0, int wstride, bool last, char* smraw) {
;     ...
;   auto half_fma = [&](const u32x4 (&q)[8], const f32x4& c0, const f32x4& c1) {
; #pragma unroll
;     for (int i = 0; i < 8; ++i) {
;       const float ci = i < 4 ? c0[i & 3] : c1[i & 3];
; #pragma unroll
;       for (int m = 0; m < 4; ++m) {
;         unsigned dw = q[i][m];
;         asm volatile("" : "+v"(dw) : "v"(acc[(8 * m + 31) & 31]));
;         const f32x2 e0 = __builtin_amdgcn_cvt_scalef32_pk_f32_fp4(dw, 1.0f, 0), e1 = __builtin_amdgcn_cvt_scalef32_pk_f32_fp4(dw, 1.0f, 1);
;         const f32x2 e2 = __builtin_amdgcn_cvt_scalef32_pk_f32_fp4(dw, 1.0f, 2), e3 = __builtin_amdgcn_cvt_scalef32_pk_f32_fp4(dw, 1.0f, 3);
;         acc[8 * m + 0] += ci * e0[0]; acc[8 * m + 1] += ci * e0[1]; acc[8 * m + 2] += ci * e1[0]; acc[8 * m + 3] += ci * e1[1];
;         acc[8 * m + 4] += ci * e2[0]; acc[8 * m + 5] += ci * e2[1]; acc[8 * m + 6] += ci * e3[0]; acc[8 * m + 7] += ci * e3[1];
;       }
;     }
	v_pk_fma_f32 v[68:69], v[46:47], v[100:101], v[68:69] op_sel:[1,0,0] op_sel_hi:[1,1,1]
	v_pk_fma_f32 v[70:71], v[46:47], v[102:103], v[70:71] op_sel:[1,0,0] op_sel_hi:[1,1,1]
	v_pk_fma_f32 v[72:73], v[46:47], v[104:105], v[72:73] op_sel:[1,0,0] op_sel_hi:[1,1,1]
	v_cvt_scalef32_pk_f32_fp4 v[98:99], v197, 1.0
	v_cvt_scalef32_pk_f32_fp4 v[100:101], v197, 1.0 op_sel:[1,0,0]
	v_cvt_scalef32_pk_f32_fp4 v[102:103], v197, 1.0 op_sel:[0,1,0]
	v_cvt_scalef32_pk_f32_fp4 v[104:105], v197, 1.0 op_sel:[1,1,0]
	v_pk_fma_f32 v[74:75], v[46:47], v[98:99], v[74:75] op_sel:[1,0,0] op_sel_hi:[1,1,1]
	v_pk_fma_f32 v[76:77], v[46:47], v[100:101], v[76:77] op_sel:[1,0,0] op_sel_hi:[1,1,1]
	v_pk_fma_f32 v[78:79], v[46:47], v[102:103], v[78:79] op_sel:[1,0,0] op_sel_hi:[1,1,1]
	v_pk_fma_f32 v[80:81], v[46:47], v[104:105], v[80:81] op_sel:[1,0,0] op_sel_hi:[1,1,1]
	v_cvt_scalef32_pk_f32_fp4 v[98:99], v198, 1.0
	v_cvt_scalef32_pk_f32_fp4 v[100:101], v198, 1.0 op_sel:[1,0,0]
	v_cvt_scalef32_pk_f32_fp4 v[102:103], v198, 1.0 op_sel:[0,1,0]
	v_cvt_scalef32_pk_f32_fp4 v[104:105], v198, 1.0 op_sel:[1,1,0]
	v_pk_fma_f32 v[82:83], v[46:47], v[98:99], v[82:83] op_sel:[1,0,0] op_sel_hi:[1,1,1]
	v_pk_fma_f32 v[84:85], v[46:47], v[100:101], v[84:85] op_sel:[1,0,0] op_sel_hi:[1,1,1]
	v_pk_fma_f32 v[86:87], v[46:47], v[102:103], v[86:87] op_sel:[1,0,0] op_sel_hi:[1,1,1]
	v_pk_fma_f32 v[88:89], v[46:47], v[104:105], v[88:89] op_sel:[1,0,0] op_sel_hi:[1,1,1]
	v_cvt_scalef32_pk_f32_fp4 v[98:99], v199, 1.0
	v_cvt_scalef32_pk_f32_fp4 v[100:101], v199, 1.0 op_sel:[1,0,0]
	v_cvt_scalef32_pk_f32_fp4 v[102:103], v199, 1.0 op_sel:[0,1,0]
	v_cvt_scalef32_pk_f32_fp4 v[104:105], v199, 1.0 op_sel:[1,1,0]
	v_pk_fma_f32 v[90:91], v[46:47], v[98:99], v[90:91] op_sel:[1,0,0] op_sel_hi:[1,1,1]
	v_pk_fma_f32 v[92:93], v[46:47], v[100:101], v[92:93] op_sel:[1,0,0] op_sel_hi:[1,1,1]
	v_pk_fma_f32 v[94:95], v[46:47], v[102:103], v[94:95] op_sel:[1,0,0] op_sel_hi:[1,1,1]
	v_pk_fma_f32 v[96:97], v[46:47], v[104:105], v[96:97] op_sel:[1,0,0] op_sel_hi:[1,1,1]
	v_cvt_scalef32_pk_f32_fp4 v[98:99], v200, 1.0
	v_cvt_scalef32_pk_f32_fp4 v[100:101], v200, 1.0 op_sel:[1,0,0]
	v_cvt_scalef32_pk_f32_fp4 v[102:103], v200, 1.0 op_sel:[0,1,0]
	v_cvt_scalef32_pk_f32_fp4 v[104:105], v200, 1.0 op_sel:[1,1,0]
	v_pk_fma_f32 v[66:67], v[48:49], v[98:99], v[66:67] op_sel_hi:[0,1,1]
	v_pk_fma_f32 v[68:69], v[48:49], v[100:101], v[68:69] op_sel_hi:[0,1,1]
	v_pk_fma_f32 v[70:71], v[48:49], v[102:103], v[70:71] op_sel_hi:[0,1,1]
	v_pk_fma_f32 v[72:73], v[48:49], v[104:105], v[72:73] op_sel_hi:[0,1,1]
	v_cvt_scalef32_pk_f32_fp4 v[98:99], v201, 1.0
	v_cvt_scalef32_pk_f32_fp4 v[100:101], v201, 1.0 op_sel:[1,0,0]
	v_cvt_scalef32_pk_f32_fp4 v[102:103], v201, 1.0 op_sel:[0,1,0]
	v_cvt_scalef32_pk_f32_fp4 v[104:105], v201, 1.0 op_sel:[1,1,0]
	v_pk_fma_f32 v[74:75], v[48:49], v[98:99], v[74:75] op_sel_hi:[0,1,1]
	v_pk_fma_f32 v[76:77], v[48:49], v[100:101], v[76:77] op_sel_hi:[0,1,1]
	v_pk_fma_f32 v[78:79], v[48:49], v[102:103], v[78:79] op_sel_hi:[0,1,1]
	v_pk_fma_f32 v[80:81], v[48:49], v[104:105], v[80:81] op_sel_hi:[0,1,1]
	v_cvt_scalef32_pk_f32_fp4 v[98:99], v202, 1.0
	v_cvt_scalef32_pk_f32_fp4 v[100:101], v202, 1.0 op_sel:[1,0,0]
	v_cvt_scalef32_pk_f32_fp4 v[102:103], v202, 1.0 op_sel:[0,1,0]
	v_cvt_scalef32_pk_f32_fp4 v[104:105], v202, 1.0 op_sel:[1,1,0]
	v_pk_fma_f32 v[82:83], v[48:49], v[98:99], v[82:83] op_sel_hi:[0,1,1]
	v_pk_fma_f32 v[84:85], v[48:49], v[100:101], v[84:85] op_sel_hi:[0,1,1]
	v_pk_fma_f32 v[86:87], v[48:49], v[102:103], v[86:87] op_sel_hi:[0,1,1]
	v_pk_fma_f32 v[88:89], v[48:49], v[104:105], v[88:89] op_sel_hi:[0,1,1]
	v_cvt_scalef32_pk_f32_fp4 v[98:99], v203, 1.0
	v_cvt_scalef32_pk_f32_fp4 v[100:101], v203, 1.0 op_sel:[1,0,0]
	v_cvt_scalef32_pk_f32_fp4 v[102:103], v203, 1.0 op_sel:[0,1,0]
	v_cvt_scalef32_pk_f32_fp4 v[104:105], v203, 1.0 op_sel:[1,1,0]
	v_pk_fma_f32 v[90:91], v[48:49], v[98:99], v[90:91] op_sel_hi:[0,1,1]
	v_pk_fma_f32 v[92:93], v[48:49], v[100:101], v[92:93] op_sel_hi:[0,1,1]
	v_pk_fma_f32 v[94:95], v[48:49], v[102:103], v[94:95] op_sel_hi:[0,1,1]
	v_pk_fma_f32 v[96:97], v[48:49], v[104:105], v[96:97] op_sel_hi:[0,1,1]
	v_cvt_scalef32_pk_f32_fp4 v[98:99], v204, 1.0
	v_cvt_scalef32_pk_f32_fp4 v[100:101], v204, 1.0 op_sel:[1,0,0]
	v_cvt_scalef32_pk_f32_fp4 v[102:103], v204, 1.0 op_sel:[0,1,0]
	v_cvt_scalef32_pk_f32_fp4 v[104:105], v204, 1.0 op_sel:[1,1,0]
	v_pk_fma_f32 v[66:67], v[48:49], v[98:99], v[66:67] op_sel:[1,0,0] op_sel_hi:[1,1,1]
	v_pk_fma_f32 v[68:69], v[48:49], v[100:101], v[68:69] op_sel:[1,0,0] op_sel_hi:[1,1,1]
	v_pk_fma_f32 v[70:71], v[48:49], v[102:103], v[70:71] op_sel:[1,0,0] op_sel_hi:[1,1,1]
	v_pk_fma_f32 v[72:73], v[48:49], v[104:105], v[72:73] op_sel:[1,0,0] op_sel_hi:[1,1,1]
	v_cvt_scalef32_pk_f32_fp4 v[98:99], v205, 1.0
	v_cvt_scalef32_pk_f32_fp4 v[100:101], v205, 1.0 op_sel:[1,0,0]
	v_cvt_scalef32_pk_f32_fp4 v[102:103], v205, 1.0 op_sel:[0,1,0]
	v_cvt_scalef32_pk_f32_fp4 v[104:105], v205, 1.0 op_sel:[1,1,0]
	v_pk_fma_f32 v[74:75], v[48:49], v[98:99], v[74:75] op_sel:[1,0,0] op_sel_hi:[1,1,1]
	v_pk_fma_f32 v[76:77], v[48:49], v[100:101], v[76:77] op_sel:[1,0,0] op_sel_hi:[1,1,1]
	v_pk_fma_f32 v[78:79], v[48:49], v[102:103], v[78:79] op_sel:[1,0,0] op_sel_hi:[1,1,1]
	v_pk_fma_f32 v[80:81], v[48:49], v[104:105], v[80:81] op_sel:[1,0,0] op_sel_hi:[1,1,1]
	v_cvt_scalef32_pk_f32_fp4 v[98:99], v206, 1.0
	v_cvt_scalef32_pk_f32_fp4 v[100:101], v206, 1.0 op_sel:[1,0,0]
	v_cvt_scalef32_pk_f32_fp4 v[102:103], v206, 1.0 op_sel:[0,1,0]
	v_cvt_scalef32_pk_f32_fp4 v[104:105], v206, 1.0 op_sel:[1,1,0]
	v_pk_fma_f32 v[82:83], v[48:49], v[98:99], v[82:83] op_sel:[1,0,0] op_sel_hi:[1,1,1]
; __device__ __forceinline__ void phase_peer_v(const Params& p, int layer, int xs, int wid0, int wstride, bool last, char* smraw) {
;     ...
;   auto half_fma = [&](const u32x4 (&q)[8], const f32x4& c0, const f32x4& c1) {
; #pragma unroll
;     for (int i = 0; i < 8; ++i) {
;       const float ci = i < 4 ? c0[i & 3] : c1[i & 3];
; #pragma unroll
;       for (int m = 0; m < 4; ++m) {
;         unsigned dw = q[i][m];
;         asm volatile("" : "+v"(dw) : "v"(acc[(8 * m + 31) & 31]));
;         const f32x2 e0 = __builtin_amdgcn_cvt_scalef32_pk_f32_fp4(dw, 1.0f, 0), e1 = __builtin_amdgcn_cvt_scalef32_pk_f32_fp4(dw, 1.0f, 1);
;         const f32x2 e2 = __builtin_amdgcn_cvt_scalef32_pk_f32_fp4(dw, 1.0f, 2), e3 = __builtin_amdgcn_cvt_scalef32_pk_f32_fp4(dw, 1.0f, 3);
;         acc[8 * m + 0] += ci * e0[0]; acc[8 * m + 1] += ci * e0[1]; acc[8 * m + 2] += ci * e1[0]; acc[8 * m + 3] += ci * e1[1];
;         acc[8 * m + 4] += ci * e2[0]; acc[8 * m + 5] += ci * e2[1]; acc[8 * m + 6] += ci * e3[0]; acc[8 * m + 7] += ci * e3[1];
;       }
;     }
	v_pk_fma_f32 v[84:85], v[48:49], v[100:101], v[84:85] op_sel:[1,0,0] op_sel_hi:[1,1,1]
	v_pk_fma_f32 v[86:87], v[48:49], v[102:103], v[86:87] op_sel:[1,0,0] op_sel_hi:[1,1,1]
	v_pk_fma_f32 v[88:89], v[48:49], v[104:105], v[88:89] op_sel:[1,0,0] op_sel_hi:[1,1,1]
	v_cvt_scalef32_pk_f32_fp4 v[98:99], v207, 1.0
	v_cvt_scalef32_pk_f32_fp4 v[100:101], v207, 1.0 op_sel:[1,0,0]
	v_cvt_scalef32_pk_f32_fp4 v[102:103], v207, 1.0 op_sel:[0,1,0]
	v_cvt_scalef32_pk_f32_fp4 v[104:105], v207, 1.0 op_sel:[1,1,0]
	v_pk_fma_f32 v[90:91], v[48:49], v[98:99], v[90:91] op_sel:[1,0,0] op_sel_hi:[1,1,1]
	v_pk_fma_f32 v[92:93], v[48:49], v[100:101], v[92:93] op_sel:[1,0,0] op_sel_hi:[1,1,1]
	v_pk_fma_f32 v[94:95], v[48:49], v[102:103], v[94:95] op_sel:[1,0,0] op_sel_hi:[1,1,1]
	v_pk_fma_f32 v[96:97], v[48:49], v[104:105], v[96:97] op_sel:[1,0,0] op_sel_hi:[1,1,1]
	v_cvt_scalef32_pk_f32_fp4 v[98:99], v208, 1.0
	v_cvt_scalef32_pk_f32_fp4 v[100:101], v208, 1.0 op_sel:[1,0,0]
	v_cvt_scalef32_pk_f32_fp4 v[102:103], v208, 1.0 op_sel:[0,1,0]
	v_cvt_scalef32_pk_f32_fp4 v[104:105], v208, 1.0 op_sel:[1,1,0]
	v_pk_fma_f32 v[66:67], v[50:51], v[98:99], v[66:67] op_sel_hi:[0,1,1]
	v_pk_fma_f32 v[68:69], v[50:51], v[100:101], v[68:69] op_sel_hi:[0,1,1]
	v_pk_fma_f32 v[70:71], v[50:51], v[102:103], v[70:71] op_sel_hi:[0,1,1]
	v_pk_fma_f32 v[72:73], v[50:51], v[104:105], v[72:73] op_sel_hi:[0,1,1]
	v_cvt_scalef32_pk_f32_fp4 v[98:99], v209, 1.0
	v_cvt_scalef32_pk_f32_fp4 v[100:101], v209, 1.0 op_sel:[1,0,0]
	v_cvt_scalef32_pk_f32_fp4 v[102:103], v209, 1.0 op_sel:[0,1,0]
	v_cvt_scalef32_pk_f32_fp4 v[104:105], v209, 1.0 op_sel:[1,1,0]
	v_pk_fma_f32 v[74:75], v[50:51], v[98:99], v[74:75] op_sel_hi:[0,1,1]
	v_pk_fma_f32 v[76:77], v[50:51], v[100:101], v[76:77] op_sel_hi:[0,1,1]
	v_pk_fma_f32 v[78:79], v[50:51], v[102:103], v[78:79] op_sel_hi:[0,1,1]
	v_pk_fma_f32 v[80:81], v[50:51], v[104:105], v[80:81] op_sel_hi:[0,1,1]
	v_cvt_scalef32_pk_f32_fp4 v[98:99], v210, 1.0
	v_cvt_scalef32_pk_f32_fp4 v[100:101], v210, 1.0 op_sel:[1,0,0]
	v_cvt_scalef32_pk_f32_fp4 v[102:103], v210, 1.0 op_sel:[0,1,0]
	v_cvt_scalef32_pk_f32_fp4 v[104:105], v210, 1.0 op_sel:[1,1,0]
	v_pk_fma_f32 v[82:83], v[50:51], v[98:99], v[82:83] op_sel_hi:[0,1,1]
	v_pk_fma_f32 v[84:85], v[50:51], v[100:101], v[84:85] op_sel_hi:[0,1,1]
	v_pk_fma_f32 v[86:87], v[50:51], v[102:103], v[86:87] op_sel_hi:[0,1,1]
	v_pk_fma_f32 v[88:89], v[50:51], v[104:105], v[88:89] op_sel_hi:[0,1,1]
	v_cvt_scalef32_pk_f32_fp4 v[98:99], v211, 1.0
	v_cvt_scalef32_pk_f32_fp4 v[100:101], v211, 1.0 op_sel:[1,0,0]
	v_cvt_scalef32_pk_f32_fp4 v[102:103], v211, 1.0 op_sel:[0,1,0]
	v_cvt_scalef32_pk_f32_fp4 v[104:105], v211, 1.0 op_sel:[1,1,0]
	v_pk_fma_f32 v[90:91], v[50:51], v[98:99], v[90:91] op_sel_hi:[0,1,1]
	v_pk_fma_f32 v[92:93], v[50:51], v[100:101], v[92:93] op_sel_hi:[0,1,1]
	v_pk_fma_f32 v[94:95], v[50:51], v[102:103], v[94:95] op_sel_hi:[0,1,1]
	v_pk_fma_f32 v[96:97], v[50:51], v[104:105], v[96:97] op_sel_hi:[0,1,1]
	v_cvt_scalef32_pk_f32_fp4 v[98:99], v212, 1.0
	v_cvt_scalef32_pk_f32_fp4 v[100:101], v212, 1.0 op_sel:[1,0,0]
	v_cvt_scalef32_pk_f32_fp4 v[102:103], v212, 1.0 op_sel:[0,1,0]
	v_cvt_scalef32_pk_f32_fp4 v[104:105], v212, 1.0 op_sel:[1,1,0]
	v_pk_fma_f32 v[66:67], v[50:51], v[98:99], v[66:67] op_sel:[1,0,0] op_sel_hi:[1,1,1]
	v_pk_fma_f32 v[68:69], v[50:51], v[100:101], v[68:69] op_sel:[1,0,0] op_sel_hi:[1,1,1]
	v_pk_fma_f32 v[70:71], v[50:51], v[102:103], v[70:71] op_sel:[1,0,0] op_sel_hi:[1,1,1]
	v_pk_fma_f32 v[72:73], v[50:51], v[104:105], v[72:73] op_sel:[1,0,0] op_sel_hi:[1,1,1]
	v_cvt_scalef32_pk_f32_fp4 v[98:99], v213, 1.0
	v_cvt_scalef32_pk_f32_fp4 v[100:101], v213, 1.0 op_sel:[1,0,0]
	v_cvt_scalef32_pk_f32_fp4 v[102:103], v213, 1.0 op_sel:[0,1,0]
	v_cvt_scalef32_pk_f32_fp4 v[104:105], v213, 1.0 op_sel:[1,1,0]
	v_pk_fma_f32 v[74:75], v[50:51], v[98:99], v[74:75] op_sel:[1,0,0] op_sel_hi:[1,1,1]
	v_pk_fma_f32 v[76:77], v[50:51], v[100:101], v[76:77] op_sel:[1,0,0] op_sel_hi:[1,1,1]
	v_pk_fma_f32 v[78:79], v[50:51], v[102:103], v[78:79] op_sel:[1,0,0] op_sel_hi:[1,1,1]
	v_pk_fma_f32 v[80:81], v[50:51], v[104:105], v[80:81] op_sel:[1,0,0] op_sel_hi:[1,1,1]
	v_cvt_scalef32_pk_f32_fp4 v[98:99], v214, 1.0
	v_cvt_scalef32_pk_f32_fp4 v[100:101], v214, 1.0 op_sel:[1,0,0]
	v_cvt_scalef32_pk_f32_fp4 v[102:103], v214, 1.0 op_sel:[0,1,0]
	v_cvt_scalef32_pk_f32_fp4 v[104:105], v214, 1.0 op_sel:[1,1,0]
	v_pk_fma_f32 v[82:83], v[50:51], v[98:99], v[82:83] op_sel:[1,0,0] op_sel_hi:[1,1,1]
	v_pk_fma_f32 v[84:85], v[50:51], v[100:101], v[84:85] op_sel:[1,0,0] op_sel_hi:[1,1,1]
	v_pk_fma_f32 v[86:87], v[50:51], v[102:103], v[86:87] op_sel:[1,0,0] op_sel_hi:[1,1,1]
	v_pk_fma_f32 v[88:89], v[50:51], v[104:105], v[88:89] op_sel:[1,0,0] op_sel_hi:[1,1,1]
	v_cvt_scalef32_pk_f32_fp4 v[98:99], v215, 1.0
	v_cvt_scalef32_pk_f32_fp4 v[100:101], v215, 1.0 op_sel:[1,0,0]
	v_cvt_scalef32_pk_f32_fp4 v[102:103], v215, 1.0 op_sel:[0,1,0]
	v_cvt_scalef32_pk_f32_fp4 v[104:105], v215, 1.0 op_sel:[1,1,0]
	v_pk_fma_f32 v[90:91], v[50:51], v[98:99], v[90:91] op_sel:[1,0,0] op_sel_hi:[1,1,1]
	v_pk_fma_f32 v[92:93], v[50:51], v[100:101], v[92:93] op_sel:[1,0,0] op_sel_hi:[1,1,1]
	v_pk_fma_f32 v[94:95], v[50:51], v[102:103], v[94:95] op_sel:[1,0,0] op_sel_hi:[1,1,1]
	v_pk_fma_f32 v[96:97], v[50:51], v[104:105], v[96:97] op_sel:[1,0,0] op_sel_hi:[1,1,1]
	v_cvt_scalef32_pk_f32_fp4 v[98:99], v216, 1.0
	v_cvt_scalef32_pk_f32_fp4 v[100:101], v216, 1.0 op_sel:[1,0,0]
	v_cvt_scalef32_pk_f32_fp4 v[102:103], v216, 1.0 op_sel:[0,1,0]
	v_cvt_scalef32_pk_f32_fp4 v[104:105], v216, 1.0 op_sel:[1,1,0]
	v_pk_fma_f32 v[66:67], v[52:53], v[98:99], v[66:67] op_sel_hi:[0,1,1]
; __device__ __forceinline__ void phase_peer_v(const Params& p, int layer, int xs, int wid0, int wstride, bool last, char* smraw) {
;     ...
;   auto half_fma = [&](const u32x4 (&q)[8], const f32x4& c0, const f32x4& c1) {
; #pragma unroll
;     for (int i = 0; i < 8; ++i) {
;       const float ci = i < 4 ? c0[i & 3] : c1[i & 3];
; #pragma unroll
;       for (int m = 0; m < 4; ++m) {
;         unsigned dw = q[i][m];
;         asm volatile("" : "+v"(dw) : "v"(acc[(8 * m + 31) & 31]));
;         const f32x2 e0 = __builtin_amdgcn_cvt_scalef32_pk_f32_fp4(dw, 1.0f, 0), e1 = __builtin_amdgcn_cvt_scalef32_pk_f32_fp4(dw, 1.0f, 1);
;         const f32x2 e2 = __builtin_amdgcn_cvt_scalef32_pk_f32_fp4(dw, 1.0f, 2), e3 = __builtin_amdgcn_cvt_scalef32_pk_f32_fp4(dw, 1.0f, 3);
;         acc[8 * m + 0] += ci * e0[0]; acc[8 * m + 1] += ci * e0[1]; acc[8 * m + 2] += ci * e1[0]; acc[8 * m + 3] += ci * e1[1];
;         acc[8 * m + 4] += ci * e2[0]; acc[8 * m + 5] += ci * e2[1]; acc[8 * m + 6] += ci * e3[0]; acc[8 * m + 7] += ci * e3[1];
;       }
;     }
	v_pk_fma_f32 v[68:69], v[52:53], v[100:101], v[68:69] op_sel_hi:[0,1,1]
	v_pk_fma_f32 v[70:71], v[52:53], v[102:103], v[70:71] op_sel_hi:[0,1,1]
	v_pk_fma_f32 v[72:73], v[52:53], v[104:105], v[72:73] op_sel_hi:[0,1,1]
	v_cvt_scalef32_pk_f32_fp4 v[98:99], v217, 1.0
	v_cvt_scalef32_pk_f32_fp4 v[100:101], v217, 1.0 op_sel:[1,0,0]
	v_cvt_scalef32_pk_f32_fp4 v[102:103], v217, 1.0 op_sel:[0,1,0]
	v_cvt_scalef32_pk_f32_fp4 v[104:105], v217, 1.0 op_sel:[1,1,0]
	v_pk_fma_f32 v[74:75], v[52:53], v[98:99], v[74:75] op_sel_hi:[0,1,1]
	v_pk_fma_f32 v[76:77], v[52:53], v[100:101], v[76:77] op_sel_hi:[0,1,1]
	v_pk_fma_f32 v[78:79], v[52:53], v[102:103], v[78:79] op_sel_hi:[0,1,1]
	v_pk_fma_f32 v[80:81], v[52:53], v[104:105], v[80:81] op_sel_hi:[0,1,1]
	v_cvt_scalef32_pk_f32_fp4 v[98:99], v218, 1.0
	v_cvt_scalef32_pk_f32_fp4 v[100:101], v218, 1.0 op_sel:[1,0,0]
	v_cvt_scalef32_pk_f32_fp4 v[102:103], v218, 1.0 op_sel:[0,1,0]
	v_cvt_scalef32_pk_f32_fp4 v[104:105], v218, 1.0 op_sel:[1,1,0]
	v_pk_fma_f32 v[82:83], v[52:53], v[98:99], v[82:83] op_sel_hi:[0,1,1]
	v_pk_fma_f32 v[84:85], v[52:53], v[100:101], v[84:85] op_sel_hi:[0,1,1]
	v_pk_fma_f32 v[86:87], v[52:53], v[102:103], v[86:87] op_sel_hi:[0,1,1]
	v_pk_fma_f32 v[88:89], v[52:53], v[104:105], v[88:89] op_sel_hi:[0,1,1]
	v_cvt_scalef32_pk_f32_fp4 v[98:99], v219, 1.0
	v_cvt_scalef32_pk_f32_fp4 v[100:101], v219, 1.0 op_sel:[1,0,0]
	v_cvt_scalef32_pk_f32_fp4 v[102:103], v219, 1.0 op_sel:[0,1,0]
	v_cvt_scalef32_pk_f32_fp4 v[104:105], v219, 1.0 op_sel:[1,1,0]
	v_pk_fma_f32 v[90:91], v[52:53], v[98:99], v[90:91] op_sel_hi:[0,1,1]
	v_pk_fma_f32 v[92:93], v[52:53], v[100:101], v[92:93] op_sel_hi:[0,1,1]
	v_pk_fma_f32 v[94:95], v[52:53], v[102:103], v[94:95] op_sel_hi:[0,1,1]
	v_pk_fma_f32 v[96:97], v[52:53], v[104:105], v[96:97] op_sel_hi:[0,1,1]
	v_cvt_scalef32_pk_f32_fp4 v[98:99], v220, 1.0
	v_cvt_scalef32_pk_f32_fp4 v[100:101], v220, 1.0 op_sel:[1,0,0]
	v_cvt_scalef32_pk_f32_fp4 v[102:103], v220, 1.0 op_sel:[0,1,0]
	v_cvt_scalef32_pk_f32_fp4 v[104:105], v220, 1.0 op_sel:[1,1,0]
	v_pk_fma_f32 v[66:67], v[52:53], v[98:99], v[66:67] op_sel:[1,0,0] op_sel_hi:[1,1,1]
	v_pk_fma_f32 v[68:69], v[52:53], v[100:101], v[68:69] op_sel:[1,0,0] op_sel_hi:[1,1,1]
	v_pk_fma_f32 v[70:71], v[52:53], v[102:103], v[70:71] op_sel:[1,0,0] op_sel_hi:[1,1,1]
	v_pk_fma_f32 v[72:73], v[52:53], v[104:105], v[72:73] op_sel:[1,0,0] op_sel_hi:[1,1,1]
	v_cvt_scalef32_pk_f32_fp4 v[98:99], v221, 1.0
	v_cvt_scalef32_pk_f32_fp4 v[100:101], v221, 1.0 op_sel:[1,0,0]
	v_cvt_scalef32_pk_f32_fp4 v[102:103], v221, 1.0 op_sel:[0,1,0]
	v_cvt_scalef32_pk_f32_fp4 v[104:105], v221, 1.0 op_sel:[1,1,0]
	v_pk_fma_f32 v[74:75], v[52:53], v[98:99], v[74:75] op_sel:[1,0,0] op_sel_hi:[1,1,1]
	v_pk_fma_f32 v[76:77], v[52:53], v[100:101], v[76:77] op_sel:[1,0,0] op_sel_hi:[1,1,1]
	v_pk_fma_f32 v[78:79], v[52:53], v[102:103], v[78:79] op_sel:[1,0,0] op_sel_hi:[1,1,1]
	v_pk_fma_f32 v[80:81], v[52:53], v[104:105], v[80:81] op_sel:[1,0,0] op_sel_hi:[1,1,1]
	v_cvt_scalef32_pk_f32_fp4 v[98:99], v222, 1.0
	v_cvt_scalef32_pk_f32_fp4 v[100:101], v222, 1.0 op_sel:[1,0,0]
	v_cvt_scalef32_pk_f32_fp4 v[102:103], v222, 1.0 op_sel:[0,1,0]
	v_cvt_scalef32_pk_f32_fp4 v[104:105], v222, 1.0 op_sel:[1,1,0]
	v_pk_fma_f32 v[82:83], v[52:53], v[98:99], v[82:83] op_sel:[1,0,0] op_sel_hi:[1,1,1]
	v_pk_fma_f32 v[84:85], v[52:53], v[100:101], v[84:85] op_sel:[1,0,0] op_sel_hi:[1,1,1]
	v_pk_fma_f32 v[86:87], v[52:53], v[102:103], v[86:87] op_sel:[1,0,0] op_sel_hi:[1,1,1]
	v_pk_fma_f32 v[88:89], v[52:53], v[104:105], v[88:89] op_sel:[1,0,0] op_sel_hi:[1,1,1]
	v_cvt_scalef32_pk_f32_fp4 v[98:99], v223, 1.0
	v_cvt_scalef32_pk_f32_fp4 v[100:101], v223, 1.0 op_sel:[1,0,0]
	v_cvt_scalef32_pk_f32_fp4 v[102:103], v223, 1.0 op_sel:[0,1,0]
	v_cvt_scalef32_pk_f32_fp4 v[104:105], v223, 1.0 op_sel:[1,1,0]
	v_pk_fma_f32 v[90:91], v[52:53], v[98:99], v[90:91] op_sel:[1,0,0] op_sel_hi:[1,1,1]
	v_pk_fma_f32 v[92:93], v[52:53], v[100:101], v[92:93] op_sel:[1,0,0] op_sel_hi:[1,1,1]
	v_pk_fma_f32 v[94:95], v[52:53], v[102:103], v[94:95] op_sel:[1,0,0] op_sel_hi:[1,1,1]
	v_pk_fma_f32 v[96:97], v[52:53], v[104:105], v[96:97] op_sel:[1,0,0] op_sel_hi:[1,1,1]
	v_cvt_scalef32_pk_f32_fp4 v[98:99], v224, 1.0
	v_cvt_scalef32_pk_f32_fp4 v[100:101], v224, 1.0 op_sel:[1,0,0]
	v_cvt_scalef32_pk_f32_fp4 v[102:103], v224, 1.0 op_sel:[0,1,0]
	v_cvt_scalef32_pk_f32_fp4 v[104:105], v224, 1.0 op_sel:[1,1,0]
	v_pk_fma_f32 v[66:67], v[54:55], v[98:99], v[66:67] op_sel_hi:[0,1,1]
	v_pk_fma_f32 v[68:69], v[54:55], v[100:101], v[68:69] op_sel_hi:[0,1,1]
	v_pk_fma_f32 v[70:71], v[54:55], v[102:103], v[70:71] op_sel_hi:[0,1,1]
	v_pk_fma_f32 v[72:73], v[54:55], v[104:105], v[72:73] op_sel_hi:[0,1,1]
	v_cvt_scalef32_pk_f32_fp4 v[98:99], v225, 1.0
	v_cvt_scalef32_pk_f32_fp4 v[100:101], v225, 1.0 op_sel:[1,0,0]
	v_cvt_scalef32_pk_f32_fp4 v[102:103], v225, 1.0 op_sel:[0,1,0]
	v_cvt_scalef32_pk_f32_fp4 v[104:105], v225, 1.0 op_sel:[1,1,0]
	v_pk_fma_f32 v[74:75], v[54:55], v[98:99], v[74:75] op_sel_hi:[0,1,1]
	v_pk_fma_f32 v[76:77], v[54:55], v[100:101], v[76:77] op_sel_hi:[0,1,1]
	v_pk_fma_f32 v[78:79], v[54:55], v[102:103], v[78:79] op_sel_hi:[0,1,1]
	v_pk_fma_f32 v[80:81], v[54:55], v[104:105], v[80:81] op_sel_hi:[0,1,1]
	v_cvt_scalef32_pk_f32_fp4 v[98:99], v226, 1.0
	v_cvt_scalef32_pk_f32_fp4 v[100:101], v226, 1.0 op_sel:[1,0,0]
	v_cvt_scalef32_pk_f32_fp4 v[102:103], v226, 1.0 op_sel:[0,1,0]
	v_cvt_scalef32_pk_f32_fp4 v[104:105], v226, 1.0 op_sel:[1,1,0]
	v_pk_fma_f32 v[82:83], v[54:55], v[98:99], v[82:83] op_sel_hi:[0,1,1]
	v_pk_fma_f32 v[84:85], v[54:55], v[100:101], v[84:85] op_sel_hi:[0,1,1]
	v_pk_fma_f32 v[86:87], v[54:55], v[102:103], v[86:87] op_sel_hi:[0,1,1]
; __device__ __forceinline__ void phase_peer_v(const Params& p, int layer, int xs, int wid0, int wstride, bool last, char* smraw) {
;     ...
;   auto half_fma = [&](const u32x4 (&q)[8], const f32x4& c0, const f32x4& c1) {
; #pragma unroll
;     for (int i = 0; i < 8; ++i) {
;       const float ci = i < 4 ? c0[i & 3] : c1[i & 3];
; #pragma unroll
;       for (int m = 0; m < 4; ++m) {
;         unsigned dw = q[i][m];
;         asm volatile("" : "+v"(dw) : "v"(acc[(8 * m + 31) & 31]));
;         const f32x2 e0 = __builtin_amdgcn_cvt_scalef32_pk_f32_fp4(dw, 1.0f, 0), e1 = __builtin_amdgcn_cvt_scalef32_pk_f32_fp4(dw, 1.0f, 1);
;         const f32x2 e2 = __builtin_amdgcn_cvt_scalef32_pk_f32_fp4(dw, 1.0f, 2), e3 = __builtin_amdgcn_cvt_scalef32_pk_f32_fp4(dw, 1.0f, 3);
;         acc[8 * m + 0] += ci * e0[0]; acc[8 * m + 1] += ci * e0[1]; acc[8 * m + 2] += ci * e1[0]; acc[8 * m + 3] += ci * e1[1];
;         acc[8 * m + 4] += ci * e2[0]; acc[8 * m + 5] += ci * e2[1]; acc[8 * m + 6] += ci * e3[0]; acc[8 * m + 7] += ci * e3[1];
;       }
;     }
	v_pk_fma_f32 v[88:89], v[54:55], v[104:105], v[88:89] op_sel_hi:[0,1,1]
	v_cvt_scalef32_pk_f32_fp4 v[98:99], v227, 1.0
	v_cvt_scalef32_pk_f32_fp4 v[100:101], v227, 1.0 op_sel:[1,0,0]
	v_cvt_scalef32_pk_f32_fp4 v[102:103], v227, 1.0 op_sel:[0,1,0]
	v_cvt_scalef32_pk_f32_fp4 v[104:105], v227, 1.0 op_sel:[1,1,0]
	v_pk_fma_f32 v[90:91], v[54:55], v[98:99], v[90:91] op_sel_hi:[0,1,1]
	v_pk_fma_f32 v[92:93], v[54:55], v[100:101], v[92:93] op_sel_hi:[0,1,1]
	v_pk_fma_f32 v[94:95], v[54:55], v[102:103], v[94:95] op_sel_hi:[0,1,1]
	v_pk_fma_f32 v[96:97], v[54:55], v[104:105], v[96:97] op_sel_hi:[0,1,1]
	v_cvt_scalef32_pk_f32_fp4 v[98:99], v228, 1.0
	v_cvt_scalef32_pk_f32_fp4 v[100:101], v228, 1.0 op_sel:[1,0,0]
	v_cvt_scalef32_pk_f32_fp4 v[102:103], v228, 1.0 op_sel:[0,1,0]
	v_cvt_scalef32_pk_f32_fp4 v[104:105], v228, 1.0 op_sel:[1,1,0]
	v_pk_fma_f32 v[66:67], v[54:55], v[98:99], v[66:67] op_sel:[1,0,0] op_sel_hi:[1,1,1]
	v_pk_fma_f32 v[68:69], v[54:55], v[100:101], v[68:69] op_sel:[1,0,0] op_sel_hi:[1,1,1]
	v_pk_fma_f32 v[70:71], v[54:55], v[102:103], v[70:71] op_sel:[1,0,0] op_sel_hi:[1,1,1]
	v_pk_fma_f32 v[72:73], v[54:55], v[104:105], v[72:73] op_sel:[1,0,0] op_sel_hi:[1,1,1]
	v_cvt_scalef32_pk_f32_fp4 v[98:99], v229, 1.0
	v_cvt_scalef32_pk_f32_fp4 v[100:101], v229, 1.0 op_sel:[1,0,0]
	v_cvt_scalef32_pk_f32_fp4 v[102:103], v229, 1.0 op_sel:[0,1,0]
	v_cvt_scalef32_pk_f32_fp4 v[104:105], v229, 1.0 op_sel:[1,1,0]
	v_pk_fma_f32 v[74:75], v[54:55], v[98:99], v[74:75] op_sel:[1,0,0] op_sel_hi:[1,1,1]
	v_pk_fma_f32 v[76:77], v[54:55], v[100:101], v[76:77] op_sel:[1,0,0] op_sel_hi:[1,1,1]
	v_pk_fma_f32 v[78:79], v[54:55], v[102:103], v[78:79] op_sel:[1,0,0] op_sel_hi:[1,1,1]
	v_pk_fma_f32 v[80:81], v[54:55], v[104:105], v[80:81] op_sel:[1,0,0] op_sel_hi:[1,1,1]
	v_cvt_scalef32_pk_f32_fp4 v[98:99], v230, 1.0
	v_cvt_scalef32_pk_f32_fp4 v[100:101], v230, 1.0 op_sel:[1,0,0]
	v_cvt_scalef32_pk_f32_fp4 v[102:103], v230, 1.0 op_sel:[0,1,0]
	v_cvt_scalef32_pk_f32_fp4 v[104:105], v230, 1.0 op_sel:[1,1,0]
	v_pk_fma_f32 v[82:83], v[54:55], v[98:99], v[82:83] op_sel:[1,0,0] op_sel_hi:[1,1,1]
	v_pk_fma_f32 v[84:85], v[54:55], v[100:101], v[84:85] op_sel:[1,0,0] op_sel_hi:[1,1,1]
	v_pk_fma_f32 v[86:87], v[54:55], v[102:103], v[86:87] op_sel:[1,0,0] op_sel_hi:[1,1,1]
	v_pk_fma_f32 v[88:89], v[54:55], v[104:105], v[88:89] op_sel:[1,0,0] op_sel_hi:[1,1,1]
	v_cvt_scalef32_pk_f32_fp4 v[98:99], v231, 1.0
	v_cvt_scalef32_pk_f32_fp4 v[100:101], v231, 1.0 op_sel:[1,0,0]
	v_cvt_scalef32_pk_f32_fp4 v[102:103], v231, 1.0 op_sel:[0,1,0]
	v_cvt_scalef32_pk_f32_fp4 v[104:105], v231, 1.0 op_sel:[1,1,0]
	v_pk_fma_f32 v[90:91], v[54:55], v[98:99], v[90:91] op_sel:[1,0,0] op_sel_hi:[1,1,1]
	v_pk_fma_f32 v[92:93], v[54:55], v[100:101], v[92:93] op_sel:[1,0,0] op_sel_hi:[1,1,1]
	v_pk_fma_f32 v[94:95], v[54:55], v[102:103], v[94:95] op_sel:[1,0,0] op_sel_hi:[1,1,1]
	v_pk_fma_f32 v[96:97], v[54:55], v[104:105], v[96:97] op_sel:[1,0,0] op_sel_hi:[1,1,1]
	v_cvt_scalef32_pk_f32_fp4 v[98:99], v232, 1.0
	v_cvt_scalef32_pk_f32_fp4 v[100:101], v232, 1.0 op_sel:[1,0,0]
	v_cvt_scalef32_pk_f32_fp4 v[102:103], v232, 1.0 op_sel:[0,1,0]
	v_cvt_scalef32_pk_f32_fp4 v[104:105], v232, 1.0 op_sel:[1,1,0]
	v_pk_fma_f32 v[66:67], v[56:57], v[98:99], v[66:67] op_sel_hi:[0,1,1]
	v_pk_fma_f32 v[68:69], v[56:57], v[100:101], v[68:69] op_sel_hi:[0,1,1]
	v_pk_fma_f32 v[70:71], v[56:57], v[102:103], v[70:71] op_sel_hi:[0,1,1]
	v_pk_fma_f32 v[72:73], v[56:57], v[104:105], v[72:73] op_sel_hi:[0,1,1]
	v_cvt_scalef32_pk_f32_fp4 v[98:99], v233, 1.0
	v_cvt_scalef32_pk_f32_fp4 v[100:101], v233, 1.0 op_sel:[1,0,0]
	v_cvt_scalef32_pk_f32_fp4 v[102:103], v233, 1.0 op_sel:[0,1,0]
	v_cvt_scalef32_pk_f32_fp4 v[104:105], v233, 1.0 op_sel:[1,1,0]
	v_pk_fma_f32 v[74:75], v[56:57], v[98:99], v[74:75] op_sel_hi:[0,1,1]
	v_pk_fma_f32 v[76:77], v[56:57], v[100:101], v[76:77] op_sel_hi:[0,1,1]
	v_pk_fma_f32 v[78:79], v[56:57], v[102:103], v[78:79] op_sel_hi:[0,1,1]
	v_pk_fma_f32 v[80:81], v[56:57], v[104:105], v[80:81] op_sel_hi:[0,1,1]
	v_cvt_scalef32_pk_f32_fp4 v[98:99], v234, 1.0
	v_cvt_scalef32_pk_f32_fp4 v[100:101], v234, 1.0 op_sel:[1,0,0]
	v_cvt_scalef32_pk_f32_fp4 v[102:103], v234, 1.0 op_sel:[0,1,0]
	v_cvt_scalef32_pk_f32_fp4 v[104:105], v234, 1.0 op_sel:[1,1,0]
	v_pk_fma_f32 v[82:83], v[56:57], v[98:99], v[82:83] op_sel_hi:[0,1,1]
	v_pk_fma_f32 v[84:85], v[56:57], v[100:101], v[84:85] op_sel_hi:[0,1,1]
	v_pk_fma_f32 v[86:87], v[56:57], v[102:103], v[86:87] op_sel_hi:[0,1,1]
	v_pk_fma_f32 v[88:89], v[56:57], v[104:105], v[88:89] op_sel_hi:[0,1,1]
	v_cvt_scalef32_pk_f32_fp4 v[98:99], v235, 1.0
; __device__ __forceinline__ void phase_peer_v(const Params& p, int layer, int xs, int wid0, int wstride, bool last, char* smraw) {
;     ...
;         const f32x2 e0 = __builtin_amdgcn_cvt_scalef32_pk_f32_fp4(dw, 1.0f, 0), e1 = __builtin_amdgcn_cvt_scalef32_pk_f32_fp4(dw, 1.0f, 1);
;         const f32x2 e2 = __builtin_amdgcn_cvt_scalef32_pk_f32_fp4(dw, 1.0f, 2), e3 = __builtin_amdgcn_cvt_scalef32_pk_f32_fp4(dw, 1.0f, 3);
;         acc[8 * m + 0] += ci * e0[0]; acc[8 * m + 1] += ci * e0[1]; acc[8 * m + 2] += ci * e1[0]; acc[8 * m + 3] += ci * e1[1];
;         acc[8 * m + 4] += ci * e2[0]; acc[8 * m + 5] += ci * e2[1]; acc[8 * m + 6] += ci * e3[0]; acc[8 * m + 7] += ci * e3[1];
;       }
;     }
;   };
;   int tt = wid;
;   if (tt < TH) load_idx(tt);
;   while (tt < TH) {
;     const int tn = tt + wstride;
;     const int t = 2 * tt + par;
; #pragma unroll
;     for (int i = 0; i < 8; ++i) qA[i] = *(const u32x4*)(Vq + (ni[i >> 2][i & 3] * 128u + joff));
;     float* hq = hrow(p, t) + sl * 256 + 4 * l;
;     f32x4 hv = *(const f32x4*)hq;
;     const f32x4 c0 = nc[0], c1 = nc[1], c2 = nc[2], c3 = nc[3];
; #pragma unroll
;     for (int m = 0; m < 32; ++m) acc[m] = 0.f;
;     half_fma(qA, c0, c1);
; #pragma unroll
;     for (int i = 0; i < 8; ++i) qA[i] = *(const u32x4*)(Vq + (ni[2 + (i >> 2)][i & 3] * 128u + joff));
;     if (tn < TH) load_idx(tn);
;     half_fma(qA, c2, c3);
; #pragma unroll
;     for (int q4 = 0; q4 < 8; ++q4) *(f32x4*)(red + g * 256 + j * 32 + q4 * 4) = f32x4{acc[q4 * 4], acc[q4 * 4 + 1], acc[q4 * 4 + 2], acc[q4 * 4 + 3]};
;     __builtin_amdgcn_fence(__ATOMIC_RELEASE, "wavefront");
;     __builtin_amdgcn_wave_barrier();
;     __builtin_amdgcn_fence(__ATOMIC_ACQUIRE, "wavefront");
;     f32x4 r = {0.f, 0.f, 0.f, 0.f};
; #pragma unroll
;     for (int gg = 0; gg < 8; ++gg) { f32x4 v = *(const f32x4*)(red + gg * 256 + 4 * l); r += v; }
;     asm volatile("" ::: "memory");
;     __builtin_amdgcn_wave_barrier();
;     {
;       hv += r;
;       *(f32x4*)hq = hv;
;       if (!last) { u32x2 o; o[0] = cvtpk(hv[0], hv[1]); o[1] = cvtpk(hv[2], hv[3]); *(u32x2*)((char*)p.hb + ((unsigned)t * 2048u + (unsigned)(sl * 512 + l * 8))) = o; }
	v_cvt_scalef32_pk_f32_fp4 v[100:101], v235, 1.0 op_sel:[1,0,0]
	v_cvt_scalef32_pk_f32_fp4 v[102:103], v235, 1.0 op_sel:[0,1,0]
	v_cvt_scalef32_pk_f32_fp4 v[104:105], v235, 1.0 op_sel:[1,1,0]
	v_pk_fma_f32 v[90:91], v[56:57], v[98:99], v[90:91] op_sel_hi:[0,1,1]
	v_pk_fma_f32 v[92:93], v[56:57], v[100:101], v[92:93] op_sel_hi:[0,1,1]
	v_pk_fma_f32 v[94:95], v[56:57], v[102:103], v[94:95] op_sel_hi:[0,1,1]
	v_pk_fma_f32 v[96:97], v[56:57], v[104:105], v[96:97] op_sel_hi:[0,1,1]
	v_cvt_scalef32_pk_f32_fp4 v[98:99], v236, 1.0
	v_cvt_scalef32_pk_f32_fp4 v[100:101], v236, 1.0 op_sel:[1,0,0]
	v_cvt_scalef32_pk_f32_fp4 v[102:103], v236, 1.0 op_sel:[0,1,0]
	v_cvt_scalef32_pk_f32_fp4 v[104:105], v236, 1.0 op_sel:[1,1,0]
	v_pk_fma_f32 v[66:67], v[56:57], v[98:99], v[66:67] op_sel:[1,0,0] op_sel_hi:[1,1,1]
	v_pk_fma_f32 v[68:69], v[56:57], v[100:101], v[68:69] op_sel:[1,0,0] op_sel_hi:[1,1,1]
	v_pk_fma_f32 v[70:71], v[56:57], v[102:103], v[70:71] op_sel:[1,0,0] op_sel_hi:[1,1,1]
	v_pk_fma_f32 v[72:73], v[56:57], v[104:105], v[72:73] op_sel:[1,0,0] op_sel_hi:[1,1,1]
	v_cvt_scalef32_pk_f32_fp4 v[98:99], v237, 1.0
	v_cvt_scalef32_pk_f32_fp4 v[100:101], v237, 1.0 op_sel:[1,0,0]
	v_cvt_scalef32_pk_f32_fp4 v[102:103], v237, 1.0 op_sel:[0,1,0]
	v_cvt_scalef32_pk_f32_fp4 v[104:105], v237, 1.0 op_sel:[1,1,0]
	v_pk_fma_f32 v[74:75], v[56:57], v[98:99], v[74:75] op_sel:[1,0,0] op_sel_hi:[1,1,1]
	v_pk_fma_f32 v[76:77], v[56:57], v[100:101], v[76:77] op_sel:[1,0,0] op_sel_hi:[1,1,1]
	v_pk_fma_f32 v[78:79], v[56:57], v[102:103], v[78:79] op_sel:[1,0,0] op_sel_hi:[1,1,1]
	v_pk_fma_f32 v[80:81], v[56:57], v[104:105], v[80:81] op_sel:[1,0,0] op_sel_hi:[1,1,1]
	v_cvt_scalef32_pk_f32_fp4 v[98:99], v238, 1.0
	v_cvt_scalef32_pk_f32_fp4 v[100:101], v238, 1.0 op_sel:[1,0,0]
	v_cvt_scalef32_pk_f32_fp4 v[102:103], v238, 1.0 op_sel:[0,1,0]
	v_cvt_scalef32_pk_f32_fp4 v[104:105], v238, 1.0 op_sel:[1,1,0]
	v_pk_fma_f32 v[82:83], v[56:57], v[98:99], v[82:83] op_sel:[1,0,0] op_sel_hi:[1,1,1]
	v_pk_fma_f32 v[84:85], v[56:57], v[100:101], v[84:85] op_sel:[1,0,0] op_sel_hi:[1,1,1]
	v_pk_fma_f32 v[86:87], v[56:57], v[102:103], v[86:87] op_sel:[1,0,0] op_sel_hi:[1,1,1]
	v_pk_fma_f32 v[88:89], v[56:57], v[104:105], v[88:89] op_sel:[1,0,0] op_sel_hi:[1,1,1]
	v_cvt_scalef32_pk_f32_fp4 v[98:99], v239, 1.0
	v_cvt_scalef32_pk_f32_fp4 v[100:101], v239, 1.0 op_sel:[1,0,0]
	v_cvt_scalef32_pk_f32_fp4 v[102:103], v239, 1.0 op_sel:[0,1,0]
	v_cvt_scalef32_pk_f32_fp4 v[104:105], v239, 1.0 op_sel:[1,1,0]
	v_pk_fma_f32 v[90:91], v[56:57], v[98:99], v[90:91] op_sel:[1,0,0] op_sel_hi:[1,1,1]
	v_pk_fma_f32 v[92:93], v[56:57], v[100:101], v[92:93] op_sel:[1,0,0] op_sel_hi:[1,1,1]
	v_pk_fma_f32 v[94:95], v[56:57], v[102:103], v[94:95] op_sel:[1,0,0] op_sel_hi:[1,1,1]
	v_pk_fma_f32 v[96:97], v[56:57], v[104:105], v[96:97] op_sel:[1,0,0] op_sel_hi:[1,1,1]
	ds_write_b128 v240, v[66:69]
	ds_write_b128 v241, v[70:73]
	ds_write_b128 v242, v[74:77]
	ds_write_b128 v243, v[78:81]
	ds_write_b128 v244, v[82:85]
	ds_write_b128 v245, v[86:89]
	ds_write_b128 v246, v[90:93]
	ds_write_b128 v247, v[94:97]
	s_waitcnt lgkmcnt(0)
	ds_read_b128 v[66:69], v4
	ds_read_b128 v[70:73], v4 offset:1024
	ds_read_b128 v[74:77], v4 offset:2048
	ds_read_b128 v[78:81], v4 offset:3072
	ds_read_b128 v[82:85], v4 offset:4096
	ds_read_b128 v[86:89], v4 offset:5120
	ds_read_b128 v[90:93], v4 offset:6144
	ds_read_b128 v[94:97], v4 offset:7168
	s_waitcnt lgkmcnt(6)
	v_pk_add_f32 v[66:67], v[66:67], v[70:71]
	v_pk_add_f32 v[68:69], v[68:69], v[72:73]
	s_waitcnt lgkmcnt(5)
	v_pk_add_f32 v[66:67], v[66:67], v[74:75]
	v_pk_add_f32 v[68:69], v[68:69], v[76:77]
	s_waitcnt lgkmcnt(4)
	v_pk_add_f32 v[66:67], v[66:67], v[78:79]
	v_pk_add_f32 v[68:69], v[68:69], v[80:81]
	s_waitcnt lgkmcnt(3)
	v_pk_add_f32 v[66:67], v[66:67], v[82:83]
	v_pk_add_f32 v[68:69], v[68:69], v[84:85]
	s_waitcnt lgkmcnt(2)
	v_pk_add_f32 v[66:67], v[66:67], v[86:87]
	v_pk_add_f32 v[68:69], v[68:69], v[88:89]
	s_waitcnt lgkmcnt(1)
	v_pk_add_f32 v[66:67], v[66:67], v[90:91]
	v_pk_add_f32 v[68:69], v[68:69], v[92:93]
	s_waitcnt lgkmcnt(0)
	v_pk_add_f32 v[66:67], v[66:67], v[94:95]
	v_pk_add_f32 v[68:69], v[68:69], v[96:97]
	v_pk_add_f32 v[62:63], v[62:63], v[66:67]
	v_pk_add_f32 v[64:65], v[64:65], v[68:69]
	global_store_dwordx4 v0, v[62:65], s[46:47]
	v_cvt_pk_bf16_f32 v98, v62, v63
	v_cvt_pk_bf16_f32 v99, v64, v65
	s_lshl_b32 s0, s36, 1
	s_add_u32 s0, s0, s28
	s_lshl_b32 s0, s0, 11
	s_lshl_b32 s1, s14, 9
	s_add_u32 s0, s0, s1
	v_add_u32_e32 v6, s0, v5
	global_store_dwordx2 v6, v[98:99], s[76:77]
	s_mov_b32 s36, s51
	s_cmp_lt_u32 s36, s38
	s_cbranch_scc1 .Lmy_pv0_bodyA

; __device__ __forceinline__ int tid_opaque() { int t = threadIdx.x; asm volatile("" : "+v"(t)); return t; }
; __device__ __forceinline__ void phase_peer_v(const Params& p, int layer, int xs, int wid0, int wstride, bool last, char* smraw) {
;   const int tid = tid_opaque(), w = tid >> 6, l = tid & 63, g = l >> 3, j = l & 7;
;   const int wid = wid0 + w;
;   const int sl = xs >> 1, par = xs & 1;
;   constexpr int TH = T / 2;
;   float* red = (float*)smraw + w * 2048;
;   const unsigned char* Vq = p.Vq + (size_t)(layer * 4 + sl) * NEXP * 128;
;   const unsigned joff = j * 16;
;   u32x4 ni[4]; f32x4 nc[4];
;   auto load_idx = [&](int tt) {
;     const unsigned o = (unsigned)(2 * tt + par) * 512u + (unsigned)g * 64u;
;     const u32x4* ip = (const u32x4*)((const char*)p.sel_idx + o);
;     const f32x4* cp = (const f32x4*)((const char*)p.coef + o);
; #pragma unroll
;     for (int q4 = 0; q4 < 4; ++q4) { ni[q4] = ip[q4]; nc[q4] = cp[q4]; }
;   };
;   u32x4 qA[8];
;   float acc[32];
;   auto half_fma = [&](const u32x4 (&q)[8], const f32x4& c0, const f32x4& c1) {
; #pragma unroll
;     for (int i = 0; i < 8; ++i) {
;       const float ci = i < 4 ? c0[i & 3] : c1[i & 3];
; #pragma unroll
;       for (int m = 0; m < 4; ++m) {
;         unsigned dw = q[i][m];
;         asm volatile("" : "+v"(dw) : "v"(acc[(8 * m + 31) & 31]));
;         const f32x2 e0 = __builtin_amdgcn_cvt_scalef32_pk_f32_fp4(dw, 1.0f, 0), e1 = __builtin_amdgcn_cvt_scalef32_pk_f32_fp4(dw, 1.0f, 1);
;         const f32x2 e2 = __builtin_amdgcn_cvt_scalef32_pk_f32_fp4(dw, 1.0f, 2), e3 = __builtin_amdgcn_cvt_scalef32_pk_f32_fp4(dw, 1.0f, 3);
;         acc[8 * m + 0] += ci * e0[0]; acc[8 * m + 1] += ci * e0[1]; acc[8 * m + 2] += ci * e1[0]; acc[8 * m + 3] += ci * e1[1];
;         acc[8 * m + 4] += ci * e2[0]; acc[8 * m + 5] += ci * e2[1]; acc[8 * m + 6] += ci * e3[0]; acc[8 * m + 7] += ci * e3[1];
;       }
;     }
;   };
;   int tt = wid;
;   if (tt < TH) load_idx(tt);
;   while (tt < TH) {
;     const int tn = tt + wstride;
;     const int t = 2 * tt + par;
; #pragma unroll
;     for (int i = 0; i < 8; ++i) qA[i] = *(const u32x4*)(Vq + (ni[i >> 2][i & 3] * 128u + joff));
;     float* hq = hrow(p, t) + sl * 256 + 4 * l;
;     f32x4 hv = *(const f32x4*)hq;
;     const f32x4 c0 = nc[0], c1 = nc[1], c2 = nc[2], c3 = nc[3];
.LBB0_1377:
	s_or_b64 exec, exec, s[0:1]
	s_barrier
	v_and_b32_e32 v6, 63, v189
	v_lshrrev_b32_e32 v7, 6, v189
	v_lshlrev_b32_e32 v0, 4, v6
	v_and_b32_e32 v1, 7, v6
	v_lshlrev_b32_e32 v1, 4, v1
	v_lshrrev_b32_e32 v8, 3, v6
	v_readfirstlane_b32 s0, v7
	s_lshl_b32 s1, s28, 9
	v_lshl_add_u32 v2, v8, 6, s1
	v_lshlrev_b32_e32 v3, 13, v7
	v_xor_b32_e32 v4, v6, v8
	v_lshl_add_u32 v4, v4, 4, v3
	v_lshl_add_u32 v3, v8, 10, v3
	v_lshl_add_u32 v3, v1, 3, v3
	v_xor_b32_e32 v240, 0, v1
	v_xor_b32_e32 v241, 16, v1
	v_xor_b32_e32 v242, 32, v1
	v_xor_b32_e32 v243, 48, v1
	v_xor_b32_e32 v244, 64, v1
	v_xor_b32_e32 v245, 80, v1
	v_xor_b32_e32 v246, 96, v1
	v_xor_b32_e32 v247, 112, v1
	v_add_u32_e32 v240, v240, v3
	v_add_u32_e32 v241, v241, v3
	v_add_u32_e32 v242, v242, v3
	v_add_u32_e32 v243, v243, v3
	v_add_u32_e32 v244, v244, v3
	v_add_u32_e32 v245, v245, v3
	v_add_u32_e32 v246, v246, v3
	v_add_u32_e32 v247, v247, v3
	v_lshlrev_b32_e32 v5, 3, v6
	s_add_u32 s36, s92, s0
	s_movk_i32 s38, 0x4020
	s_cmp_ge_u32 s36, s38
	s_cbranch_scc1 .Lmy_pv1_done
	s_lshl_b32 s0, s14, 21
	s_add_u32 s0, s0, 0x800000
	s_add_u32 s40, s90, s0
	s_addc_u32 s41, s91, 0
	v_readlane_b32 s42, v254, 6
	v_readlane_b32 s43, v254, 7
	v_readlane_b32 s10, v254, 30
	v_readlane_b32 s11, v254, 31
	v_readlane_b32 s12, v254, 32
	v_readlane_b32 s13, v254, 33
	s_lshl_b32 s39, s14, 10
	s_mov_b32 s49, 0x7fc02
	s_sub_u32 s10, s10, 0x10000
	s_subb_u32 s11, s11, 0
	s_lshl_b32 s0, s36, 10
	v_add_u32_e32 v9, s0, v2
	global_load_dwordx4 v[10:13], v9, s[52:53]
	global_load_dwordx4 v[14:17], v9, s[52:53] offset:16
	global_load_dwordx4 v[18:21], v9, s[52:53] offset:32
	global_load_dwordx4 v[22:25], v9, s[52:53] offset:48
	s_waitcnt vmcnt(0)
	v_lshl_add_u32 v6, v10, 7, v1
	global_load_dwordx4 v[106:109], v6, s[40:41]
	v_lshl_add_u32 v7, v11, 7, v1
	global_load_dwordx4 v[110:113], v7, s[40:41]
	v_lshl_add_u32 v6, v12, 7, v1
	global_load_dwordx4 v[114:117], v6, s[40:41]
	v_lshl_add_u32 v7, v13, 7, v1
	global_load_dwordx4 v[118:121], v7, s[40:41]
	v_lshl_add_u32 v6, v14, 7, v1
	global_load_dwordx4 v[122:125], v6, s[40:41]
	v_lshl_add_u32 v7, v15, 7, v1
	global_load_dwordx4 v[126:129], v7, s[40:41]
	v_lshl_add_u32 v6, v16, 7, v1
	global_load_dwordx4 v[130:133], v6, s[40:41]
	v_lshl_add_u32 v7, v17, 7, v1
	global_load_dwordx4 v[134:137], v7, s[40:41]
	v_lshl_add_u32 v6, v18, 7, v1
	global_load_dwordx4 v[138:141], v6, s[40:41]
	v_lshl_add_u32 v7, v19, 7, v1
	global_load_dwordx4 v[142:145], v7, s[40:41]
	v_lshl_add_u32 v6, v20, 7, v1
	global_load_dwordx4 v[146:149], v6, s[40:41]
	v_lshl_add_u32 v7, v21, 7, v1
	global_load_dwordx4 v[150:153], v7, s[40:41]
	v_lshl_add_u32 v6, v22, 7, v1
	global_load_dwordx4 v[154:157], v6, s[40:41]
	v_lshl_add_u32 v7, v23, 7, v1
	global_load_dwordx4 v[158:161], v7, s[40:41]
	v_lshl_add_u32 v6, v24, 7, v1
	global_load_dwordx4 v[162:165], v6, s[40:41]
	v_lshl_add_u32 v7, v25, 7, v1
	global_load_dwordx4 v[166:169], v7, s[40:41]
	s_lshl_b32 s0, s36, 1
	s_add_u32 s0, s0, s28
	s_mul_hi_u32 s1, s0, s49
	s_mul_i32 s3, s1, 0x2010
	s_sub_u32 s3, s0, s3
	s_lshl_b32 s6, s1, 13
	s_add_u32 s6, s6, s3
	s_lshl_b32 s7, s1, 4
	s_add_u32 s7, s7, s3
	s_cmp_lt_u32 s3, 16
	s_cselect_b32 s6, s7, s6
	s_cselect_b32 s7, s12, s10
	s_cselect_b32 s8, s13, s11
	s_lshl_b32 s6, s6, 12
	s_add_u32 s6, s6, s39
	s_add_u32 s44, s7, s6
	s_addc_u32 s45, s8, 0
	global_load_dwordx4 v[58:61], v0, s[44:45]
	s_lshl_b32 s0, s36, 10
	v_add_u32_e32 v8, s0, v2
	global_load_dwordx4 v[26:29], v8, s[42:43]
	global_load_dwordx4 v[30:33], v8, s[42:43] offset:16
	global_load_dwordx4 v[34:37], v8, s[42:43] offset:32
	global_load_dwordx4 v[38:41], v8, s[42:43] offset:48
	s_add_u32 s51, s36, s33
	s_cmp_ge_u32 s51, s38
	s_cbranch_scc1 .Lmy_pv1_pro1
	s_lshl_b32 s0, s51, 10
	v_add_u32_e32 v9, s0, v2
	global_load_dwordx4 v[10:13], v9, s[52:53]
	global_load_dwordx4 v[14:17], v9, s[52:53] offset:16
	global_load_dwordx4 v[18:21], v9, s[52:53] offset:32
	global_load_dwordx4 v[22:25], v9, s[52:53] offset:48

; __device__ __forceinline__ void phase_peer_v(const Params& p, int layer, int xs, int wid0, int wstride, bool last, char* smraw) {
;     ...
;   auto half_fma = [&](const u32x4 (&q)[8], const f32x4& c0, const f32x4& c1) {
; #pragma unroll
;     for (int i = 0; i < 8; ++i) {
;       const float ci = i < 4 ? c0[i & 3] : c1[i & 3];
; #pragma unroll
;       for (int m = 0; m < 4; ++m) {
;         unsigned dw = q[i][m];
;         asm volatile("" : "+v"(dw) : "v"(acc[(8 * m + 31) & 31]));
;         const f32x2 e0 = __builtin_amdgcn_cvt_scalef32_pk_f32_fp4(dw, 1.0f, 0), e1 = __builtin_amdgcn_cvt_scalef32_pk_f32_fp4(dw, 1.0f, 1);
;         const f32x2 e2 = __builtin_amdgcn_cvt_scalef32_pk_f32_fp4(dw, 1.0f, 2), e3 = __builtin_amdgcn_cvt_scalef32_pk_f32_fp4(dw, 1.0f, 3);
;         acc[8 * m + 0] += ci * e0[0]; acc[8 * m + 1] += ci * e0[1]; acc[8 * m + 2] += ci * e1[0]; acc[8 * m + 3] += ci * e1[1];
;         acc[8 * m + 4] += ci * e2[0]; acc[8 * m + 5] += ci * e2[1]; acc[8 * m + 6] += ci * e3[0]; acc[8 * m + 7] += ci * e3[1];
;       }
;     }
.Lmy_pv1_noissueA:
	v_cvt_scalef32_pk_f32_fp4 v[98:99], v106, 1.0
	v_cvt_scalef32_pk_f32_fp4 v[100:101], v106, 1.0 op_sel:[1,0,0]
	v_cvt_scalef32_pk_f32_fp4 v[102:103], v106, 1.0 op_sel:[0,1,0]
	v_cvt_scalef32_pk_f32_fp4 v[104:105], v106, 1.0 op_sel:[1,1,0]
	v_pk_fma_f32 v[66:67], v[26:27], v[98:99], 0 op_sel_hi:[0,1,0]
	v_pk_fma_f32 v[68:69], v[26:27], v[100:101], 0 op_sel_hi:[0,1,0]
	v_pk_fma_f32 v[70:71], v[26:27], v[102:103], 0 op_sel_hi:[0,1,0]
	v_pk_fma_f32 v[72:73], v[26:27], v[104:105], 0 op_sel_hi:[0,1,0]
	v_cvt_scalef32_pk_f32_fp4 v[98:99], v107, 1.0
	v_cvt_scalef32_pk_f32_fp4 v[100:101], v107, 1.0 op_sel:[1,0,0]
	v_cvt_scalef32_pk_f32_fp4 v[102:103], v107, 1.0 op_sel:[0,1,0]
	v_cvt_scalef32_pk_f32_fp4 v[104:105], v107, 1.0 op_sel:[1,1,0]
	v_pk_fma_f32 v[74:75], v[26:27], v[98:99], 0 op_sel_hi:[0,1,0]
	v_pk_fma_f32 v[76:77], v[26:27], v[100:101], 0 op_sel_hi:[0,1,0]
	v_pk_fma_f32 v[78:79], v[26:27], v[102:103], 0 op_sel_hi:[0,1,0]
	v_pk_fma_f32 v[80:81], v[26:27], v[104:105], 0 op_sel_hi:[0,1,0]
	v_cvt_scalef32_pk_f32_fp4 v[98:99], v108, 1.0
	v_cvt_scalef32_pk_f32_fp4 v[100:101], v108, 1.0 op_sel:[1,0,0]
	v_cvt_scalef32_pk_f32_fp4 v[102:103], v108, 1.0 op_sel:[0,1,0]
	v_cvt_scalef32_pk_f32_fp4 v[104:105], v108, 1.0 op_sel:[1,1,0]
	v_pk_fma_f32 v[82:83], v[26:27], v[98:99], 0 op_sel_hi:[0,1,0]
	v_pk_fma_f32 v[84:85], v[26:27], v[100:101], 0 op_sel_hi:[0,1,0]
	v_pk_fma_f32 v[86:87], v[26:27], v[102:103], 0 op_sel_hi:[0,1,0]
	v_pk_fma_f32 v[88:89], v[26:27], v[104:105], 0 op_sel_hi:[0,1,0]
	v_cvt_scalef32_pk_f32_fp4 v[98:99], v109, 1.0
	v_cvt_scalef32_pk_f32_fp4 v[100:101], v109, 1.0 op_sel:[1,0,0]
	v_cvt_scalef32_pk_f32_fp4 v[102:103], v109, 1.0 op_sel:[0,1,0]
	v_cvt_scalef32_pk_f32_fp4 v[104:105], v109, 1.0 op_sel:[1,1,0]
	v_pk_fma_f32 v[90:91], v[26:27], v[98:99], 0 op_sel_hi:[0,1,0]
	v_pk_fma_f32 v[92:93], v[26:27], v[100:101], 0 op_sel_hi:[0,1,0]
	v_pk_fma_f32 v[94:95], v[26:27], v[102:103], 0 op_sel_hi:[0,1,0]
	v_pk_fma_f32 v[96:97], v[26:27], v[104:105], 0 op_sel_hi:[0,1,0]
	v_cvt_scalef32_pk_f32_fp4 v[98:99], v110, 1.0
	v_cvt_scalef32_pk_f32_fp4 v[100:101], v110, 1.0 op_sel:[1,0,0]
	v_cvt_scalef32_pk_f32_fp4 v[102:103], v110, 1.0 op_sel:[0,1,0]
	v_cvt_scalef32_pk_f32_fp4 v[104:105], v110, 1.0 op_sel:[1,1,0]
	v_pk_fma_f32 v[66:67], v[26:27], v[98:99], v[66:67] op_sel:[1,0,0] op_sel_hi:[1,1,1]
	v_pk_fma_f32 v[68:69], v[26:27], v[100:101], v[68:69] op_sel:[1,0,0] op_sel_hi:[1,1,1]
	v_pk_fma_f32 v[70:71], v[26:27], v[102:103], v[70:71] op_sel:[1,0,0] op_sel_hi:[1,1,1]
	v_pk_fma_f32 v[72:73], v[26:27], v[104:105], v[72:73] op_sel:[1,0,0] op_sel_hi:[1,1,1]
	v_cvt_scalef32_pk_f32_fp4 v[98:99], v111, 1.0
	v_cvt_scalef32_pk_f32_fp4 v[100:101], v111, 1.0 op_sel:[1,0,0]
	v_cvt_scalef32_pk_f32_fp4 v[102:103], v111, 1.0 op_sel:[0,1,0]
	v_cvt_scalef32_pk_f32_fp4 v[104:105], v111, 1.0 op_sel:[1,1,0]
	v_pk_fma_f32 v[74:75], v[26:27], v[98:99], v[74:75] op_sel:[1,0,0] op_sel_hi:[1,1,1]
	v_pk_fma_f32 v[76:77], v[26:27], v[100:101], v[76:77] op_sel:[1,0,0] op_sel_hi:[1,1,1]
	v_pk_fma_f32 v[78:79], v[26:27], v[102:103], v[78:79] op_sel:[1,0,0] op_sel_hi:[1,1,1]
	v_pk_fma_f32 v[80:81], v[26:27], v[104:105], v[80:81] op_sel:[1,0,0] op_sel_hi:[1,1,1]
	v_cvt_scalef32_pk_f32_fp4 v[98:99], v112, 1.0
	v_cvt_scalef32_pk_f32_fp4 v[100:101], v112, 1.0 op_sel:[1,0,0]
	v_cvt_scalef32_pk_f32_fp4 v[102:103], v112, 1.0 op_sel:[0,1,0]
	v_cvt_scalef32_pk_f32_fp4 v[104:105], v112, 1.0 op_sel:[1,1,0]
	v_pk_fma_f32 v[82:83], v[26:27], v[98:99], v[82:83] op_sel:[1,0,0] op_sel_hi:[1,1,1]
	v_pk_fma_f32 v[84:85], v[26:27], v[100:101], v[84:85] op_sel:[1,0,0] op_sel_hi:[1,1,1]
	v_pk_fma_f32 v[86:87], v[26:27], v[102:103], v[86:87] op_sel:[1,0,0] op_sel_hi:[1,1,1]
	v_pk_fma_f32 v[88:89], v[26:27], v[104:105], v[88:89] op_sel:[1,0,0] op_sel_hi:[1,1,1]
	v_cvt_scalef32_pk_f32_fp4 v[98:99], v113, 1.0
	v_cvt_scalef32_pk_f32_fp4 v[100:101], v113, 1.0 op_sel:[1,0,0]
	v_cvt_scalef32_pk_f32_fp4 v[102:103], v113, 1.0 op_sel:[0,1,0]
	v_cvt_scalef32_pk_f32_fp4 v[104:105], v113, 1.0 op_sel:[1,1,0]
	v_pk_fma_f32 v[90:91], v[26:27], v[98:99], v[90:91] op_sel:[1,0,0] op_sel_hi:[1,1,1]
	v_pk_fma_f32 v[92:93], v[26:27], v[100:101], v[92:93] op_sel:[1,0,0] op_sel_hi:[1,1,1]
	v_pk_fma_f32 v[94:95], v[26:27], v[102:103], v[94:95] op_sel:[1,0,0] op_sel_hi:[1,1,1]
	v_pk_fma_f32 v[96:97], v[26:27], v[104:105], v[96:97] op_sel:[1,0,0] op_sel_hi:[1,1,1]
	v_cvt_scalef32_pk_f32_fp4 v[98:99], v114, 1.0
	v_cvt_scalef32_pk_f32_fp4 v[100:101], v114, 1.0 op_sel:[1,0,0]
	v_cvt_scalef32_pk_f32_fp4 v[102:103], v114, 1.0 op_sel:[0,1,0]
	v_cvt_scalef32_pk_f32_fp4 v[104:105], v114, 1.0 op_sel:[1,1,0]
	v_pk_fma_f32 v[66:67], v[28:29], v[98:99], v[66:67] op_sel_hi:[0,1,1]
	v_pk_fma_f32 v[68:69], v[28:29], v[100:101], v[68:69] op_sel_hi:[0,1,1]
	v_pk_fma_f32 v[70:71], v[28:29], v[102:103], v[70:71] op_sel_hi:[0,1,1]
	v_pk_fma_f32 v[72:73], v[28:29], v[104:105], v[72:73] op_sel_hi:[0,1,1]
	v_cvt_scalef32_pk_f32_fp4 v[98:99], v115, 1.0
	v_cvt_scalef32_pk_f32_fp4 v[100:101], v115, 1.0 op_sel:[1,0,0]
	v_cvt_scalef32_pk_f32_fp4 v[102:103], v115, 1.0 op_sel:[0,1,0]
	v_cvt_scalef32_pk_f32_fp4 v[104:105], v115, 1.0 op_sel:[1,1,0]
	v_pk_fma_f32 v[74:75], v[28:29], v[98:99], v[74:75] op_sel_hi:[0,1,1]
	v_pk_fma_f32 v[76:77], v[28:29], v[100:101], v[76:77] op_sel_hi:[0,1,1]
	v_pk_fma_f32 v[78:79], v[28:29], v[102:103], v[78:79] op_sel_hi:[0,1,1]
	v_pk_fma_f32 v[80:81], v[28:29], v[104:105], v[80:81] op_sel_hi:[0,1,1]
	v_cvt_scalef32_pk_f32_fp4 v[98:99], v116, 1.0
	v_cvt_scalef32_pk_f32_fp4 v[100:101], v116, 1.0 op_sel:[1,0,0]
	v_cvt_scalef32_pk_f32_fp4 v[102:103], v116, 1.0 op_sel:[0,1,0]
; __device__ __forceinline__ void phase_peer_v(const Params& p, int layer, int xs, int wid0, int wstride, bool last, char* smraw) {
;     ...
;   auto half_fma = [&](const u32x4 (&q)[8], const f32x4& c0, const f32x4& c1) {
; #pragma unroll
;     for (int i = 0; i < 8; ++i) {
;       const float ci = i < 4 ? c0[i & 3] : c1[i & 3];
; #pragma unroll
;       for (int m = 0; m < 4; ++m) {
;         unsigned dw = q[i][m];
;         asm volatile("" : "+v"(dw) : "v"(acc[(8 * m + 31) & 31]));
;         const f32x2 e0 = __builtin_amdgcn_cvt_scalef32_pk_f32_fp4(dw, 1.0f, 0), e1 = __builtin_amdgcn_cvt_scalef32_pk_f32_fp4(dw, 1.0f, 1);
;         const f32x2 e2 = __builtin_amdgcn_cvt_scalef32_pk_f32_fp4(dw, 1.0f, 2), e3 = __builtin_amdgcn_cvt_scalef32_pk_f32_fp4(dw, 1.0f, 3);
;         acc[8 * m + 0] += ci * e0[0]; acc[8 * m + 1] += ci * e0[1]; acc[8 * m + 2] += ci * e1[0]; acc[8 * m + 3] += ci * e1[1];
;         acc[8 * m + 4] += ci * e2[0]; acc[8 * m + 5] += ci * e2[1]; acc[8 * m + 6] += ci * e3[0]; acc[8 * m + 7] += ci * e3[1];
;       }
;     }
	v_cvt_scalef32_pk_f32_fp4 v[104:105], v116, 1.0 op_sel:[1,1,0]
	v_pk_fma_f32 v[82:83], v[28:29], v[98:99], v[82:83] op_sel_hi:[0,1,1]
	v_pk_fma_f32 v[84:85], v[28:29], v[100:101], v[84:85] op_sel_hi:[0,1,1]
	v_pk_fma_f32 v[86:87], v[28:29], v[102:103], v[86:87] op_sel_hi:[0,1,1]
	v_pk_fma_f32 v[88:89], v[28:29], v[104:105], v[88:89] op_sel_hi:[0,1,1]
	v_cvt_scalef32_pk_f32_fp4 v[98:99], v117, 1.0
	v_cvt_scalef32_pk_f32_fp4 v[100:101], v117, 1.0 op_sel:[1,0,0]
	v_cvt_scalef32_pk_f32_fp4 v[102:103], v117, 1.0 op_sel:[0,1,0]
	v_cvt_scalef32_pk_f32_fp4 v[104:105], v117, 1.0 op_sel:[1,1,0]
	v_pk_fma_f32 v[90:91], v[28:29], v[98:99], v[90:91] op_sel_hi:[0,1,1]
	v_pk_fma_f32 v[92:93], v[28:29], v[100:101], v[92:93] op_sel_hi:[0,1,1]
	v_pk_fma_f32 v[94:95], v[28:29], v[102:103], v[94:95] op_sel_hi:[0,1,1]
	v_pk_fma_f32 v[96:97], v[28:29], v[104:105], v[96:97] op_sel_hi:[0,1,1]
	v_cvt_scalef32_pk_f32_fp4 v[98:99], v118, 1.0
	v_cvt_scalef32_pk_f32_fp4 v[100:101], v118, 1.0 op_sel:[1,0,0]
	v_cvt_scalef32_pk_f32_fp4 v[102:103], v118, 1.0 op_sel:[0,1,0]
	v_cvt_scalef32_pk_f32_fp4 v[104:105], v118, 1.0 op_sel:[1,1,0]
	v_pk_fma_f32 v[66:67], v[28:29], v[98:99], v[66:67] op_sel:[1,0,0] op_sel_hi:[1,1,1]
	v_pk_fma_f32 v[68:69], v[28:29], v[100:101], v[68:69] op_sel:[1,0,0] op_sel_hi:[1,1,1]
	v_pk_fma_f32 v[70:71], v[28:29], v[102:103], v[70:71] op_sel:[1,0,0] op_sel_hi:[1,1,1]
	v_pk_fma_f32 v[72:73], v[28:29], v[104:105], v[72:73] op_sel:[1,0,0] op_sel_hi:[1,1,1]
	v_cvt_scalef32_pk_f32_fp4 v[98:99], v119, 1.0
	v_cvt_scalef32_pk_f32_fp4 v[100:101], v119, 1.0 op_sel:[1,0,0]
	v_cvt_scalef32_pk_f32_fp4 v[102:103], v119, 1.0 op_sel:[0,1,0]
	v_cvt_scalef32_pk_f32_fp4 v[104:105], v119, 1.0 op_sel:[1,1,0]
	v_pk_fma_f32 v[74:75], v[28:29], v[98:99], v[74:75] op_sel:[1,0,0] op_sel_hi:[1,1,1]
	v_pk_fma_f32 v[76:77], v[28:29], v[100:101], v[76:77] op_sel:[1,0,0] op_sel_hi:[1,1,1]
	v_pk_fma_f32 v[78:79], v[28:29], v[102:103], v[78:79] op_sel:[1,0,0] op_sel_hi:[1,1,1]
	v_pk_fma_f32 v[80:81], v[28:29], v[104:105], v[80:81] op_sel:[1,0,0] op_sel_hi:[1,1,1]
	v_cvt_scalef32_pk_f32_fp4 v[98:99], v120, 1.0
	v_cvt_scalef32_pk_f32_fp4 v[100:101], v120, 1.0 op_sel:[1,0,0]
	v_cvt_scalef32_pk_f32_fp4 v[102:103], v120, 1.0 op_sel:[0,1,0]
	v_cvt_scalef32_pk_f32_fp4 v[104:105], v120, 1.0 op_sel:[1,1,0]
	v_pk_fma_f32 v[82:83], v[28:29], v[98:99], v[82:83] op_sel:[1,0,0] op_sel_hi:[1,1,1]
	v_pk_fma_f32 v[84:85], v[28:29], v[100:101], v[84:85] op_sel:[1,0,0] op_sel_hi:[1,1,1]
	v_pk_fma_f32 v[86:87], v[28:29], v[102:103], v[86:87] op_sel:[1,0,0] op_sel_hi:[1,1,1]
	v_pk_fma_f32 v[88:89], v[28:29], v[104:105], v[88:89] op_sel:[1,0,0] op_sel_hi:[1,1,1]
	v_cvt_scalef32_pk_f32_fp4 v[98:99], v121, 1.0
	v_cvt_scalef32_pk_f32_fp4 v[100:101], v121, 1.0 op_sel:[1,0,0]
	v_cvt_scalef32_pk_f32_fp4 v[102:103], v121, 1.0 op_sel:[0,1,0]
	v_cvt_scalef32_pk_f32_fp4 v[104:105], v121, 1.0 op_sel:[1,1,0]
	v_pk_fma_f32 v[90:91], v[28:29], v[98:99], v[90:91] op_sel:[1,0,0] op_sel_hi:[1,1,1]
	v_pk_fma_f32 v[92:93], v[28:29], v[100:101], v[92:93] op_sel:[1,0,0] op_sel_hi:[1,1,1]
	v_pk_fma_f32 v[94:95], v[28:29], v[102:103], v[94:95] op_sel:[1,0,0] op_sel_hi:[1,1,1]
	v_pk_fma_f32 v[96:97], v[28:29], v[104:105], v[96:97] op_sel:[1,0,0] op_sel_hi:[1,1,1]
	v_cvt_scalef32_pk_f32_fp4 v[98:99], v122, 1.0
	v_cvt_scalef32_pk_f32_fp4 v[100:101], v122, 1.0 op_sel:[1,0,0]
	v_cvt_scalef32_pk_f32_fp4 v[102:103], v122, 1.0 op_sel:[0,1,0]
	v_cvt_scalef32_pk_f32_fp4 v[104:105], v122, 1.0 op_sel:[1,1,0]
	v_pk_fma_f32 v[66:67], v[30:31], v[98:99], v[66:67] op_sel_hi:[0,1,1]
	v_pk_fma_f32 v[68:69], v[30:31], v[100:101], v[68:69] op_sel_hi:[0,1,1]
	v_pk_fma_f32 v[70:71], v[30:31], v[102:103], v[70:71] op_sel_hi:[0,1,1]
	v_pk_fma_f32 v[72:73], v[30:31], v[104:105], v[72:73] op_sel_hi:[0,1,1]
	v_cvt_scalef32_pk_f32_fp4 v[98:99], v123, 1.0
	v_cvt_scalef32_pk_f32_fp4 v[100:101], v123, 1.0 op_sel:[1,0,0]
	v_cvt_scalef32_pk_f32_fp4 v[102:103], v123, 1.0 op_sel:[0,1,0]
	v_cvt_scalef32_pk_f32_fp4 v[104:105], v123, 1.0 op_sel:[1,1,0]
	v_pk_fma_f32 v[74:75], v[30:31], v[98:99], v[74:75] op_sel_hi:[0,1,1]
	v_pk_fma_f32 v[76:77], v[30:31], v[100:101], v[76:77] op_sel_hi:[0,1,1]
	v_pk_fma_f32 v[78:79], v[30:31], v[102:103], v[78:79] op_sel_hi:[0,1,1]
	v_pk_fma_f32 v[80:81], v[30:31], v[104:105], v[80:81] op_sel_hi:[0,1,1]
	v_cvt_scalef32_pk_f32_fp4 v[98:99], v124, 1.0
	v_cvt_scalef32_pk_f32_fp4 v[100:101], v124, 1.0 op_sel:[1,0,0]
	v_cvt_scalef32_pk_f32_fp4 v[102:103], v124, 1.0 op_sel:[0,1,0]
	v_cvt_scalef32_pk_f32_fp4 v[104:105], v124, 1.0 op_sel:[1,1,0]
	v_pk_fma_f32 v[82:83], v[30:31], v[98:99], v[82:83] op_sel_hi:[0,1,1]
	v_pk_fma_f32 v[84:85], v[30:31], v[100:101], v[84:85] op_sel_hi:[0,1,1]
	v_pk_fma_f32 v[86:87], v[30:31], v[102:103], v[86:87] op_sel_hi:[0,1,1]
	v_pk_fma_f32 v[88:89], v[30:31], v[104:105], v[88:89] op_sel_hi:[0,1,1]
	v_cvt_scalef32_pk_f32_fp4 v[98:99], v125, 1.0
	v_cvt_scalef32_pk_f32_fp4 v[100:101], v125, 1.0 op_sel:[1,0,0]
	v_cvt_scalef32_pk_f32_fp4 v[102:103], v125, 1.0 op_sel:[0,1,0]
	v_cvt_scalef32_pk_f32_fp4 v[104:105], v125, 1.0 op_sel:[1,1,0]
	v_pk_fma_f32 v[90:91], v[30:31], v[98:99], v[90:91] op_sel_hi:[0,1,1]
	v_pk_fma_f32 v[92:93], v[30:31], v[100:101], v[92:93] op_sel_hi:[0,1,1]
	v_pk_fma_f32 v[94:95], v[30:31], v[102:103], v[94:95] op_sel_hi:[0,1,1]
	v_pk_fma_f32 v[96:97], v[30:31], v[104:105], v[96:97] op_sel_hi:[0,1,1]
	v_cvt_scalef32_pk_f32_fp4 v[98:99], v126, 1.0
	v_cvt_scalef32_pk_f32_fp4 v[100:101], v126, 1.0 op_sel:[1,0,0]
	v_cvt_scalef32_pk_f32_fp4 v[102:103], v126, 1.0 op_sel:[0,1,0]
	v_cvt_scalef32_pk_f32_fp4 v[104:105], v126, 1.0 op_sel:[1,1,0]
	v_pk_fma_f32 v[66:67], v[30:31], v[98:99], v[66:67] op_sel:[1,0,0] op_sel_hi:[1,1,1]
; __device__ __forceinline__ void phase_peer_v(const Params& p, int layer, int xs, int wid0, int wstride, bool last, char* smraw) {
;     ...
;   auto half_fma = [&](const u32x4 (&q)[8], const f32x4& c0, const f32x4& c1) {
; #pragma unroll
;     for (int i = 0; i < 8; ++i) {
;       const float ci = i < 4 ? c0[i & 3] : c1[i & 3];
; #pragma unroll
;       for (int m = 0; m < 4; ++m) {
;         unsigned dw = q[i][m];
;         asm volatile("" : "+v"(dw) : "v"(acc[(8 * m + 31) & 31]));
;         const f32x2 e0 = __builtin_amdgcn_cvt_scalef32_pk_f32_fp4(dw, 1.0f, 0), e1 = __builtin_amdgcn_cvt_scalef32_pk_f32_fp4(dw, 1.0f, 1);
;         const f32x2 e2 = __builtin_amdgcn_cvt_scalef32_pk_f32_fp4(dw, 1.0f, 2), e3 = __builtin_amdgcn_cvt_scalef32_pk_f32_fp4(dw, 1.0f, 3);
;         acc[8 * m + 0] += ci * e0[0]; acc[8 * m + 1] += ci * e0[1]; acc[8 * m + 2] += ci * e1[0]; acc[8 * m + 3] += ci * e1[1];
;         acc[8 * m + 4] += ci * e2[0]; acc[8 * m + 5] += ci * e2[1]; acc[8 * m + 6] += ci * e3[0]; acc[8 * m + 7] += ci * e3[1];
;       }
;     }
	v_pk_fma_f32 v[68:69], v[30:31], v[100:101], v[68:69] op_sel:[1,0,0] op_sel_hi:[1,1,1]
	v_pk_fma_f32 v[70:71], v[30:31], v[102:103], v[70:71] op_sel:[1,0,0] op_sel_hi:[1,1,1]
	v_pk_fma_f32 v[72:73], v[30:31], v[104:105], v[72:73] op_sel:[1,0,0] op_sel_hi:[1,1,1]
	v_cvt_scalef32_pk_f32_fp4 v[98:99], v127, 1.0
	v_cvt_scalef32_pk_f32_fp4 v[100:101], v127, 1.0 op_sel:[1,0,0]
	v_cvt_scalef32_pk_f32_fp4 v[102:103], v127, 1.0 op_sel:[0,1,0]
	v_cvt_scalef32_pk_f32_fp4 v[104:105], v127, 1.0 op_sel:[1,1,0]
	v_pk_fma_f32 v[74:75], v[30:31], v[98:99], v[74:75] op_sel:[1,0,0] op_sel_hi:[1,1,1]
	v_pk_fma_f32 v[76:77], v[30:31], v[100:101], v[76:77] op_sel:[1,0,0] op_sel_hi:[1,1,1]
	v_pk_fma_f32 v[78:79], v[30:31], v[102:103], v[78:79] op_sel:[1,0,0] op_sel_hi:[1,1,1]
	v_pk_fma_f32 v[80:81], v[30:31], v[104:105], v[80:81] op_sel:[1,0,0] op_sel_hi:[1,1,1]
	v_cvt_scalef32_pk_f32_fp4 v[98:99], v128, 1.0
	v_cvt_scalef32_pk_f32_fp4 v[100:101], v128, 1.0 op_sel:[1,0,0]
	v_cvt_scalef32_pk_f32_fp4 v[102:103], v128, 1.0 op_sel:[0,1,0]
	v_cvt_scalef32_pk_f32_fp4 v[104:105], v128, 1.0 op_sel:[1,1,0]
	v_pk_fma_f32 v[82:83], v[30:31], v[98:99], v[82:83] op_sel:[1,0,0] op_sel_hi:[1,1,1]
	v_pk_fma_f32 v[84:85], v[30:31], v[100:101], v[84:85] op_sel:[1,0,0] op_sel_hi:[1,1,1]
	v_pk_fma_f32 v[86:87], v[30:31], v[102:103], v[86:87] op_sel:[1,0,0] op_sel_hi:[1,1,1]
	v_pk_fma_f32 v[88:89], v[30:31], v[104:105], v[88:89] op_sel:[1,0,0] op_sel_hi:[1,1,1]
	v_cvt_scalef32_pk_f32_fp4 v[98:99], v129, 1.0
	v_cvt_scalef32_pk_f32_fp4 v[100:101], v129, 1.0 op_sel:[1,0,0]
	v_cvt_scalef32_pk_f32_fp4 v[102:103], v129, 1.0 op_sel:[0,1,0]
	v_cvt_scalef32_pk_f32_fp4 v[104:105], v129, 1.0 op_sel:[1,1,0]
	v_pk_fma_f32 v[90:91], v[30:31], v[98:99], v[90:91] op_sel:[1,0,0] op_sel_hi:[1,1,1]
	v_pk_fma_f32 v[92:93], v[30:31], v[100:101], v[92:93] op_sel:[1,0,0] op_sel_hi:[1,1,1]
	v_pk_fma_f32 v[94:95], v[30:31], v[102:103], v[94:95] op_sel:[1,0,0] op_sel_hi:[1,1,1]
	v_pk_fma_f32 v[96:97], v[30:31], v[104:105], v[96:97] op_sel:[1,0,0] op_sel_hi:[1,1,1]
	v_cvt_scalef32_pk_f32_fp4 v[98:99], v130, 1.0
	v_cvt_scalef32_pk_f32_fp4 v[100:101], v130, 1.0 op_sel:[1,0,0]
	v_cvt_scalef32_pk_f32_fp4 v[102:103], v130, 1.0 op_sel:[0,1,0]
	v_cvt_scalef32_pk_f32_fp4 v[104:105], v130, 1.0 op_sel:[1,1,0]
	v_pk_fma_f32 v[66:67], v[32:33], v[98:99], v[66:67] op_sel_hi:[0,1,1]
	v_pk_fma_f32 v[68:69], v[32:33], v[100:101], v[68:69] op_sel_hi:[0,1,1]
	v_pk_fma_f32 v[70:71], v[32:33], v[102:103], v[70:71] op_sel_hi:[0,1,1]
	v_pk_fma_f32 v[72:73], v[32:33], v[104:105], v[72:73] op_sel_hi:[0,1,1]
	v_cvt_scalef32_pk_f32_fp4 v[98:99], v131, 1.0
	v_cvt_scalef32_pk_f32_fp4 v[100:101], v131, 1.0 op_sel:[1,0,0]
	v_cvt_scalef32_pk_f32_fp4 v[102:103], v131, 1.0 op_sel:[0,1,0]
	v_cvt_scalef32_pk_f32_fp4 v[104:105], v131, 1.0 op_sel:[1,1,0]
	v_pk_fma_f32 v[74:75], v[32:33], v[98:99], v[74:75] op_sel_hi:[0,1,1]
	v_pk_fma_f32 v[76:77], v[32:33], v[100:101], v[76:77] op_sel_hi:[0,1,1]
	v_pk_fma_f32 v[78:79], v[32:33], v[102:103], v[78:79] op_sel_hi:[0,1,1]
	v_pk_fma_f32 v[80:81], v[32:33], v[104:105], v[80:81] op_sel_hi:[0,1,1]
	v_cvt_scalef32_pk_f32_fp4 v[98:99], v132, 1.0
	v_cvt_scalef32_pk_f32_fp4 v[100:101], v132, 1.0 op_sel:[1,0,0]
	v_cvt_scalef32_pk_f32_fp4 v[102:103], v132, 1.0 op_sel:[0,1,0]
	v_cvt_scalef32_pk_f32_fp4 v[104:105], v132, 1.0 op_sel:[1,1,0]
	v_pk_fma_f32 v[82:83], v[32:33], v[98:99], v[82:83] op_sel_hi:[0,1,1]
	v_pk_fma_f32 v[84:85], v[32:33], v[100:101], v[84:85] op_sel_hi:[0,1,1]
	v_pk_fma_f32 v[86:87], v[32:33], v[102:103], v[86:87] op_sel_hi:[0,1,1]
	v_pk_fma_f32 v[88:89], v[32:33], v[104:105], v[88:89] op_sel_hi:[0,1,1]
	v_cvt_scalef32_pk_f32_fp4 v[98:99], v133, 1.0
	v_cvt_scalef32_pk_f32_fp4 v[100:101], v133, 1.0 op_sel:[1,0,0]
	v_cvt_scalef32_pk_f32_fp4 v[102:103], v133, 1.0 op_sel:[0,1,0]
	v_cvt_scalef32_pk_f32_fp4 v[104:105], v133, 1.0 op_sel:[1,1,0]
	v_pk_fma_f32 v[90:91], v[32:33], v[98:99], v[90:91] op_sel_hi:[0,1,1]
	v_pk_fma_f32 v[92:93], v[32:33], v[100:101], v[92:93] op_sel_hi:[0,1,1]
	v_pk_fma_f32 v[94:95], v[32:33], v[102:103], v[94:95] op_sel_hi:[0,1,1]
	v_pk_fma_f32 v[96:97], v[32:33], v[104:105], v[96:97] op_sel_hi:[0,1,1]
	v_cvt_scalef32_pk_f32_fp4 v[98:99], v134, 1.0
	v_cvt_scalef32_pk_f32_fp4 v[100:101], v134, 1.0 op_sel:[1,0,0]
	v_cvt_scalef32_pk_f32_fp4 v[102:103], v134, 1.0 op_sel:[0,1,0]
	v_cvt_scalef32_pk_f32_fp4 v[104:105], v134, 1.0 op_sel:[1,1,0]
	v_pk_fma_f32 v[66:67], v[32:33], v[98:99], v[66:67] op_sel:[1,0,0] op_sel_hi:[1,1,1]
	v_pk_fma_f32 v[68:69], v[32:33], v[100:101], v[68:69] op_sel:[1,0,0] op_sel_hi:[1,1,1]
	v_pk_fma_f32 v[70:71], v[32:33], v[102:103], v[70:71] op_sel:[1,0,0] op_sel_hi:[1,1,1]
	v_pk_fma_f32 v[72:73], v[32:33], v[104:105], v[72:73] op_sel:[1,0,0] op_sel_hi:[1,1,1]
	v_cvt_scalef32_pk_f32_fp4 v[98:99], v135, 1.0
	v_cvt_scalef32_pk_f32_fp4 v[100:101], v135, 1.0 op_sel:[1,0,0]
	v_cvt_scalef32_pk_f32_fp4 v[102:103], v135, 1.0 op_sel:[0,1,0]
	v_cvt_scalef32_pk_f32_fp4 v[104:105], v135, 1.0 op_sel:[1,1,0]
	v_pk_fma_f32 v[74:75], v[32:33], v[98:99], v[74:75] op_sel:[1,0,0] op_sel_hi:[1,1,1]
	v_pk_fma_f32 v[76:77], v[32:33], v[100:101], v[76:77] op_sel:[1,0,0] op_sel_hi:[1,1,1]
	v_pk_fma_f32 v[78:79], v[32:33], v[102:103], v[78:79] op_sel:[1,0,0] op_sel_hi:[1,1,1]
	v_pk_fma_f32 v[80:81], v[32:33], v[104:105], v[80:81] op_sel:[1,0,0] op_sel_hi:[1,1,1]
	v_cvt_scalef32_pk_f32_fp4 v[98:99], v136, 1.0
	v_cvt_scalef32_pk_f32_fp4 v[100:101], v136, 1.0 op_sel:[1,0,0]
	v_cvt_scalef32_pk_f32_fp4 v[102:103], v136, 1.0 op_sel:[0,1,0]
	v_cvt_scalef32_pk_f32_fp4 v[104:105], v136, 1.0 op_sel:[1,1,0]
	v_pk_fma_f32 v[82:83], v[32:33], v[98:99], v[82:83] op_sel:[1,0,0] op_sel_hi:[1,1,1]
; __device__ __forceinline__ void phase_peer_v(const Params& p, int layer, int xs, int wid0, int wstride, bool last, char* smraw) {
;     ...
;   auto half_fma = [&](const u32x4 (&q)[8], const f32x4& c0, const f32x4& c1) {
; #pragma unroll
;     for (int i = 0; i < 8; ++i) {
;       const float ci = i < 4 ? c0[i & 3] : c1[i & 3];
; #pragma unroll
;       for (int m = 0; m < 4; ++m) {
;         unsigned dw = q[i][m];
;         asm volatile("" : "+v"(dw) : "v"(acc[(8 * m + 31) & 31]));
;         const f32x2 e0 = __builtin_amdgcn_cvt_scalef32_pk_f32_fp4(dw, 1.0f, 0), e1 = __builtin_amdgcn_cvt_scalef32_pk_f32_fp4(dw, 1.0f, 1);
;         const f32x2 e2 = __builtin_amdgcn_cvt_scalef32_pk_f32_fp4(dw, 1.0f, 2), e3 = __builtin_amdgcn_cvt_scalef32_pk_f32_fp4(dw, 1.0f, 3);
;         acc[8 * m + 0] += ci * e0[0]; acc[8 * m + 1] += ci * e0[1]; acc[8 * m + 2] += ci * e1[0]; acc[8 * m + 3] += ci * e1[1];
;         acc[8 * m + 4] += ci * e2[0]; acc[8 * m + 5] += ci * e2[1]; acc[8 * m + 6] += ci * e3[0]; acc[8 * m + 7] += ci * e3[1];
;       }
;     }
	v_pk_fma_f32 v[84:85], v[32:33], v[100:101], v[84:85] op_sel:[1,0,0] op_sel_hi:[1,1,1]
	v_pk_fma_f32 v[86:87], v[32:33], v[102:103], v[86:87] op_sel:[1,0,0] op_sel_hi:[1,1,1]
	v_pk_fma_f32 v[88:89], v[32:33], v[104:105], v[88:89] op_sel:[1,0,0] op_sel_hi:[1,1,1]
	v_cvt_scalef32_pk_f32_fp4 v[98:99], v137, 1.0
	v_cvt_scalef32_pk_f32_fp4 v[100:101], v137, 1.0 op_sel:[1,0,0]
	v_cvt_scalef32_pk_f32_fp4 v[102:103], v137, 1.0 op_sel:[0,1,0]
	v_cvt_scalef32_pk_f32_fp4 v[104:105], v137, 1.0 op_sel:[1,1,0]
	v_pk_fma_f32 v[90:91], v[32:33], v[98:99], v[90:91] op_sel:[1,0,0] op_sel_hi:[1,1,1]
	v_pk_fma_f32 v[92:93], v[32:33], v[100:101], v[92:93] op_sel:[1,0,0] op_sel_hi:[1,1,1]
	v_pk_fma_f32 v[94:95], v[32:33], v[102:103], v[94:95] op_sel:[1,0,0] op_sel_hi:[1,1,1]
	v_pk_fma_f32 v[96:97], v[32:33], v[104:105], v[96:97] op_sel:[1,0,0] op_sel_hi:[1,1,1]
	v_cvt_scalef32_pk_f32_fp4 v[98:99], v138, 1.0
	v_cvt_scalef32_pk_f32_fp4 v[100:101], v138, 1.0 op_sel:[1,0,0]
	v_cvt_scalef32_pk_f32_fp4 v[102:103], v138, 1.0 op_sel:[0,1,0]
	v_cvt_scalef32_pk_f32_fp4 v[104:105], v138, 1.0 op_sel:[1,1,0]
	v_pk_fma_f32 v[66:67], v[34:35], v[98:99], v[66:67] op_sel_hi:[0,1,1]
	v_pk_fma_f32 v[68:69], v[34:35], v[100:101], v[68:69] op_sel_hi:[0,1,1]
	v_pk_fma_f32 v[70:71], v[34:35], v[102:103], v[70:71] op_sel_hi:[0,1,1]
	v_pk_fma_f32 v[72:73], v[34:35], v[104:105], v[72:73] op_sel_hi:[0,1,1]
	v_cvt_scalef32_pk_f32_fp4 v[98:99], v139, 1.0
	v_cvt_scalef32_pk_f32_fp4 v[100:101], v139, 1.0 op_sel:[1,0,0]
	v_cvt_scalef32_pk_f32_fp4 v[102:103], v139, 1.0 op_sel:[0,1,0]
	v_cvt_scalef32_pk_f32_fp4 v[104:105], v139, 1.0 op_sel:[1,1,0]
	v_pk_fma_f32 v[74:75], v[34:35], v[98:99], v[74:75] op_sel_hi:[0,1,1]
	v_pk_fma_f32 v[76:77], v[34:35], v[100:101], v[76:77] op_sel_hi:[0,1,1]
	v_pk_fma_f32 v[78:79], v[34:35], v[102:103], v[78:79] op_sel_hi:[0,1,1]
	v_pk_fma_f32 v[80:81], v[34:35], v[104:105], v[80:81] op_sel_hi:[0,1,1]
	v_cvt_scalef32_pk_f32_fp4 v[98:99], v140, 1.0
	v_cvt_scalef32_pk_f32_fp4 v[100:101], v140, 1.0 op_sel:[1,0,0]
	v_cvt_scalef32_pk_f32_fp4 v[102:103], v140, 1.0 op_sel:[0,1,0]
	v_cvt_scalef32_pk_f32_fp4 v[104:105], v140, 1.0 op_sel:[1,1,0]
	v_pk_fma_f32 v[82:83], v[34:35], v[98:99], v[82:83] op_sel_hi:[0,1,1]
	v_pk_fma_f32 v[84:85], v[34:35], v[100:101], v[84:85] op_sel_hi:[0,1,1]
	v_pk_fma_f32 v[86:87], v[34:35], v[102:103], v[86:87] op_sel_hi:[0,1,1]
	v_pk_fma_f32 v[88:89], v[34:35], v[104:105], v[88:89] op_sel_hi:[0,1,1]
	v_cvt_scalef32_pk_f32_fp4 v[98:99], v141, 1.0
	v_cvt_scalef32_pk_f32_fp4 v[100:101], v141, 1.0 op_sel:[1,0,0]
	v_cvt_scalef32_pk_f32_fp4 v[102:103], v141, 1.0 op_sel:[0,1,0]
	v_cvt_scalef32_pk_f32_fp4 v[104:105], v141, 1.0 op_sel:[1,1,0]
	v_pk_fma_f32 v[90:91], v[34:35], v[98:99], v[90:91] op_sel_hi:[0,1,1]
	v_pk_fma_f32 v[92:93], v[34:35], v[100:101], v[92:93] op_sel_hi:[0,1,1]
	v_pk_fma_f32 v[94:95], v[34:35], v[102:103], v[94:95] op_sel_hi:[0,1,1]
	v_pk_fma_f32 v[96:97], v[34:35], v[104:105], v[96:97] op_sel_hi:[0,1,1]
	v_cvt_scalef32_pk_f32_fp4 v[98:99], v142, 1.0
	v_cvt_scalef32_pk_f32_fp4 v[100:101], v142, 1.0 op_sel:[1,0,0]
	v_cvt_scalef32_pk_f32_fp4 v[102:103], v142, 1.0 op_sel:[0,1,0]
	v_cvt_scalef32_pk_f32_fp4 v[104:105], v142, 1.0 op_sel:[1,1,0]
	v_pk_fma_f32 v[66:67], v[34:35], v[98:99], v[66:67] op_sel:[1,0,0] op_sel_hi:[1,1,1]
	v_pk_fma_f32 v[68:69], v[34:35], v[100:101], v[68:69] op_sel:[1,0,0] op_sel_hi:[1,1,1]
	v_pk_fma_f32 v[70:71], v[34:35], v[102:103], v[70:71] op_sel:[1,0,0] op_sel_hi:[1,1,1]
	v_pk_fma_f32 v[72:73], v[34:35], v[104:105], v[72:73] op_sel:[1,0,0] op_sel_hi:[1,1,1]
	v_cvt_scalef32_pk_f32_fp4 v[98:99], v143, 1.0
	v_cvt_scalef32_pk_f32_fp4 v[100:101], v143, 1.0 op_sel:[1,0,0]
	v_cvt_scalef32_pk_f32_fp4 v[102:103], v143, 1.0 op_sel:[0,1,0]
	v_cvt_scalef32_pk_f32_fp4 v[104:105], v143, 1.0 op_sel:[1,1,0]
	v_pk_fma_f32 v[74:75], v[34:35], v[98:99], v[74:75] op_sel:[1,0,0] op_sel_hi:[1,1,1]
	v_pk_fma_f32 v[76:77], v[34:35], v[100:101], v[76:77] op_sel:[1,0,0] op_sel_hi:[1,1,1]
	v_pk_fma_f32 v[78:79], v[34:35], v[102:103], v[78:79] op_sel:[1,0,0] op_sel_hi:[1,1,1]
	v_pk_fma_f32 v[80:81], v[34:35], v[104:105], v[80:81] op_sel:[1,0,0] op_sel_hi:[1,1,1]
	v_cvt_scalef32_pk_f32_fp4 v[98:99], v144, 1.0
	v_cvt_scalef32_pk_f32_fp4 v[100:101], v144, 1.0 op_sel:[1,0,0]
	v_cvt_scalef32_pk_f32_fp4 v[102:103], v144, 1.0 op_sel:[0,1,0]
	v_cvt_scalef32_pk_f32_fp4 v[104:105], v144, 1.0 op_sel:[1,1,0]
	v_pk_fma_f32 v[82:83], v[34:35], v[98:99], v[82:83] op_sel:[1,0,0] op_sel_hi:[1,1,1]
	v_pk_fma_f32 v[84:85], v[34:35], v[100:101], v[84:85] op_sel:[1,0,0] op_sel_hi:[1,1,1]
	v_pk_fma_f32 v[86:87], v[34:35], v[102:103], v[86:87] op_sel:[1,0,0] op_sel_hi:[1,1,1]
	v_pk_fma_f32 v[88:89], v[34:35], v[104:105], v[88:89] op_sel:[1,0,0] op_sel_hi:[1,1,1]
	v_cvt_scalef32_pk_f32_fp4 v[98:99], v145, 1.0
	v_cvt_scalef32_pk_f32_fp4 v[100:101], v145, 1.0 op_sel:[1,0,0]
	v_cvt_scalef32_pk_f32_fp4 v[102:103], v145, 1.0 op_sel:[0,1,0]
	v_cvt_scalef32_pk_f32_fp4 v[104:105], v145, 1.0 op_sel:[1,1,0]
	v_pk_fma_f32 v[90:91], v[34:35], v[98:99], v[90:91] op_sel:[1,0,0] op_sel_hi:[1,1,1]
	v_pk_fma_f32 v[92:93], v[34:35], v[100:101], v[92:93] op_sel:[1,0,0] op_sel_hi:[1,1,1]
	v_pk_fma_f32 v[94:95], v[34:35], v[102:103], v[94:95] op_sel:[1,0,0] op_sel_hi:[1,1,1]
	v_pk_fma_f32 v[96:97], v[34:35], v[104:105], v[96:97] op_sel:[1,0,0] op_sel_hi:[1,1,1]
	v_cvt_scalef32_pk_f32_fp4 v[98:99], v146, 1.0
	v_cvt_scalef32_pk_f32_fp4 v[100:101], v146, 1.0 op_sel:[1,0,0]
	v_cvt_scalef32_pk_f32_fp4 v[102:103], v146, 1.0 op_sel:[0,1,0]
	v_cvt_scalef32_pk_f32_fp4 v[104:105], v146, 1.0 op_sel:[1,1,0]
	v_pk_fma_f32 v[66:67], v[36:37], v[98:99], v[66:67] op_sel_hi:[0,1,1]
; __device__ __forceinline__ void phase_peer_v(const Params& p, int layer, int xs, int wid0, int wstride, bool last, char* smraw) {
;     ...
;   auto half_fma = [&](const u32x4 (&q)[8], const f32x4& c0, const f32x4& c1) {
; #pragma unroll
;     for (int i = 0; i < 8; ++i) {
;       const float ci = i < 4 ? c0[i & 3] : c1[i & 3];
; #pragma unroll
;       for (int m = 0; m < 4; ++m) {
;         unsigned dw = q[i][m];
;         asm volatile("" : "+v"(dw) : "v"(acc[(8 * m + 31) & 31]));
;         const f32x2 e0 = __builtin_amdgcn_cvt_scalef32_pk_f32_fp4(dw, 1.0f, 0), e1 = __builtin_amdgcn_cvt_scalef32_pk_f32_fp4(dw, 1.0f, 1);
;         const f32x2 e2 = __builtin_amdgcn_cvt_scalef32_pk_f32_fp4(dw, 1.0f, 2), e3 = __builtin_amdgcn_cvt_scalef32_pk_f32_fp4(dw, 1.0f, 3);
;         acc[8 * m + 0] += ci * e0[0]; acc[8 * m + 1] += ci * e0[1]; acc[8 * m + 2] += ci * e1[0]; acc[8 * m + 3] += ci * e1[1];
;         acc[8 * m + 4] += ci * e2[0]; acc[8 * m + 5] += ci * e2[1]; acc[8 * m + 6] += ci * e3[0]; acc[8 * m + 7] += ci * e3[1];
;       }
;     }
	v_pk_fma_f32 v[68:69], v[36:37], v[100:101], v[68:69] op_sel_hi:[0,1,1]
	v_pk_fma_f32 v[70:71], v[36:37], v[102:103], v[70:71] op_sel_hi:[0,1,1]
	v_pk_fma_f32 v[72:73], v[36:37], v[104:105], v[72:73] op_sel_hi:[0,1,1]
	v_cvt_scalef32_pk_f32_fp4 v[98:99], v147, 1.0
	v_cvt_scalef32_pk_f32_fp4 v[100:101], v147, 1.0 op_sel:[1,0,0]
	v_cvt_scalef32_pk_f32_fp4 v[102:103], v147, 1.0 op_sel:[0,1,0]
	v_cvt_scalef32_pk_f32_fp4 v[104:105], v147, 1.0 op_sel:[1,1,0]
	v_pk_fma_f32 v[74:75], v[36:37], v[98:99], v[74:75] op_sel_hi:[0,1,1]
	v_pk_fma_f32 v[76:77], v[36:37], v[100:101], v[76:77] op_sel_hi:[0,1,1]
	v_pk_fma_f32 v[78:79], v[36:37], v[102:103], v[78:79] op_sel_hi:[0,1,1]
	v_pk_fma_f32 v[80:81], v[36:37], v[104:105], v[80:81] op_sel_hi:[0,1,1]
	v_cvt_scalef32_pk_f32_fp4 v[98:99], v148, 1.0
	v_cvt_scalef32_pk_f32_fp4 v[100:101], v148, 1.0 op_sel:[1,0,0]
	v_cvt_scalef32_pk_f32_fp4 v[102:103], v148, 1.0 op_sel:[0,1,0]
	v_cvt_scalef32_pk_f32_fp4 v[104:105], v148, 1.0 op_sel:[1,1,0]
	v_pk_fma_f32 v[82:83], v[36:37], v[98:99], v[82:83] op_sel_hi:[0,1,1]
	v_pk_fma_f32 v[84:85], v[36:37], v[100:101], v[84:85] op_sel_hi:[0,1,1]
	v_pk_fma_f32 v[86:87], v[36:37], v[102:103], v[86:87] op_sel_hi:[0,1,1]
	v_pk_fma_f32 v[88:89], v[36:37], v[104:105], v[88:89] op_sel_hi:[0,1,1]
	v_cvt_scalef32_pk_f32_fp4 v[98:99], v149, 1.0
	v_cvt_scalef32_pk_f32_fp4 v[100:101], v149, 1.0 op_sel:[1,0,0]
	v_cvt_scalef32_pk_f32_fp4 v[102:103], v149, 1.0 op_sel:[0,1,0]
	v_cvt_scalef32_pk_f32_fp4 v[104:105], v149, 1.0 op_sel:[1,1,0]
	v_pk_fma_f32 v[90:91], v[36:37], v[98:99], v[90:91] op_sel_hi:[0,1,1]
	v_pk_fma_f32 v[92:93], v[36:37], v[100:101], v[92:93] op_sel_hi:[0,1,1]
	v_pk_fma_f32 v[94:95], v[36:37], v[102:103], v[94:95] op_sel_hi:[0,1,1]
	v_pk_fma_f32 v[96:97], v[36:37], v[104:105], v[96:97] op_sel_hi:[0,1,1]
	v_cvt_scalef32_pk_f32_fp4 v[98:99], v150, 1.0
	v_cvt_scalef32_pk_f32_fp4 v[100:101], v150, 1.0 op_sel:[1,0,0]
	v_cvt_scalef32_pk_f32_fp4 v[102:103], v150, 1.0 op_sel:[0,1,0]
	v_cvt_scalef32_pk_f32_fp4 v[104:105], v150, 1.0 op_sel:[1,1,0]
	v_pk_fma_f32 v[66:67], v[36:37], v[98:99], v[66:67] op_sel:[1,0,0] op_sel_hi:[1,1,1]
	v_pk_fma_f32 v[68:69], v[36:37], v[100:101], v[68:69] op_sel:[1,0,0] op_sel_hi:[1,1,1]
	v_pk_fma_f32 v[70:71], v[36:37], v[102:103], v[70:71] op_sel:[1,0,0] op_sel_hi:[1,1,1]
	v_pk_fma_f32 v[72:73], v[36:37], v[104:105], v[72:73] op_sel:[1,0,0] op_sel_hi:[1,1,1]
	v_cvt_scalef32_pk_f32_fp4 v[98:99], v151, 1.0
	v_cvt_scalef32_pk_f32_fp4 v[100:101], v151, 1.0 op_sel:[1,0,0]
	v_cvt_scalef32_pk_f32_fp4 v[102:103], v151, 1.0 op_sel:[0,1,0]
	v_cvt_scalef32_pk_f32_fp4 v[104:105], v151, 1.0 op_sel:[1,1,0]
	v_pk_fma_f32 v[74:75], v[36:37], v[98:99], v[74:75] op_sel:[1,0,0] op_sel_hi:[1,1,1]
	v_pk_fma_f32 v[76:77], v[36:37], v[100:101], v[76:77] op_sel:[1,0,0] op_sel_hi:[1,1,1]
	v_pk_fma_f32 v[78:79], v[36:37], v[102:103], v[78:79] op_sel:[1,0,0] op_sel_hi:[1,1,1]
	v_pk_fma_f32 v[80:81], v[36:37], v[104:105], v[80:81] op_sel:[1,0,0] op_sel_hi:[1,1,1]
	v_cvt_scalef32_pk_f32_fp4 v[98:99], v152, 1.0
	v_cvt_scalef32_pk_f32_fp4 v[100:101], v152, 1.0 op_sel:[1,0,0]
	v_cvt_scalef32_pk_f32_fp4 v[102:103], v152, 1.0 op_sel:[0,1,0]
	v_cvt_scalef32_pk_f32_fp4 v[104:105], v152, 1.0 op_sel:[1,1,0]
	v_pk_fma_f32 v[82:83], v[36:37], v[98:99], v[82:83] op_sel:[1,0,0] op_sel_hi:[1,1,1]
	v_pk_fma_f32 v[84:85], v[36:37], v[100:101], v[84:85] op_sel:[1,0,0] op_sel_hi:[1,1,1]
	v_pk_fma_f32 v[86:87], v[36:37], v[102:103], v[86:87] op_sel:[1,0,0] op_sel_hi:[1,1,1]
	v_pk_fma_f32 v[88:89], v[36:37], v[104:105], v[88:89] op_sel:[1,0,0] op_sel_hi:[1,1,1]
	v_cvt_scalef32_pk_f32_fp4 v[98:99], v153, 1.0
	v_cvt_scalef32_pk_f32_fp4 v[100:101], v153, 1.0 op_sel:[1,0,0]
	v_cvt_scalef32_pk_f32_fp4 v[102:103], v153, 1.0 op_sel:[0,1,0]
	v_cvt_scalef32_pk_f32_fp4 v[104:105], v153, 1.0 op_sel:[1,1,0]
	v_pk_fma_f32 v[90:91], v[36:37], v[98:99], v[90:91] op_sel:[1,0,0] op_sel_hi:[1,1,1]
	v_pk_fma_f32 v[92:93], v[36:37], v[100:101], v[92:93] op_sel:[1,0,0] op_sel_hi:[1,1,1]
	v_pk_fma_f32 v[94:95], v[36:37], v[102:103], v[94:95] op_sel:[1,0,0] op_sel_hi:[1,1,1]
	v_pk_fma_f32 v[96:97], v[36:37], v[104:105], v[96:97] op_sel:[1,0,0] op_sel_hi:[1,1,1]
	v_cvt_scalef32_pk_f32_fp4 v[98:99], v154, 1.0
	v_cvt_scalef32_pk_f32_fp4 v[100:101], v154, 1.0 op_sel:[1,0,0]
	v_cvt_scalef32_pk_f32_fp4 v[102:103], v154, 1.0 op_sel:[0,1,0]
	v_cvt_scalef32_pk_f32_fp4 v[104:105], v154, 1.0 op_sel:[1,1,0]
	v_pk_fma_f32 v[66:67], v[38:39], v[98:99], v[66:67] op_sel_hi:[0,1,1]
	v_pk_fma_f32 v[68:69], v[38:39], v[100:101], v[68:69] op_sel_hi:[0,1,1]
	v_pk_fma_f32 v[70:71], v[38:39], v[102:103], v[70:71] op_sel_hi:[0,1,1]
	v_pk_fma_f32 v[72:73], v[38:39], v[104:105], v[72:73] op_sel_hi:[0,1,1]
	v_cvt_scalef32_pk_f32_fp4 v[98:99], v155, 1.0
	v_cvt_scalef32_pk_f32_fp4 v[100:101], v155, 1.0 op_sel:[1,0,0]
	v_cvt_scalef32_pk_f32_fp4 v[102:103], v155, 1.0 op_sel:[0,1,0]
	v_cvt_scalef32_pk_f32_fp4 v[104:105], v155, 1.0 op_sel:[1,1,0]
	v_pk_fma_f32 v[74:75], v[38:39], v[98:99], v[74:75] op_sel_hi:[0,1,1]
	v_pk_fma_f32 v[76:77], v[38:39], v[100:101], v[76:77] op_sel_hi:[0,1,1]
	v_pk_fma_f32 v[78:79], v[38:39], v[102:103], v[78:79] op_sel_hi:[0,1,1]
	v_pk_fma_f32 v[80:81], v[38:39], v[104:105], v[80:81] op_sel_hi:[0,1,1]
	v_cvt_scalef32_pk_f32_fp4 v[98:99], v156, 1.0
	v_cvt_scalef32_pk_f32_fp4 v[100:101], v156, 1.0 op_sel:[1,0,0]
	v_cvt_scalef32_pk_f32_fp4 v[102:103], v156, 1.0 op_sel:[0,1,0]
	v_cvt_scalef32_pk_f32_fp4 v[104:105], v156, 1.0 op_sel:[1,1,0]
	v_pk_fma_f32 v[82:83], v[38:39], v[98:99], v[82:83] op_sel_hi:[0,1,1]
	v_pk_fma_f32 v[84:85], v[38:39], v[100:101], v[84:85] op_sel_hi:[0,1,1]
	v_pk_fma_f32 v[86:87], v[38:39], v[102:103], v[86:87] op_sel_hi:[0,1,1]
; __device__ __forceinline__ void phase_peer_v(const Params& p, int layer, int xs, int wid0, int wstride, bool last, char* smraw) {
;     ...
;   auto half_fma = [&](const u32x4 (&q)[8], const f32x4& c0, const f32x4& c1) {
; #pragma unroll
;     for (int i = 0; i < 8; ++i) {
;       const float ci = i < 4 ? c0[i & 3] : c1[i & 3];
; #pragma unroll
;       for (int m = 0; m < 4; ++m) {
;         unsigned dw = q[i][m];
;         asm volatile("" : "+v"(dw) : "v"(acc[(8 * m + 31) & 31]));
;         const f32x2 e0 = __builtin_amdgcn_cvt_scalef32_pk_f32_fp4(dw, 1.0f, 0), e1 = __builtin_amdgcn_cvt_scalef32_pk_f32_fp4(dw, 1.0f, 1);
;         const f32x2 e2 = __builtin_amdgcn_cvt_scalef32_pk_f32_fp4(dw, 1.0f, 2), e3 = __builtin_amdgcn_cvt_scalef32_pk_f32_fp4(dw, 1.0f, 3);
;         acc[8 * m + 0] += ci * e0[0]; acc[8 * m + 1] += ci * e0[1]; acc[8 * m + 2] += ci * e1[0]; acc[8 * m + 3] += ci * e1[1];
;         acc[8 * m + 4] += ci * e2[0]; acc[8 * m + 5] += ci * e2[1]; acc[8 * m + 6] += ci * e3[0]; acc[8 * m + 7] += ci * e3[1];
;       }
;     }
	v_pk_fma_f32 v[88:89], v[38:39], v[104:105], v[88:89] op_sel_hi:[0,1,1]
	v_cvt_scalef32_pk_f32_fp4 v[98:99], v157, 1.0
	v_cvt_scalef32_pk_f32_fp4 v[100:101], v157, 1.0 op_sel:[1,0,0]
	v_cvt_scalef32_pk_f32_fp4 v[102:103], v157, 1.0 op_sel:[0,1,0]
	v_cvt_scalef32_pk_f32_fp4 v[104:105], v157, 1.0 op_sel:[1,1,0]
	v_pk_fma_f32 v[90:91], v[38:39], v[98:99], v[90:91] op_sel_hi:[0,1,1]
	v_pk_fma_f32 v[92:93], v[38:39], v[100:101], v[92:93] op_sel_hi:[0,1,1]
	v_pk_fma_f32 v[94:95], v[38:39], v[102:103], v[94:95] op_sel_hi:[0,1,1]
	v_pk_fma_f32 v[96:97], v[38:39], v[104:105], v[96:97] op_sel_hi:[0,1,1]
	v_cvt_scalef32_pk_f32_fp4 v[98:99], v158, 1.0
	v_cvt_scalef32_pk_f32_fp4 v[100:101], v158, 1.0 op_sel:[1,0,0]
	v_cvt_scalef32_pk_f32_fp4 v[102:103], v158, 1.0 op_sel:[0,1,0]
	v_cvt_scalef32_pk_f32_fp4 v[104:105], v158, 1.0 op_sel:[1,1,0]
	v_pk_fma_f32 v[66:67], v[38:39], v[98:99], v[66:67] op_sel:[1,0,0] op_sel_hi:[1,1,1]
	v_pk_fma_f32 v[68:69], v[38:39], v[100:101], v[68:69] op_sel:[1,0,0] op_sel_hi:[1,1,1]
	v_pk_fma_f32 v[70:71], v[38:39], v[102:103], v[70:71] op_sel:[1,0,0] op_sel_hi:[1,1,1]
	v_pk_fma_f32 v[72:73], v[38:39], v[104:105], v[72:73] op_sel:[1,0,0] op_sel_hi:[1,1,1]
	v_cvt_scalef32_pk_f32_fp4 v[98:99], v159, 1.0
	v_cvt_scalef32_pk_f32_fp4 v[100:101], v159, 1.0 op_sel:[1,0,0]
	v_cvt_scalef32_pk_f32_fp4 v[102:103], v159, 1.0 op_sel:[0,1,0]
	v_cvt_scalef32_pk_f32_fp4 v[104:105], v159, 1.0 op_sel:[1,1,0]
	v_pk_fma_f32 v[74:75], v[38:39], v[98:99], v[74:75] op_sel:[1,0,0] op_sel_hi:[1,1,1]
	v_pk_fma_f32 v[76:77], v[38:39], v[100:101], v[76:77] op_sel:[1,0,0] op_sel_hi:[1,1,1]
	v_pk_fma_f32 v[78:79], v[38:39], v[102:103], v[78:79] op_sel:[1,0,0] op_sel_hi:[1,1,1]
	v_pk_fma_f32 v[80:81], v[38:39], v[104:105], v[80:81] op_sel:[1,0,0] op_sel_hi:[1,1,1]
	v_cvt_scalef32_pk_f32_fp4 v[98:99], v160, 1.0
	v_cvt_scalef32_pk_f32_fp4 v[100:101], v160, 1.0 op_sel:[1,0,0]
	v_cvt_scalef32_pk_f32_fp4 v[102:103], v160, 1.0 op_sel:[0,1,0]
	v_cvt_scalef32_pk_f32_fp4 v[104:105], v160, 1.0 op_sel:[1,1,0]
	v_pk_fma_f32 v[82:83], v[38:39], v[98:99], v[82:83] op_sel:[1,0,0] op_sel_hi:[1,1,1]
	v_pk_fma_f32 v[84:85], v[38:39], v[100:101], v[84:85] op_sel:[1,0,0] op_sel_hi:[1,1,1]
	v_pk_fma_f32 v[86:87], v[38:39], v[102:103], v[86:87] op_sel:[1,0,0] op_sel_hi:[1,1,1]
	v_pk_fma_f32 v[88:89], v[38:39], v[104:105], v[88:89] op_sel:[1,0,0] op_sel_hi:[1,1,1]
	v_cvt_scalef32_pk_f32_fp4 v[98:99], v161, 1.0
	v_cvt_scalef32_pk_f32_fp4 v[100:101], v161, 1.0 op_sel:[1,0,0]
	v_cvt_scalef32_pk_f32_fp4 v[102:103], v161, 1.0 op_sel:[0,1,0]
	v_cvt_scalef32_pk_f32_fp4 v[104:105], v161, 1.0 op_sel:[1,1,0]
	v_pk_fma_f32 v[90:91], v[38:39], v[98:99], v[90:91] op_sel:[1,0,0] op_sel_hi:[1,1,1]
	v_pk_fma_f32 v[92:93], v[38:39], v[100:101], v[92:93] op_sel:[1,0,0] op_sel_hi:[1,1,1]
	v_pk_fma_f32 v[94:95], v[38:39], v[102:103], v[94:95] op_sel:[1,0,0] op_sel_hi:[1,1,1]
	v_pk_fma_f32 v[96:97], v[38:39], v[104:105], v[96:97] op_sel:[1,0,0] op_sel_hi:[1,1,1]
	v_cvt_scalef32_pk_f32_fp4 v[98:99], v162, 1.0
	v_cvt_scalef32_pk_f32_fp4 v[100:101], v162, 1.0 op_sel:[1,0,0]
	v_cvt_scalef32_pk_f32_fp4 v[102:103], v162, 1.0 op_sel:[0,1,0]
	v_cvt_scalef32_pk_f32_fp4 v[104:105], v162, 1.0 op_sel:[1,1,0]
	v_pk_fma_f32 v[66:67], v[40:41], v[98:99], v[66:67] op_sel_hi:[0,1,1]
	v_pk_fma_f32 v[68:69], v[40:41], v[100:101], v[68:69] op_sel_hi:[0,1,1]
	v_pk_fma_f32 v[70:71], v[40:41], v[102:103], v[70:71] op_sel_hi:[0,1,1]
	v_pk_fma_f32 v[72:73], v[40:41], v[104:105], v[72:73] op_sel_hi:[0,1,1]
	v_cvt_scalef32_pk_f32_fp4 v[98:99], v163, 1.0
	v_cvt_scalef32_pk_f32_fp4 v[100:101], v163, 1.0 op_sel:[1,0,0]
	v_cvt_scalef32_pk_f32_fp4 v[102:103], v163, 1.0 op_sel:[0,1,0]
	v_cvt_scalef32_pk_f32_fp4 v[104:105], v163, 1.0 op_sel:[1,1,0]
	v_pk_fma_f32 v[74:75], v[40:41], v[98:99], v[74:75] op_sel_hi:[0,1,1]
	v_pk_fma_f32 v[76:77], v[40:41], v[100:101], v[76:77] op_sel_hi:[0,1,1]
	v_pk_fma_f32 v[78:79], v[40:41], v[102:103], v[78:79] op_sel_hi:[0,1,1]
	v_pk_fma_f32 v[80:81], v[40:41], v[104:105], v[80:81] op_sel_hi:[0,1,1]
	v_cvt_scalef32_pk_f32_fp4 v[98:99], v164, 1.0
	v_cvt_scalef32_pk_f32_fp4 v[100:101], v164, 1.0 op_sel:[1,0,0]
	v_cvt_scalef32_pk_f32_fp4 v[102:103], v164, 1.0 op_sel:[0,1,0]
	v_cvt_scalef32_pk_f32_fp4 v[104:105], v164, 1.0 op_sel:[1,1,0]
	v_pk_fma_f32 v[82:83], v[40:41], v[98:99], v[82:83] op_sel_hi:[0,1,1]
	v_pk_fma_f32 v[84:85], v[40:41], v[100:101], v[84:85] op_sel_hi:[0,1,1]
	v_pk_fma_f32 v[86:87], v[40:41], v[102:103], v[86:87] op_sel_hi:[0,1,1]
; __device__ __forceinline__ void phase_peer_v(const Params& p, int layer, int xs, int wid0, int wstride, bool last, char* smraw) {
;     ...
;         const f32x2 e0 = __builtin_amdgcn_cvt_scalef32_pk_f32_fp4(dw, 1.0f, 0), e1 = __builtin_amdgcn_cvt_scalef32_pk_f32_fp4(dw, 1.0f, 1);
;         const f32x2 e2 = __builtin_amdgcn_cvt_scalef32_pk_f32_fp4(dw, 1.0f, 2), e3 = __builtin_amdgcn_cvt_scalef32_pk_f32_fp4(dw, 1.0f, 3);
;         acc[8 * m + 0] += ci * e0[0]; acc[8 * m + 1] += ci * e0[1]; acc[8 * m + 2] += ci * e1[0]; acc[8 * m + 3] += ci * e1[1];
;         acc[8 * m + 4] += ci * e2[0]; acc[8 * m + 5] += ci * e2[1]; acc[8 * m + 6] += ci * e3[0]; acc[8 * m + 7] += ci * e3[1];
;       }
;     }
;   };
;   int tt = wid;
;   if (tt < TH) load_idx(tt);
;   while (tt < TH) {
;     const int tn = tt + wstride;
;     const int t = 2 * tt + par;
; #pragma unroll
;     for (int i = 0; i < 8; ++i) qA[i] = *(const u32x4*)(Vq + (ni[i >> 2][i & 3] * 128u + joff));
;     float* hq = hrow(p, t) + sl * 256 + 4 * l;
;     f32x4 hv = *(const f32x4*)hq;
;     const f32x4 c0 = nc[0], c1 = nc[1], c2 = nc[2], c3 = nc[3];
; #pragma unroll
;     for (int m = 0; m < 32; ++m) acc[m] = 0.f;
;     half_fma(qA, c0, c1);
; #pragma unroll
;     for (int i = 0; i < 8; ++i) qA[i] = *(const u32x4*)(Vq + (ni[2 + (i >> 2)][i & 3] * 128u + joff));
;     if (tn < TH) load_idx(tn);
;     half_fma(qA, c2, c3);
; #pragma unroll
;     for (int q4 = 0; q4 < 8; ++q4) *(f32x4*)(red + g * 256 + j * 32 + q4 * 4) = f32x4{acc[q4 * 4], acc[q4 * 4 + 1], acc[q4 * 4 + 2], acc[q4 * 4 + 3]};
;     __builtin_amdgcn_fence(__ATOMIC_RELEASE, "wavefront");
;     __builtin_amdgcn_wave_barrier();
;     __builtin_amdgcn_fence(__ATOMIC_ACQUIRE, "wavefront");
;     f32x4 r = {0.f, 0.f, 0.f, 0.f};
; #pragma unroll
;     for (int gg = 0; gg < 8; ++gg) { f32x4 v = *(const f32x4*)(red + gg * 256 + 4 * l); r += v; }
;     asm volatile("" ::: "memory");
;     __builtin_amdgcn_wave_barrier();
;     {
;       hv += r;
;       *(f32x4*)hq = hv;
;       if (!last) { u32x2 o; o[0] = cvtpk(hv[0], hv[1]); o[1] = cvtpk(hv[2], hv[3]); *(u32x2*)((char*)p.hb + ((unsigned)t * 2048u + (unsigned)(sl * 512 + l * 8))) = o; }
	v_pk_fma_f32 v[88:89], v[40:41], v[104:105], v[88:89] op_sel_hi:[0,1,1]
	v_cvt_scalef32_pk_f32_fp4 v[98:99], v165, 1.0
	v_cvt_scalef32_pk_f32_fp4 v[100:101], v165, 1.0 op_sel:[1,0,0]
	v_cvt_scalef32_pk_f32_fp4 v[102:103], v165, 1.0 op_sel:[0,1,0]
	v_cvt_scalef32_pk_f32_fp4 v[104:105], v165, 1.0 op_sel:[1,1,0]
	v_pk_fma_f32 v[90:91], v[40:41], v[98:99], v[90:91] op_sel_hi:[0,1,1]
	v_pk_fma_f32 v[92:93], v[40:41], v[100:101], v[92:93] op_sel_hi:[0,1,1]
	v_pk_fma_f32 v[94:95], v[40:41], v[102:103], v[94:95] op_sel_hi:[0,1,1]
	v_pk_fma_f32 v[96:97], v[40:41], v[104:105], v[96:97] op_sel_hi:[0,1,1]
	v_cvt_scalef32_pk_f32_fp4 v[98:99], v166, 1.0
	v_cvt_scalef32_pk_f32_fp4 v[100:101], v166, 1.0 op_sel:[1,0,0]
	v_cvt_scalef32_pk_f32_fp4 v[102:103], v166, 1.0 op_sel:[0,1,0]
	v_cvt_scalef32_pk_f32_fp4 v[104:105], v166, 1.0 op_sel:[1,1,0]
	v_pk_fma_f32 v[66:67], v[40:41], v[98:99], v[66:67] op_sel:[1,0,0] op_sel_hi:[1,1,1]
	v_pk_fma_f32 v[68:69], v[40:41], v[100:101], v[68:69] op_sel:[1,0,0] op_sel_hi:[1,1,1]
	v_pk_fma_f32 v[70:71], v[40:41], v[102:103], v[70:71] op_sel:[1,0,0] op_sel_hi:[1,1,1]
	v_pk_fma_f32 v[72:73], v[40:41], v[104:105], v[72:73] op_sel:[1,0,0] op_sel_hi:[1,1,1]
	v_cvt_scalef32_pk_f32_fp4 v[98:99], v167, 1.0
	v_cvt_scalef32_pk_f32_fp4 v[100:101], v167, 1.0 op_sel:[1,0,0]
	v_cvt_scalef32_pk_f32_fp4 v[102:103], v167, 1.0 op_sel:[0,1,0]
	v_cvt_scalef32_pk_f32_fp4 v[104:105], v167, 1.0 op_sel:[1,1,0]
	v_pk_fma_f32 v[74:75], v[40:41], v[98:99], v[74:75] op_sel:[1,0,0] op_sel_hi:[1,1,1]
	v_pk_fma_f32 v[76:77], v[40:41], v[100:101], v[76:77] op_sel:[1,0,0] op_sel_hi:[1,1,1]
	v_pk_fma_f32 v[78:79], v[40:41], v[102:103], v[78:79] op_sel:[1,0,0] op_sel_hi:[1,1,1]
	v_pk_fma_f32 v[80:81], v[40:41], v[104:105], v[80:81] op_sel:[1,0,0] op_sel_hi:[1,1,1]
	v_cvt_scalef32_pk_f32_fp4 v[98:99], v168, 1.0
	v_cvt_scalef32_pk_f32_fp4 v[100:101], v168, 1.0 op_sel:[1,0,0]
	v_cvt_scalef32_pk_f32_fp4 v[102:103], v168, 1.0 op_sel:[0,1,0]
	v_cvt_scalef32_pk_f32_fp4 v[104:105], v168, 1.0 op_sel:[1,1,0]
	v_pk_fma_f32 v[82:83], v[40:41], v[98:99], v[82:83] op_sel:[1,0,0] op_sel_hi:[1,1,1]
	v_pk_fma_f32 v[84:85], v[40:41], v[100:101], v[84:85] op_sel:[1,0,0] op_sel_hi:[1,1,1]
	v_pk_fma_f32 v[86:87], v[40:41], v[102:103], v[86:87] op_sel:[1,0,0] op_sel_hi:[1,1,1]
	v_pk_fma_f32 v[88:89], v[40:41], v[104:105], v[88:89] op_sel:[1,0,0] op_sel_hi:[1,1,1]
	v_cvt_scalef32_pk_f32_fp4 v[98:99], v169, 1.0
	v_cvt_scalef32_pk_f32_fp4 v[100:101], v169, 1.0 op_sel:[1,0,0]
	v_cvt_scalef32_pk_f32_fp4 v[102:103], v169, 1.0 op_sel:[0,1,0]
	v_cvt_scalef32_pk_f32_fp4 v[104:105], v169, 1.0 op_sel:[1,1,0]
	v_pk_fma_f32 v[90:91], v[40:41], v[98:99], v[90:91] op_sel:[1,0,0] op_sel_hi:[1,1,1]
	v_pk_fma_f32 v[92:93], v[40:41], v[100:101], v[92:93] op_sel:[1,0,0] op_sel_hi:[1,1,1]
	v_pk_fma_f32 v[94:95], v[40:41], v[102:103], v[94:95] op_sel:[1,0,0] op_sel_hi:[1,1,1]
	v_pk_fma_f32 v[96:97], v[40:41], v[104:105], v[96:97] op_sel:[1,0,0] op_sel_hi:[1,1,1]
	ds_write_b128 v240, v[66:69]
	ds_write_b128 v241, v[70:73]
	ds_write_b128 v242, v[74:77]
	ds_write_b128 v243, v[78:81]
	ds_write_b128 v244, v[82:85]
	ds_write_b128 v245, v[86:89]
	ds_write_b128 v246, v[90:93]
	ds_write_b128 v247, v[94:97]
	s_waitcnt lgkmcnt(0)
	ds_read_b128 v[66:69], v4
	ds_read_b128 v[70:73], v4 offset:1024
	ds_read_b128 v[74:77], v4 offset:2048
	ds_read_b128 v[78:81], v4 offset:3072
	ds_read_b128 v[82:85], v4 offset:4096
	ds_read_b128 v[86:89], v4 offset:5120
	ds_read_b128 v[90:93], v4 offset:6144
	ds_read_b128 v[94:97], v4 offset:7168
	s_waitcnt lgkmcnt(6)
	v_pk_add_f32 v[66:67], v[66:67], v[70:71]
	v_pk_add_f32 v[68:69], v[68:69], v[72:73]
	s_waitcnt lgkmcnt(5)
	v_pk_add_f32 v[66:67], v[66:67], v[74:75]
	v_pk_add_f32 v[68:69], v[68:69], v[76:77]
	s_waitcnt lgkmcnt(4)
	v_pk_add_f32 v[66:67], v[66:67], v[78:79]
	v_pk_add_f32 v[68:69], v[68:69], v[80:81]
	s_waitcnt lgkmcnt(3)
	v_pk_add_f32 v[66:67], v[66:67], v[82:83]
	v_pk_add_f32 v[68:69], v[68:69], v[84:85]
	s_waitcnt lgkmcnt(2)
	v_pk_add_f32 v[66:67], v[66:67], v[86:87]
	v_pk_add_f32 v[68:69], v[68:69], v[88:89]
	s_waitcnt lgkmcnt(1)
	v_pk_add_f32 v[66:67], v[66:67], v[90:91]
	v_pk_add_f32 v[68:69], v[68:69], v[92:93]
	s_waitcnt lgkmcnt(0)
	v_pk_add_f32 v[66:67], v[66:67], v[94:95]
	v_pk_add_f32 v[68:69], v[68:69], v[96:97]
	v_pk_add_f32 v[58:59], v[58:59], v[66:67]
	v_pk_add_f32 v[60:61], v[60:61], v[68:69]
	global_store_dwordx4 v0, v[58:61], s[44:45]
	s_mov_b32 s36, s51
	s_cmp_lt_u32 s36, s38
	s_cbranch_scc0 .Lmy_pv1_done

; __device__ __forceinline__ void phase_peer_v(const Params& p, int layer, int xs, int wid0, int wstride, bool last, char* smraw) {
;     ...
;   auto half_fma = [&](const u32x4 (&q)[8], const f32x4& c0, const f32x4& c1) {
; #pragma unroll
;     for (int i = 0; i < 8; ++i) {
;       const float ci = i < 4 ? c0[i & 3] : c1[i & 3];
; #pragma unroll
;       for (int m = 0; m < 4; ++m) {
;         unsigned dw = q[i][m];
;         asm volatile("" : "+v"(dw) : "v"(acc[(8 * m + 31) & 31]));
;         const f32x2 e0 = __builtin_amdgcn_cvt_scalef32_pk_f32_fp4(dw, 1.0f, 0), e1 = __builtin_amdgcn_cvt_scalef32_pk_f32_fp4(dw, 1.0f, 1);
;         const f32x2 e2 = __builtin_amdgcn_cvt_scalef32_pk_f32_fp4(dw, 1.0f, 2), e3 = __builtin_amdgcn_cvt_scalef32_pk_f32_fp4(dw, 1.0f, 3);
;         acc[8 * m + 0] += ci * e0[0]; acc[8 * m + 1] += ci * e0[1]; acc[8 * m + 2] += ci * e1[0]; acc[8 * m + 3] += ci * e1[1];
;         acc[8 * m + 4] += ci * e2[0]; acc[8 * m + 5] += ci * e2[1]; acc[8 * m + 6] += ci * e3[0]; acc[8 * m + 7] += ci * e3[1];
;       }
;     }
.Lmy_pv1_noissueB:
	v_cvt_scalef32_pk_f32_fp4 v[98:99], v170, 1.0
	v_cvt_scalef32_pk_f32_fp4 v[100:101], v170, 1.0 op_sel:[1,0,0]
	v_cvt_scalef32_pk_f32_fp4 v[102:103], v170, 1.0 op_sel:[0,1,0]
	v_cvt_scalef32_pk_f32_fp4 v[104:105], v170, 1.0 op_sel:[1,1,0]
	v_pk_fma_f32 v[66:67], v[42:43], v[98:99], 0 op_sel_hi:[0,1,0]
	v_pk_fma_f32 v[68:69], v[42:43], v[100:101], 0 op_sel_hi:[0,1,0]
	v_pk_fma_f32 v[70:71], v[42:43], v[102:103], 0 op_sel_hi:[0,1,0]
	v_pk_fma_f32 v[72:73], v[42:43], v[104:105], 0 op_sel_hi:[0,1,0]
	v_cvt_scalef32_pk_f32_fp4 v[98:99], v171, 1.0
	v_cvt_scalef32_pk_f32_fp4 v[100:101], v171, 1.0 op_sel:[1,0,0]
	v_cvt_scalef32_pk_f32_fp4 v[102:103], v171, 1.0 op_sel:[0,1,0]
	v_cvt_scalef32_pk_f32_fp4 v[104:105], v171, 1.0 op_sel:[1,1,0]
	v_pk_fma_f32 v[74:75], v[42:43], v[98:99], 0 op_sel_hi:[0,1,0]
	v_pk_fma_f32 v[76:77], v[42:43], v[100:101], 0 op_sel_hi:[0,1,0]
	v_pk_fma_f32 v[78:79], v[42:43], v[102:103], 0 op_sel_hi:[0,1,0]
	v_pk_fma_f32 v[80:81], v[42:43], v[104:105], 0 op_sel_hi:[0,1,0]
	v_cvt_scalef32_pk_f32_fp4 v[98:99], v172, 1.0
	v_cvt_scalef32_pk_f32_fp4 v[100:101], v172, 1.0 op_sel:[1,0,0]
	v_cvt_scalef32_pk_f32_fp4 v[102:103], v172, 1.0 op_sel:[0,1,0]
	v_cvt_scalef32_pk_f32_fp4 v[104:105], v172, 1.0 op_sel:[1,1,0]
	v_pk_fma_f32 v[82:83], v[42:43], v[98:99], 0 op_sel_hi:[0,1,0]
	v_pk_fma_f32 v[84:85], v[42:43], v[100:101], 0 op_sel_hi:[0,1,0]
	v_pk_fma_f32 v[86:87], v[42:43], v[102:103], 0 op_sel_hi:[0,1,0]
	v_pk_fma_f32 v[88:89], v[42:43], v[104:105], 0 op_sel_hi:[0,1,0]
	v_cvt_scalef32_pk_f32_fp4 v[98:99], v173, 1.0
	v_cvt_scalef32_pk_f32_fp4 v[100:101], v173, 1.0 op_sel:[1,0,0]
	v_cvt_scalef32_pk_f32_fp4 v[102:103], v173, 1.0 op_sel:[0,1,0]
	v_cvt_scalef32_pk_f32_fp4 v[104:105], v173, 1.0 op_sel:[1,1,0]
	v_pk_fma_f32 v[90:91], v[42:43], v[98:99], 0 op_sel_hi:[0,1,0]
	v_pk_fma_f32 v[92:93], v[42:43], v[100:101], 0 op_sel_hi:[0,1,0]
	v_pk_fma_f32 v[94:95], v[42:43], v[102:103], 0 op_sel_hi:[0,1,0]
	v_pk_fma_f32 v[96:97], v[42:43], v[104:105], 0 op_sel_hi:[0,1,0]
	v_cvt_scalef32_pk_f32_fp4 v[98:99], v174, 1.0
	v_cvt_scalef32_pk_f32_fp4 v[100:101], v174, 1.0 op_sel:[1,0,0]
	v_cvt_scalef32_pk_f32_fp4 v[102:103], v174, 1.0 op_sel:[0,1,0]
	v_cvt_scalef32_pk_f32_fp4 v[104:105], v174, 1.0 op_sel:[1,1,0]
	v_pk_fma_f32 v[66:67], v[42:43], v[98:99], v[66:67] op_sel:[1,0,0] op_sel_hi:[1,1,1]
	v_pk_fma_f32 v[68:69], v[42:43], v[100:101], v[68:69] op_sel:[1,0,0] op_sel_hi:[1,1,1]
	v_pk_fma_f32 v[70:71], v[42:43], v[102:103], v[70:71] op_sel:[1,0,0] op_sel_hi:[1,1,1]
	v_pk_fma_f32 v[72:73], v[42:43], v[104:105], v[72:73] op_sel:[1,0,0] op_sel_hi:[1,1,1]
	v_cvt_scalef32_pk_f32_fp4 v[98:99], v175, 1.0
	v_cvt_scalef32_pk_f32_fp4 v[100:101], v175, 1.0 op_sel:[1,0,0]
	v_cvt_scalef32_pk_f32_fp4 v[102:103], v175, 1.0 op_sel:[0,1,0]
	v_cvt_scalef32_pk_f32_fp4 v[104:105], v175, 1.0 op_sel:[1,1,0]
	v_pk_fma_f32 v[74:75], v[42:43], v[98:99], v[74:75] op_sel:[1,0,0] op_sel_hi:[1,1,1]
	v_pk_fma_f32 v[76:77], v[42:43], v[100:101], v[76:77] op_sel:[1,0,0] op_sel_hi:[1,1,1]
	v_pk_fma_f32 v[78:79], v[42:43], v[102:103], v[78:79] op_sel:[1,0,0] op_sel_hi:[1,1,1]
	v_pk_fma_f32 v[80:81], v[42:43], v[104:105], v[80:81] op_sel:[1,0,0] op_sel_hi:[1,1,1]
	v_cvt_scalef32_pk_f32_fp4 v[98:99], v176, 1.0
	v_cvt_scalef32_pk_f32_fp4 v[100:101], v176, 1.0 op_sel:[1,0,0]
	v_cvt_scalef32_pk_f32_fp4 v[102:103], v176, 1.0 op_sel:[0,1,0]
	v_cvt_scalef32_pk_f32_fp4 v[104:105], v176, 1.0 op_sel:[1,1,0]
	v_pk_fma_f32 v[82:83], v[42:43], v[98:99], v[82:83] op_sel:[1,0,0] op_sel_hi:[1,1,1]
	v_pk_fma_f32 v[84:85], v[42:43], v[100:101], v[84:85] op_sel:[1,0,0] op_sel_hi:[1,1,1]
	v_pk_fma_f32 v[86:87], v[42:43], v[102:103], v[86:87] op_sel:[1,0,0] op_sel_hi:[1,1,1]
	v_pk_fma_f32 v[88:89], v[42:43], v[104:105], v[88:89] op_sel:[1,0,0] op_sel_hi:[1,1,1]
	v_cvt_scalef32_pk_f32_fp4 v[98:99], v177, 1.0
	v_cvt_scalef32_pk_f32_fp4 v[100:101], v177, 1.0 op_sel:[1,0,0]
	v_cvt_scalef32_pk_f32_fp4 v[102:103], v177, 1.0 op_sel:[0,1,0]
	v_cvt_scalef32_pk_f32_fp4 v[104:105], v177, 1.0 op_sel:[1,1,0]
	v_pk_fma_f32 v[90:91], v[42:43], v[98:99], v[90:91] op_sel:[1,0,0] op_sel_hi:[1,1,1]
	v_pk_fma_f32 v[92:93], v[42:43], v[100:101], v[92:93] op_sel:[1,0,0] op_sel_hi:[1,1,1]
	v_pk_fma_f32 v[94:95], v[42:43], v[102:103], v[94:95] op_sel:[1,0,0] op_sel_hi:[1,1,1]
	v_pk_fma_f32 v[96:97], v[42:43], v[104:105], v[96:97] op_sel:[1,0,0] op_sel_hi:[1,1,1]
	v_cvt_scalef32_pk_f32_fp4 v[98:99], v178, 1.0
	v_cvt_scalef32_pk_f32_fp4 v[100:101], v178, 1.0 op_sel:[1,0,0]
	v_cvt_scalef32_pk_f32_fp4 v[102:103], v178, 1.0 op_sel:[0,1,0]
	v_cvt_scalef32_pk_f32_fp4 v[104:105], v178, 1.0 op_sel:[1,1,0]
	v_pk_fma_f32 v[66:67], v[44:45], v[98:99], v[66:67] op_sel_hi:[0,1,1]
	v_pk_fma_f32 v[68:69], v[44:45], v[100:101], v[68:69] op_sel_hi:[0,1,1]
	v_pk_fma_f32 v[70:71], v[44:45], v[102:103], v[70:71] op_sel_hi:[0,1,1]
	v_pk_fma_f32 v[72:73], v[44:45], v[104:105], v[72:73] op_sel_hi:[0,1,1]
	v_cvt_scalef32_pk_f32_fp4 v[98:99], v179, 1.0
	v_cvt_scalef32_pk_f32_fp4 v[100:101], v179, 1.0 op_sel:[1,0,0]
	v_cvt_scalef32_pk_f32_fp4 v[102:103], v179, 1.0 op_sel:[0,1,0]
	v_cvt_scalef32_pk_f32_fp4 v[104:105], v179, 1.0 op_sel:[1,1,0]
	v_pk_fma_f32 v[74:75], v[44:45], v[98:99], v[74:75] op_sel_hi:[0,1,1]
	v_pk_fma_f32 v[76:77], v[44:45], v[100:101], v[76:77] op_sel_hi:[0,1,1]
	v_pk_fma_f32 v[78:79], v[44:45], v[102:103], v[78:79] op_sel_hi:[0,1,1]
	v_pk_fma_f32 v[80:81], v[44:45], v[104:105], v[80:81] op_sel_hi:[0,1,1]
	v_cvt_scalef32_pk_f32_fp4 v[98:99], v180, 1.0
	v_cvt_scalef32_pk_f32_fp4 v[100:101], v180, 1.0 op_sel:[1,0,0]
	v_cvt_scalef32_pk_f32_fp4 v[102:103], v180, 1.0 op_sel:[0,1,0]
; __device__ __forceinline__ void phase_peer_v(const Params& p, int layer, int xs, int wid0, int wstride, bool last, char* smraw) {
;     ...
;   auto half_fma = [&](const u32x4 (&q)[8], const f32x4& c0, const f32x4& c1) {
; #pragma unroll
;     for (int i = 0; i < 8; ++i) {
;       const float ci = i < 4 ? c0[i & 3] : c1[i & 3];
; #pragma unroll
;       for (int m = 0; m < 4; ++m) {
;         unsigned dw = q[i][m];
;         asm volatile("" : "+v"(dw) : "v"(acc[(8 * m + 31) & 31]));
;         const f32x2 e0 = __builtin_amdgcn_cvt_scalef32_pk_f32_fp4(dw, 1.0f, 0), e1 = __builtin_amdgcn_cvt_scalef32_pk_f32_fp4(dw, 1.0f, 1);
;         const f32x2 e2 = __builtin_amdgcn_cvt_scalef32_pk_f32_fp4(dw, 1.0f, 2), e3 = __builtin_amdgcn_cvt_scalef32_pk_f32_fp4(dw, 1.0f, 3);
;         acc[8 * m + 0] += ci * e0[0]; acc[8 * m + 1] += ci * e0[1]; acc[8 * m + 2] += ci * e1[0]; acc[8 * m + 3] += ci * e1[1];
;         acc[8 * m + 4] += ci * e2[0]; acc[8 * m + 5] += ci * e2[1]; acc[8 * m + 6] += ci * e3[0]; acc[8 * m + 7] += ci * e3[1];
;       }
;     }
	v_cvt_scalef32_pk_f32_fp4 v[104:105], v180, 1.0 op_sel:[1,1,0]
	v_pk_fma_f32 v[82:83], v[44:45], v[98:99], v[82:83] op_sel_hi:[0,1,1]
	v_pk_fma_f32 v[84:85], v[44:45], v[100:101], v[84:85] op_sel_hi:[0,1,1]
	v_pk_fma_f32 v[86:87], v[44:45], v[102:103], v[86:87] op_sel_hi:[0,1,1]
	v_pk_fma_f32 v[88:89], v[44:45], v[104:105], v[88:89] op_sel_hi:[0,1,1]
	v_cvt_scalef32_pk_f32_fp4 v[98:99], v181, 1.0
	v_cvt_scalef32_pk_f32_fp4 v[100:101], v181, 1.0 op_sel:[1,0,0]
	v_cvt_scalef32_pk_f32_fp4 v[102:103], v181, 1.0 op_sel:[0,1,0]
	v_cvt_scalef32_pk_f32_fp4 v[104:105], v181, 1.0 op_sel:[1,1,0]
	v_pk_fma_f32 v[90:91], v[44:45], v[98:99], v[90:91] op_sel_hi:[0,1,1]
	v_pk_fma_f32 v[92:93], v[44:45], v[100:101], v[92:93] op_sel_hi:[0,1,1]
	v_pk_fma_f32 v[94:95], v[44:45], v[102:103], v[94:95] op_sel_hi:[0,1,1]
	v_pk_fma_f32 v[96:97], v[44:45], v[104:105], v[96:97] op_sel_hi:[0,1,1]
	v_cvt_scalef32_pk_f32_fp4 v[98:99], v182, 1.0
	v_cvt_scalef32_pk_f32_fp4 v[100:101], v182, 1.0 op_sel:[1,0,0]
	v_cvt_scalef32_pk_f32_fp4 v[102:103], v182, 1.0 op_sel:[0,1,0]
	v_cvt_scalef32_pk_f32_fp4 v[104:105], v182, 1.0 op_sel:[1,1,0]
	v_pk_fma_f32 v[66:67], v[44:45], v[98:99], v[66:67] op_sel:[1,0,0] op_sel_hi:[1,1,1]
	v_pk_fma_f32 v[68:69], v[44:45], v[100:101], v[68:69] op_sel:[1,0,0] op_sel_hi:[1,1,1]
	v_pk_fma_f32 v[70:71], v[44:45], v[102:103], v[70:71] op_sel:[1,0,0] op_sel_hi:[1,1,1]
	v_pk_fma_f32 v[72:73], v[44:45], v[104:105], v[72:73] op_sel:[1,0,0] op_sel_hi:[1,1,1]
	v_cvt_scalef32_pk_f32_fp4 v[98:99], v183, 1.0
	v_cvt_scalef32_pk_f32_fp4 v[100:101], v183, 1.0 op_sel:[1,0,0]
	v_cvt_scalef32_pk_f32_fp4 v[102:103], v183, 1.0 op_sel:[0,1,0]
	v_cvt_scalef32_pk_f32_fp4 v[104:105], v183, 1.0 op_sel:[1,1,0]
	v_pk_fma_f32 v[74:75], v[44:45], v[98:99], v[74:75] op_sel:[1,0,0] op_sel_hi:[1,1,1]
	v_pk_fma_f32 v[76:77], v[44:45], v[100:101], v[76:77] op_sel:[1,0,0] op_sel_hi:[1,1,1]
	v_pk_fma_f32 v[78:79], v[44:45], v[102:103], v[78:79] op_sel:[1,0,0] op_sel_hi:[1,1,1]
	v_pk_fma_f32 v[80:81], v[44:45], v[104:105], v[80:81] op_sel:[1,0,0] op_sel_hi:[1,1,1]
	v_cvt_scalef32_pk_f32_fp4 v[98:99], v184, 1.0
	v_cvt_scalef32_pk_f32_fp4 v[100:101], v184, 1.0 op_sel:[1,0,0]
	v_cvt_scalef32_pk_f32_fp4 v[102:103], v184, 1.0 op_sel:[0,1,0]
	v_cvt_scalef32_pk_f32_fp4 v[104:105], v184, 1.0 op_sel:[1,1,0]
	v_pk_fma_f32 v[82:83], v[44:45], v[98:99], v[82:83] op_sel:[1,0,0] op_sel_hi:[1,1,1]
	v_pk_fma_f32 v[84:85], v[44:45], v[100:101], v[84:85] op_sel:[1,0,0] op_sel_hi:[1,1,1]
	v_pk_fma_f32 v[86:87], v[44:45], v[102:103], v[86:87] op_sel:[1,0,0] op_sel_hi:[1,1,1]
	v_pk_fma_f32 v[88:89], v[44:45], v[104:105], v[88:89] op_sel:[1,0,0] op_sel_hi:[1,1,1]
	v_cvt_scalef32_pk_f32_fp4 v[98:99], v185, 1.0
	v_cvt_scalef32_pk_f32_fp4 v[100:101], v185, 1.0 op_sel:[1,0,0]
	v_cvt_scalef32_pk_f32_fp4 v[102:103], v185, 1.0 op_sel:[0,1,0]
	v_cvt_scalef32_pk_f32_fp4 v[104:105], v185, 1.0 op_sel:[1,1,0]
	v_pk_fma_f32 v[90:91], v[44:45], v[98:99], v[90:91] op_sel:[1,0,0] op_sel_hi:[1,1,1]
	v_pk_fma_f32 v[92:93], v[44:45], v[100:101], v[92:93] op_sel:[1,0,0] op_sel_hi:[1,1,1]
	v_pk_fma_f32 v[94:95], v[44:45], v[102:103], v[94:95] op_sel:[1,0,0] op_sel_hi:[1,1,1]
	v_pk_fma_f32 v[96:97], v[44:45], v[104:105], v[96:97] op_sel:[1,0,0] op_sel_hi:[1,1,1]
	v_cvt_scalef32_pk_f32_fp4 v[98:99], v192, 1.0
	v_cvt_scalef32_pk_f32_fp4 v[100:101], v192, 1.0 op_sel:[1,0,0]
	v_cvt_scalef32_pk_f32_fp4 v[102:103], v192, 1.0 op_sel:[0,1,0]
	v_cvt_scalef32_pk_f32_fp4 v[104:105], v192, 1.0 op_sel:[1,1,0]
	v_pk_fma_f32 v[66:67], v[46:47], v[98:99], v[66:67] op_sel_hi:[0,1,1]
	v_pk_fma_f32 v[68:69], v[46:47], v[100:101], v[68:69] op_sel_hi:[0,1,1]
	v_pk_fma_f32 v[70:71], v[46:47], v[102:103], v[70:71] op_sel_hi:[0,1,1]
	v_pk_fma_f32 v[72:73], v[46:47], v[104:105], v[72:73] op_sel_hi:[0,1,1]
	v_cvt_scalef32_pk_f32_fp4 v[98:99], v193, 1.0
	v_cvt_scalef32_pk_f32_fp4 v[100:101], v193, 1.0 op_sel:[1,0,0]
	v_cvt_scalef32_pk_f32_fp4 v[102:103], v193, 1.0 op_sel:[0,1,0]
	v_cvt_scalef32_pk_f32_fp4 v[104:105], v193, 1.0 op_sel:[1,1,0]
	v_pk_fma_f32 v[74:75], v[46:47], v[98:99], v[74:75] op_sel_hi:[0,1,1]
	v_pk_fma_f32 v[76:77], v[46:47], v[100:101], v[76:77] op_sel_hi:[0,1,1]
	v_pk_fma_f32 v[78:79], v[46:47], v[102:103], v[78:79] op_sel_hi:[0,1,1]
	v_pk_fma_f32 v[80:81], v[46:47], v[104:105], v[80:81] op_sel_hi:[0,1,1]
	v_cvt_scalef32_pk_f32_fp4 v[98:99], v194, 1.0
	v_cvt_scalef32_pk_f32_fp4 v[100:101], v194, 1.0 op_sel:[1,0,0]
	v_cvt_scalef32_pk_f32_fp4 v[102:103], v194, 1.0 op_sel:[0,1,0]
	v_cvt_scalef32_pk_f32_fp4 v[104:105], v194, 1.0 op_sel:[1,1,0]
	v_pk_fma_f32 v[82:83], v[46:47], v[98:99], v[82:83] op_sel_hi:[0,1,1]
	v_pk_fma_f32 v[84:85], v[46:47], v[100:101], v[84:85] op_sel_hi:[0,1,1]
	v_pk_fma_f32 v[86:87], v[46:47], v[102:103], v[86:87] op_sel_hi:[0,1,1]
	v_pk_fma_f32 v[88:89], v[46:47], v[104:105], v[88:89] op_sel_hi:[0,1,1]
	v_cvt_scalef32_pk_f32_fp4 v[98:99], v195, 1.0
	v_cvt_scalef32_pk_f32_fp4 v[100:101], v195, 1.0 op_sel:[1,0,0]
	v_cvt_scalef32_pk_f32_fp4 v[102:103], v195, 1.0 op_sel:[0,1,0]
	v_cvt_scalef32_pk_f32_fp4 v[104:105], v195, 1.0 op_sel:[1,1,0]
	v_pk_fma_f32 v[90:91], v[46:47], v[98:99], v[90:91] op_sel_hi:[0,1,1]
	v_pk_fma_f32 v[92:93], v[46:47], v[100:101], v[92:93] op_sel_hi:[0,1,1]
	v_pk_fma_f32 v[94:95], v[46:47], v[102:103], v[94:95] op_sel_hi:[0,1,1]
	v_pk_fma_f32 v[96:97], v[46:47], v[104:105], v[96:97] op_sel_hi:[0,1,1]
	v_cvt_scalef32_pk_f32_fp4 v[98:99], v196, 1.0
	v_cvt_scalef32_pk_f32_fp4 v[100:101], v196, 1.0 op_sel:[1,0,0]
	v_cvt_scalef32_pk_f32_fp4 v[102:103], v196, 1.0 op_sel:[0,1,0]
	v_cvt_scalef32_pk_f32_fp4 v[104:105], v196, 1.0 op_sel:[1,1,0]
	v_pk_fma_f32 v[66:67], v[46:47], v[98:99], v[66:67] op_sel:[1,0,0] op_sel_hi:[1,1,1]
; __device__ __forceinline__ void phase_peer_v(const Params& p, int layer, int xs, int wid0, int wstride, bool last, char* smraw) {
;     ...
;   auto half_fma = [&](const u32x4 (&q)[8], const f32x4& c0, const f32x4& c1) {
; #pragma unroll
;     for (int i = 0; i < 8; ++i) {
;       const float ci = i < 4 ? c0[i & 3] : c1[i & 3];
; #pragma unroll
;       for (int m = 0; m < 4; ++m) {
;         unsigned dw = q[i][m];
;         asm volatile("" : "+v"(dw) : "v"(acc[(8 * m + 31) & 31]));
;         const f32x2 e0 = __builtin_amdgcn_cvt_scalef32_pk_f32_fp4(dw, 1.0f, 0), e1 = __builtin_amdgcn_cvt_scalef32_pk_f32_fp4(dw, 1.0f, 1);
;         const f32x2 e2 = __builtin_amdgcn_cvt_scalef32_pk_f32_fp4(dw, 1.0f, 2), e3 = __builtin_amdgcn_cvt_scalef32_pk_f32_fp4(dw, 1.0f, 3);
;         acc[8 * m + 0] += ci * e0[0]; acc[8 * m + 1] += ci * e0[1]; acc[8 * m + 2] += ci * e1[0]; acc[8 * m + 3] += ci * e1[1];
;         acc[8 * m + 4] += ci * e2[0]; acc[8 * m + 5] += ci * e2[1]; acc[8 * m + 6] += ci * e3[0]; acc[8 * m + 7] += ci * e3[1];
;       }
;     }
	v_pk_fma_f32 v[68:69], v[46:47], v[100:101], v[68:69] op_sel:[1,0,0] op_sel_hi:[1,1,1]
	v_pk_fma_f32 v[70:71], v[46:47], v[102:103], v[70:71] op_sel:[1,0,0] op_sel_hi:[1,1,1]
	v_pk_fma_f32 v[72:73], v[46:47], v[104:105], v[72:73] op_sel:[1,0,0] op_sel_hi:[1,1,1]
	v_cvt_scalef32_pk_f32_fp4 v[98:99], v197, 1.0
	v_cvt_scalef32_pk_f32_fp4 v[100:101], v197, 1.0 op_sel:[1,0,0]
	v_cvt_scalef32_pk_f32_fp4 v[102:103], v197, 1.0 op_sel:[0,1,0]
	v_cvt_scalef32_pk_f32_fp4 v[104:105], v197, 1.0 op_sel:[1,1,0]
	v_pk_fma_f32 v[74:75], v[46:47], v[98:99], v[74:75] op_sel:[1,0,0] op_sel_hi:[1,1,1]
	v_pk_fma_f32 v[76:77], v[46:47], v[100:101], v[76:77] op_sel:[1,0,0] op_sel_hi:[1,1,1]
	v_pk_fma_f32 v[78:79], v[46:47], v[102:103], v[78:79] op_sel:[1,0,0] op_sel_hi:[1,1,1]
	v_pk_fma_f32 v[80:81], v[46:47], v[104:105], v[80:81] op_sel:[1,0,0] op_sel_hi:[1,1,1]
	v_cvt_scalef32_pk_f32_fp4 v[98:99], v198, 1.0
	v_cvt_scalef32_pk_f32_fp4 v[100:101], v198, 1.0 op_sel:[1,0,0]
	v_cvt_scalef32_pk_f32_fp4 v[102:103], v198, 1.0 op_sel:[0,1,0]
	v_cvt_scalef32_pk_f32_fp4 v[104:105], v198, 1.0 op_sel:[1,1,0]
	v_pk_fma_f32 v[82:83], v[46:47], v[98:99], v[82:83] op_sel:[1,0,0] op_sel_hi:[1,1,1]
	v_pk_fma_f32 v[84:85], v[46:47], v[100:101], v[84:85] op_sel:[1,0,0] op_sel_hi:[1,1,1]
	v_pk_fma_f32 v[86:87], v[46:47], v[102:103], v[86:87] op_sel:[1,0,0] op_sel_hi:[1,1,1]
	v_pk_fma_f32 v[88:89], v[46:47], v[104:105], v[88:89] op_sel:[1,0,0] op_sel_hi:[1,1,1]
	v_cvt_scalef32_pk_f32_fp4 v[98:99], v199, 1.0
	v_cvt_scalef32_pk_f32_fp4 v[100:101], v199, 1.0 op_sel:[1,0,0]
	v_cvt_scalef32_pk_f32_fp4 v[102:103], v199, 1.0 op_sel:[0,1,0]
	v_cvt_scalef32_pk_f32_fp4 v[104:105], v199, 1.0 op_sel:[1,1,0]
	v_pk_fma_f32 v[90:91], v[46:47], v[98:99], v[90:91] op_sel:[1,0,0] op_sel_hi:[1,1,1]
	v_pk_fma_f32 v[92:93], v[46:47], v[100:101], v[92:93] op_sel:[1,0,0] op_sel_hi:[1,1,1]
	v_pk_fma_f32 v[94:95], v[46:47], v[102:103], v[94:95] op_sel:[1,0,0] op_sel_hi:[1,1,1]
	v_pk_fma_f32 v[96:97], v[46:47], v[104:105], v[96:97] op_sel:[1,0,0] op_sel_hi:[1,1,1]
	v_cvt_scalef32_pk_f32_fp4 v[98:99], v200, 1.0
	v_cvt_scalef32_pk_f32_fp4 v[100:101], v200, 1.0 op_sel:[1,0,0]
	v_cvt_scalef32_pk_f32_fp4 v[102:103], v200, 1.0 op_sel:[0,1,0]
	v_cvt_scalef32_pk_f32_fp4 v[104:105], v200, 1.0 op_sel:[1,1,0]
	v_pk_fma_f32 v[66:67], v[48:49], v[98:99], v[66:67] op_sel_hi:[0,1,1]
	v_pk_fma_f32 v[68:69], v[48:49], v[100:101], v[68:69] op_sel_hi:[0,1,1]
	v_pk_fma_f32 v[70:71], v[48:49], v[102:103], v[70:71] op_sel_hi:[0,1,1]
	v_pk_fma_f32 v[72:73], v[48:49], v[104:105], v[72:73] op_sel_hi:[0,1,1]
	v_cvt_scalef32_pk_f32_fp4 v[98:99], v201, 1.0
	v_cvt_scalef32_pk_f32_fp4 v[100:101], v201, 1.0 op_sel:[1,0,0]
	v_cvt_scalef32_pk_f32_fp4 v[102:103], v201, 1.0 op_sel:[0,1,0]
	v_cvt_scalef32_pk_f32_fp4 v[104:105], v201, 1.0 op_sel:[1,1,0]
	v_pk_fma_f32 v[74:75], v[48:49], v[98:99], v[74:75] op_sel_hi:[0,1,1]
	v_pk_fma_f32 v[76:77], v[48:49], v[100:101], v[76:77] op_sel_hi:[0,1,1]
	v_pk_fma_f32 v[78:79], v[48:49], v[102:103], v[78:79] op_sel_hi:[0,1,1]
	v_pk_fma_f32 v[80:81], v[48:49], v[104:105], v[80:81] op_sel_hi:[0,1,1]
	v_cvt_scalef32_pk_f32_fp4 v[98:99], v202, 1.0
	v_cvt_scalef32_pk_f32_fp4 v[100:101], v202, 1.0 op_sel:[1,0,0]
	v_cvt_scalef32_pk_f32_fp4 v[102:103], v202, 1.0 op_sel:[0,1,0]
	v_cvt_scalef32_pk_f32_fp4 v[104:105], v202, 1.0 op_sel:[1,1,0]
	v_pk_fma_f32 v[82:83], v[48:49], v[98:99], v[82:83] op_sel_hi:[0,1,1]
	v_pk_fma_f32 v[84:85], v[48:49], v[100:101], v[84:85] op_sel_hi:[0,1,1]
	v_pk_fma_f32 v[86:87], v[48:49], v[102:103], v[86:87] op_sel_hi:[0,1,1]
	v_pk_fma_f32 v[88:89], v[48:49], v[104:105], v[88:89] op_sel_hi:[0,1,1]
	v_cvt_scalef32_pk_f32_fp4 v[98:99], v203, 1.0
	v_cvt_scalef32_pk_f32_fp4 v[100:101], v203, 1.0 op_sel:[1,0,0]
	v_cvt_scalef32_pk_f32_fp4 v[102:103], v203, 1.0 op_sel:[0,1,0]
	v_cvt_scalef32_pk_f32_fp4 v[104:105], v203, 1.0 op_sel:[1,1,0]
	v_pk_fma_f32 v[90:91], v[48:49], v[98:99], v[90:91] op_sel_hi:[0,1,1]
	v_pk_fma_f32 v[92:93], v[48:49], v[100:101], v[92:93] op_sel_hi:[0,1,1]
	v_pk_fma_f32 v[94:95], v[48:49], v[102:103], v[94:95] op_sel_hi:[0,1,1]
	v_pk_fma_f32 v[96:97], v[48:49], v[104:105], v[96:97] op_sel_hi:[0,1,1]
	v_cvt_scalef32_pk_f32_fp4 v[98:99], v204, 1.0
	v_cvt_scalef32_pk_f32_fp4 v[100:101], v204, 1.0 op_sel:[1,0,0]
	v_cvt_scalef32_pk_f32_fp4 v[102:103], v204, 1.0 op_sel:[0,1,0]
	v_cvt_scalef32_pk_f32_fp4 v[104:105], v204, 1.0 op_sel:[1,1,0]
	v_pk_fma_f32 v[66:67], v[48:49], v[98:99], v[66:67] op_sel:[1,0,0] op_sel_hi:[1,1,1]
	v_pk_fma_f32 v[68:69], v[48:49], v[100:101], v[68:69] op_sel:[1,0,0] op_sel_hi:[1,1,1]
	v_pk_fma_f32 v[70:71], v[48:49], v[102:103], v[70:71] op_sel:[1,0,0] op_sel_hi:[1,1,1]
	v_pk_fma_f32 v[72:73], v[48:49], v[104:105], v[72:73] op_sel:[1,0,0] op_sel_hi:[1,1,1]
	v_cvt_scalef32_pk_f32_fp4 v[98:99], v205, 1.0
	v_cvt_scalef32_pk_f32_fp4 v[100:101], v205, 1.0 op_sel:[1,0,0]
	v_cvt_scalef32_pk_f32_fp4 v[102:103], v205, 1.0 op_sel:[0,1,0]
	v_cvt_scalef32_pk_f32_fp4 v[104:105], v205, 1.0 op_sel:[1,1,0]
	v_pk_fma_f32 v[74:75], v[48:49], v[98:99], v[74:75] op_sel:[1,0,0] op_sel_hi:[1,1,1]
	v_pk_fma_f32 v[76:77], v[48:49], v[100:101], v[76:77] op_sel:[1,0,0] op_sel_hi:[1,1,1]
	v_pk_fma_f32 v[78:79], v[48:49], v[102:103], v[78:79] op_sel:[1,0,0] op_sel_hi:[1,1,1]
	v_pk_fma_f32 v[80:81], v[48:49], v[104:105], v[80:81] op_sel:[1,0,0] op_sel_hi:[1,1,1]
	v_cvt_scalef32_pk_f32_fp4 v[98:99], v206, 1.0
	v_cvt_scalef32_pk_f32_fp4 v[100:101], v206, 1.0 op_sel:[1,0,0]
	v_cvt_scalef32_pk_f32_fp4 v[102:103], v206, 1.0 op_sel:[0,1,0]
	v_cvt_scalef32_pk_f32_fp4 v[104:105], v206, 1.0 op_sel:[1,1,0]
	v_pk_fma_f32 v[82:83], v[48:49], v[98:99], v[82:83] op_sel:[1,0,0] op_sel_hi:[1,1,1]
; __device__ __forceinline__ void phase_peer_v(const Params& p, int layer, int xs, int wid0, int wstride, bool last, char* smraw) {
;     ...
;   auto half_fma = [&](const u32x4 (&q)[8], const f32x4& c0, const f32x4& c1) {
; #pragma unroll
;     for (int i = 0; i < 8; ++i) {
;       const float ci = i < 4 ? c0[i & 3] : c1[i & 3];
; #pragma unroll
;       for (int m = 0; m < 4; ++m) {
;         unsigned dw = q[i][m];
;         asm volatile("" : "+v"(dw) : "v"(acc[(8 * m + 31) & 31]));
;         const f32x2 e0 = __builtin_amdgcn_cvt_scalef32_pk_f32_fp4(dw, 1.0f, 0), e1 = __builtin_amdgcn_cvt_scalef32_pk_f32_fp4(dw, 1.0f, 1);
;         const f32x2 e2 = __builtin_amdgcn_cvt_scalef32_pk_f32_fp4(dw, 1.0f, 2), e3 = __builtin_amdgcn_cvt_scalef32_pk_f32_fp4(dw, 1.0f, 3);
;         acc[8 * m + 0] += ci * e0[0]; acc[8 * m + 1] += ci * e0[1]; acc[8 * m + 2] += ci * e1[0]; acc[8 * m + 3] += ci * e1[1];
;         acc[8 * m + 4] += ci * e2[0]; acc[8 * m + 5] += ci * e2[1]; acc[8 * m + 6] += ci * e3[0]; acc[8 * m + 7] += ci * e3[1];
;       }
;     }
	v_pk_fma_f32 v[84:85], v[48:49], v[100:101], v[84:85] op_sel:[1,0,0] op_sel_hi:[1,1,1]
	v_pk_fma_f32 v[86:87], v[48:49], v[102:103], v[86:87] op_sel:[1,0,0] op_sel_hi:[1,1,1]
	v_pk_fma_f32 v[88:89], v[48:49], v[104:105], v[88:89] op_sel:[1,0,0] op_sel_hi:[1,1,1]
	v_cvt_scalef32_pk_f32_fp4 v[98:99], v207, 1.0
	v_cvt_scalef32_pk_f32_fp4 v[100:101], v207, 1.0 op_sel:[1,0,0]
	v_cvt_scalef32_pk_f32_fp4 v[102:103], v207, 1.0 op_sel:[0,1,0]
	v_cvt_scalef32_pk_f32_fp4 v[104:105], v207, 1.0 op_sel:[1,1,0]
	v_pk_fma_f32 v[90:91], v[48:49], v[98:99], v[90:91] op_sel:[1,0,0] op_sel_hi:[1,1,1]
	v_pk_fma_f32 v[92:93], v[48:49], v[100:101], v[92:93] op_sel:[1,0,0] op_sel_hi:[1,1,1]
	v_pk_fma_f32 v[94:95], v[48:49], v[102:103], v[94:95] op_sel:[1,0,0] op_sel_hi:[1,1,1]
	v_pk_fma_f32 v[96:97], v[48:49], v[104:105], v[96:97] op_sel:[1,0,0] op_sel_hi:[1,1,1]
	v_cvt_scalef32_pk_f32_fp4 v[98:99], v208, 1.0
	v_cvt_scalef32_pk_f32_fp4 v[100:101], v208, 1.0 op_sel:[1,0,0]
	v_cvt_scalef32_pk_f32_fp4 v[102:103], v208, 1.0 op_sel:[0,1,0]
	v_cvt_scalef32_pk_f32_fp4 v[104:105], v208, 1.0 op_sel:[1,1,0]
	v_pk_fma_f32 v[66:67], v[50:51], v[98:99], v[66:67] op_sel_hi:[0,1,1]
	v_pk_fma_f32 v[68:69], v[50:51], v[100:101], v[68:69] op_sel_hi:[0,1,1]
	v_pk_fma_f32 v[70:71], v[50:51], v[102:103], v[70:71] op_sel_hi:[0,1,1]
	v_pk_fma_f32 v[72:73], v[50:51], v[104:105], v[72:73] op_sel_hi:[0,1,1]
	v_cvt_scalef32_pk_f32_fp4 v[98:99], v209, 1.0
	v_cvt_scalef32_pk_f32_fp4 v[100:101], v209, 1.0 op_sel:[1,0,0]
	v_cvt_scalef32_pk_f32_fp4 v[102:103], v209, 1.0 op_sel:[0,1,0]
	v_cvt_scalef32_pk_f32_fp4 v[104:105], v209, 1.0 op_sel:[1,1,0]
	v_pk_fma_f32 v[74:75], v[50:51], v[98:99], v[74:75] op_sel_hi:[0,1,1]
	v_pk_fma_f32 v[76:77], v[50:51], v[100:101], v[76:77] op_sel_hi:[0,1,1]
	v_pk_fma_f32 v[78:79], v[50:51], v[102:103], v[78:79] op_sel_hi:[0,1,1]
	v_pk_fma_f32 v[80:81], v[50:51], v[104:105], v[80:81] op_sel_hi:[0,1,1]
	v_cvt_scalef32_pk_f32_fp4 v[98:99], v210, 1.0
	v_cvt_scalef32_pk_f32_fp4 v[100:101], v210, 1.0 op_sel:[1,0,0]
	v_cvt_scalef32_pk_f32_fp4 v[102:103], v210, 1.0 op_sel:[0,1,0]
	v_cvt_scalef32_pk_f32_fp4 v[104:105], v210, 1.0 op_sel:[1,1,0]
	v_pk_fma_f32 v[82:83], v[50:51], v[98:99], v[82:83] op_sel_hi:[0,1,1]
	v_pk_fma_f32 v[84:85], v[50:51], v[100:101], v[84:85] op_sel_hi:[0,1,1]
	v_pk_fma_f32 v[86:87], v[50:51], v[102:103], v[86:87] op_sel_hi:[0,1,1]
	v_pk_fma_f32 v[88:89], v[50:51], v[104:105], v[88:89] op_sel_hi:[0,1,1]
	v_cvt_scalef32_pk_f32_fp4 v[98:99], v211, 1.0
	v_cvt_scalef32_pk_f32_fp4 v[100:101], v211, 1.0 op_sel:[1,0,0]
	v_cvt_scalef32_pk_f32_fp4 v[102:103], v211, 1.0 op_sel:[0,1,0]
	v_cvt_scalef32_pk_f32_fp4 v[104:105], v211, 1.0 op_sel:[1,1,0]
	v_pk_fma_f32 v[90:91], v[50:51], v[98:99], v[90:91] op_sel_hi:[0,1,1]
	v_pk_fma_f32 v[92:93], v[50:51], v[100:101], v[92:93] op_sel_hi:[0,1,1]
	v_pk_fma_f32 v[94:95], v[50:51], v[102:103], v[94:95] op_sel_hi:[0,1,1]
	v_pk_fma_f32 v[96:97], v[50:51], v[104:105], v[96:97] op_sel_hi:[0,1,1]
	v_cvt_scalef32_pk_f32_fp4 v[98:99], v212, 1.0
	v_cvt_scalef32_pk_f32_fp4 v[100:101], v212, 1.0 op_sel:[1,0,0]
	v_cvt_scalef32_pk_f32_fp4 v[102:103], v212, 1.0 op_sel:[0,1,0]
	v_cvt_scalef32_pk_f32_fp4 v[104:105], v212, 1.0 op_sel:[1,1,0]
	v_pk_fma_f32 v[66:67], v[50:51], v[98:99], v[66:67] op_sel:[1,0,0] op_sel_hi:[1,1,1]
	v_pk_fma_f32 v[68:69], v[50:51], v[100:101], v[68:69] op_sel:[1,0,0] op_sel_hi:[1,1,1]
	v_pk_fma_f32 v[70:71], v[50:51], v[102:103], v[70:71] op_sel:[1,0,0] op_sel_hi:[1,1,1]
	v_pk_fma_f32 v[72:73], v[50:51], v[104:105], v[72:73] op_sel:[1,0,0] op_sel_hi:[1,1,1]
	v_cvt_scalef32_pk_f32_fp4 v[98:99], v213, 1.0
	v_cvt_scalef32_pk_f32_fp4 v[100:101], v213, 1.0 op_sel:[1,0,0]
	v_cvt_scalef32_pk_f32_fp4 v[102:103], v213, 1.0 op_sel:[0,1,0]
	v_cvt_scalef32_pk_f32_fp4 v[104:105], v213, 1.0 op_sel:[1,1,0]
	v_pk_fma_f32 v[74:75], v[50:51], v[98:99], v[74:75] op_sel:[1,0,0] op_sel_hi:[1,1,1]
	v_pk_fma_f32 v[76:77], v[50:51], v[100:101], v[76:77] op_sel:[1,0,0] op_sel_hi:[1,1,1]
	v_pk_fma_f32 v[78:79], v[50:51], v[102:103], v[78:79] op_sel:[1,0,0] op_sel_hi:[1,1,1]
	v_pk_fma_f32 v[80:81], v[50:51], v[104:105], v[80:81] op_sel:[1,0,0] op_sel_hi:[1,1,1]
	v_cvt_scalef32_pk_f32_fp4 v[98:99], v214, 1.0
	v_cvt_scalef32_pk_f32_fp4 v[100:101], v214, 1.0 op_sel:[1,0,0]
	v_cvt_scalef32_pk_f32_fp4 v[102:103], v214, 1.0 op_sel:[0,1,0]
	v_cvt_scalef32_pk_f32_fp4 v[104:105], v214, 1.0 op_sel:[1,1,0]
	v_pk_fma_f32 v[82:83], v[50:51], v[98:99], v[82:83] op_sel:[1,0,0] op_sel_hi:[1,1,1]
	v_pk_fma_f32 v[84:85], v[50:51], v[100:101], v[84:85] op_sel:[1,0,0] op_sel_hi:[1,1,1]
	v_pk_fma_f32 v[86:87], v[50:51], v[102:103], v[86:87] op_sel:[1,0,0] op_sel_hi:[1,1,1]
	v_pk_fma_f32 v[88:89], v[50:51], v[104:105], v[88:89] op_sel:[1,0,0] op_sel_hi:[1,1,1]
	v_cvt_scalef32_pk_f32_fp4 v[98:99], v215, 1.0
	v_cvt_scalef32_pk_f32_fp4 v[100:101], v215, 1.0 op_sel:[1,0,0]
	v_cvt_scalef32_pk_f32_fp4 v[102:103], v215, 1.0 op_sel:[0,1,0]
	v_cvt_scalef32_pk_f32_fp4 v[104:105], v215, 1.0 op_sel:[1,1,0]
	v_pk_fma_f32 v[90:91], v[50:51], v[98:99], v[90:91] op_sel:[1,0,0] op_sel_hi:[1,1,1]
	v_pk_fma_f32 v[92:93], v[50:51], v[100:101], v[92:93] op_sel:[1,0,0] op_sel_hi:[1,1,1]
	v_pk_fma_f32 v[94:95], v[50:51], v[102:103], v[94:95] op_sel:[1,0,0] op_sel_hi:[1,1,1]
	v_pk_fma_f32 v[96:97], v[50:51], v[104:105], v[96:97] op_sel:[1,0,0] op_sel_hi:[1,1,1]
	v_cvt_scalef32_pk_f32_fp4 v[98:99], v216, 1.0
	v_cvt_scalef32_pk_f32_fp4 v[100:101], v216, 1.0 op_sel:[1,0,0]
	v_cvt_scalef32_pk_f32_fp4 v[102:103], v216, 1.0 op_sel:[0,1,0]
	v_cvt_scalef32_pk_f32_fp4 v[104:105], v216, 1.0 op_sel:[1,1,0]
	v_pk_fma_f32 v[66:67], v[52:53], v[98:99], v[66:67] op_sel_hi:[0,1,1]
; __device__ __forceinline__ void phase_peer_v(const Params& p, int layer, int xs, int wid0, int wstride, bool last, char* smraw) {
;     ...
;   auto half_fma = [&](const u32x4 (&q)[8], const f32x4& c0, const f32x4& c1) {
; #pragma unroll
;     for (int i = 0; i < 8; ++i) {
;       const float ci = i < 4 ? c0[i & 3] : c1[i & 3];
; #pragma unroll
;       for (int m = 0; m < 4; ++m) {
;         unsigned dw = q[i][m];
;         asm volatile("" : "+v"(dw) : "v"(acc[(8 * m + 31) & 31]));
;         const f32x2 e0 = __builtin_amdgcn_cvt_scalef32_pk_f32_fp4(dw, 1.0f, 0), e1 = __builtin_amdgcn_cvt_scalef32_pk_f32_fp4(dw, 1.0f, 1);
;         const f32x2 e2 = __builtin_amdgcn_cvt_scalef32_pk_f32_fp4(dw, 1.0f, 2), e3 = __builtin_amdgcn_cvt_scalef32_pk_f32_fp4(dw, 1.0f, 3);
;         acc[8 * m + 0] += ci * e0[0]; acc[8 * m + 1] += ci * e0[1]; acc[8 * m + 2] += ci * e1[0]; acc[8 * m + 3] += ci * e1[1];
;         acc[8 * m + 4] += ci * e2[0]; acc[8 * m + 5] += ci * e2[1]; acc[8 * m + 6] += ci * e3[0]; acc[8 * m + 7] += ci * e3[1];
;       }
;     }
	v_pk_fma_f32 v[68:69], v[52:53], v[100:101], v[68:69] op_sel_hi:[0,1,1]
	v_pk_fma_f32 v[70:71], v[52:53], v[102:103], v[70:71] op_sel_hi:[0,1,1]
	v_pk_fma_f32 v[72:73], v[52:53], v[104:105], v[72:73] op_sel_hi:[0,1,1]
	v_cvt_scalef32_pk_f32_fp4 v[98:99], v217, 1.0
	v_cvt_scalef32_pk_f32_fp4 v[100:101], v217, 1.0 op_sel:[1,0,0]
	v_cvt_scalef32_pk_f32_fp4 v[102:103], v217, 1.0 op_sel:[0,1,0]
	v_cvt_scalef32_pk_f32_fp4 v[104:105], v217, 1.0 op_sel:[1,1,0]
	v_pk_fma_f32 v[74:75], v[52:53], v[98:99], v[74:75] op_sel_hi:[0,1,1]
	v_pk_fma_f32 v[76:77], v[52:53], v[100:101], v[76:77] op_sel_hi:[0,1,1]
	v_pk_fma_f32 v[78:79], v[52:53], v[102:103], v[78:79] op_sel_hi:[0,1,1]
	v_pk_fma_f32 v[80:81], v[52:53], v[104:105], v[80:81] op_sel_hi:[0,1,1]
	v_cvt_scalef32_pk_f32_fp4 v[98:99], v218, 1.0
	v_cvt_scalef32_pk_f32_fp4 v[100:101], v218, 1.0 op_sel:[1,0,0]
	v_cvt_scalef32_pk_f32_fp4 v[102:103], v218, 1.0 op_sel:[0,1,0]
	v_cvt_scalef32_pk_f32_fp4 v[104:105], v218, 1.0 op_sel:[1,1,0]
	v_pk_fma_f32 v[82:83], v[52:53], v[98:99], v[82:83] op_sel_hi:[0,1,1]
	v_pk_fma_f32 v[84:85], v[52:53], v[100:101], v[84:85] op_sel_hi:[0,1,1]
	v_pk_fma_f32 v[86:87], v[52:53], v[102:103], v[86:87] op_sel_hi:[0,1,1]
	v_pk_fma_f32 v[88:89], v[52:53], v[104:105], v[88:89] op_sel_hi:[0,1,1]
	v_cvt_scalef32_pk_f32_fp4 v[98:99], v219, 1.0
	v_cvt_scalef32_pk_f32_fp4 v[100:101], v219, 1.0 op_sel:[1,0,0]
	v_cvt_scalef32_pk_f32_fp4 v[102:103], v219, 1.0 op_sel:[0,1,0]
	v_cvt_scalef32_pk_f32_fp4 v[104:105], v219, 1.0 op_sel:[1,1,0]
	v_pk_fma_f32 v[90:91], v[52:53], v[98:99], v[90:91] op_sel_hi:[0,1,1]
	v_pk_fma_f32 v[92:93], v[52:53], v[100:101], v[92:93] op_sel_hi:[0,1,1]
	v_pk_fma_f32 v[94:95], v[52:53], v[102:103], v[94:95] op_sel_hi:[0,1,1]
	v_pk_fma_f32 v[96:97], v[52:53], v[104:105], v[96:97] op_sel_hi:[0,1,1]
	v_cvt_scalef32_pk_f32_fp4 v[98:99], v220, 1.0
	v_cvt_scalef32_pk_f32_fp4 v[100:101], v220, 1.0 op_sel:[1,0,0]
	v_cvt_scalef32_pk_f32_fp4 v[102:103], v220, 1.0 op_sel:[0,1,0]
	v_cvt_scalef32_pk_f32_fp4 v[104:105], v220, 1.0 op_sel:[1,1,0]
	v_pk_fma_f32 v[66:67], v[52:53], v[98:99], v[66:67] op_sel:[1,0,0] op_sel_hi:[1,1,1]
	v_pk_fma_f32 v[68:69], v[52:53], v[100:101], v[68:69] op_sel:[1,0,0] op_sel_hi:[1,1,1]
	v_pk_fma_f32 v[70:71], v[52:53], v[102:103], v[70:71] op_sel:[1,0,0] op_sel_hi:[1,1,1]
	v_pk_fma_f32 v[72:73], v[52:53], v[104:105], v[72:73] op_sel:[1,0,0] op_sel_hi:[1,1,1]
	v_cvt_scalef32_pk_f32_fp4 v[98:99], v221, 1.0
	v_cvt_scalef32_pk_f32_fp4 v[100:101], v221, 1.0 op_sel:[1,0,0]
	v_cvt_scalef32_pk_f32_fp4 v[102:103], v221, 1.0 op_sel:[0,1,0]
	v_cvt_scalef32_pk_f32_fp4 v[104:105], v221, 1.0 op_sel:[1,1,0]
	v_pk_fma_f32 v[74:75], v[52:53], v[98:99], v[74:75] op_sel:[1,0,0] op_sel_hi:[1,1,1]
	v_pk_fma_f32 v[76:77], v[52:53], v[100:101], v[76:77] op_sel:[1,0,0] op_sel_hi:[1,1,1]
	v_pk_fma_f32 v[78:79], v[52:53], v[102:103], v[78:79] op_sel:[1,0,0] op_sel_hi:[1,1,1]
	v_pk_fma_f32 v[80:81], v[52:53], v[104:105], v[80:81] op_sel:[1,0,0] op_sel_hi:[1,1,1]
	v_cvt_scalef32_pk_f32_fp4 v[98:99], v222, 1.0
	v_cvt_scalef32_pk_f32_fp4 v[100:101], v222, 1.0 op_sel:[1,0,0]
	v_cvt_scalef32_pk_f32_fp4 v[102:103], v222, 1.0 op_sel:[0,1,0]
	v_cvt_scalef32_pk_f32_fp4 v[104:105], v222, 1.0 op_sel:[1,1,0]
	v_pk_fma_f32 v[82:83], v[52:53], v[98:99], v[82:83] op_sel:[1,0,0] op_sel_hi:[1,1,1]
	v_pk_fma_f32 v[84:85], v[52:53], v[100:101], v[84:85] op_sel:[1,0,0] op_sel_hi:[1,1,1]
	v_pk_fma_f32 v[86:87], v[52:53], v[102:103], v[86:87] op_sel:[1,0,0] op_sel_hi:[1,1,1]
	v_pk_fma_f32 v[88:89], v[52:53], v[104:105], v[88:89] op_sel:[1,0,0] op_sel_hi:[1,1,1]
	v_cvt_scalef32_pk_f32_fp4 v[98:99], v223, 1.0
	v_cvt_scalef32_pk_f32_fp4 v[100:101], v223, 1.0 op_sel:[1,0,0]
	v_cvt_scalef32_pk_f32_fp4 v[102:103], v223, 1.0 op_sel:[0,1,0]
	v_cvt_scalef32_pk_f32_fp4 v[104:105], v223, 1.0 op_sel:[1,1,0]
	v_pk_fma_f32 v[90:91], v[52:53], v[98:99], v[90:91] op_sel:[1,0,0] op_sel_hi:[1,1,1]
	v_pk_fma_f32 v[92:93], v[52:53], v[100:101], v[92:93] op_sel:[1,0,0] op_sel_hi:[1,1,1]
	v_pk_fma_f32 v[94:95], v[52:53], v[102:103], v[94:95] op_sel:[1,0,0] op_sel_hi:[1,1,1]
	v_pk_fma_f32 v[96:97], v[52:53], v[104:105], v[96:97] op_sel:[1,0,0] op_sel_hi:[1,1,1]
	v_cvt_scalef32_pk_f32_fp4 v[98:99], v224, 1.0
	v_cvt_scalef32_pk_f32_fp4 v[100:101], v224, 1.0 op_sel:[1,0,0]
	v_cvt_scalef32_pk_f32_fp4 v[102:103], v224, 1.0 op_sel:[0,1,0]
	v_cvt_scalef32_pk_f32_fp4 v[104:105], v224, 1.0 op_sel:[1,1,0]
	v_pk_fma_f32 v[66:67], v[54:55], v[98:99], v[66:67] op_sel_hi:[0,1,1]
	v_pk_fma_f32 v[68:69], v[54:55], v[100:101], v[68:69] op_sel_hi:[0,1,1]
	v_pk_fma_f32 v[70:71], v[54:55], v[102:103], v[70:71] op_sel_hi:[0,1,1]
	v_pk_fma_f32 v[72:73], v[54:55], v[104:105], v[72:73] op_sel_hi:[0,1,1]
	v_cvt_scalef32_pk_f32_fp4 v[98:99], v225, 1.0
	v_cvt_scalef32_pk_f32_fp4 v[100:101], v225, 1.0 op_sel:[1,0,0]
	v_cvt_scalef32_pk_f32_fp4 v[102:103], v225, 1.0 op_sel:[0,1,0]
	v_cvt_scalef32_pk_f32_fp4 v[104:105], v225, 1.0 op_sel:[1,1,0]
	v_pk_fma_f32 v[74:75], v[54:55], v[98:99], v[74:75] op_sel_hi:[0,1,1]
	v_pk_fma_f32 v[76:77], v[54:55], v[100:101], v[76:77] op_sel_hi:[0,1,1]
	v_pk_fma_f32 v[78:79], v[54:55], v[102:103], v[78:79] op_sel_hi:[0,1,1]
	v_pk_fma_f32 v[80:81], v[54:55], v[104:105], v[80:81] op_sel_hi:[0,1,1]
	v_cvt_scalef32_pk_f32_fp4 v[98:99], v226, 1.0
	v_cvt_scalef32_pk_f32_fp4 v[100:101], v226, 1.0 op_sel:[1,0,0]
	v_cvt_scalef32_pk_f32_fp4 v[102:103], v226, 1.0 op_sel:[0,1,0]
	v_cvt_scalef32_pk_f32_fp4 v[104:105], v226, 1.0 op_sel:[1,1,0]
	v_pk_fma_f32 v[82:83], v[54:55], v[98:99], v[82:83] op_sel_hi:[0,1,1]
	v_pk_fma_f32 v[84:85], v[54:55], v[100:101], v[84:85] op_sel_hi:[0,1,1]
	v_pk_fma_f32 v[86:87], v[54:55], v[102:103], v[86:87] op_sel_hi:[0,1,1]
; __device__ __forceinline__ void phase_peer_v(const Params& p, int layer, int xs, int wid0, int wstride, bool last, char* smraw) {
;     ...
;   auto half_fma = [&](const u32x4 (&q)[8], const f32x4& c0, const f32x4& c1) {
; #pragma unroll
;     for (int i = 0; i < 8; ++i) {
;       const float ci = i < 4 ? c0[i & 3] : c1[i & 3];
; #pragma unroll
;       for (int m = 0; m < 4; ++m) {
;         unsigned dw = q[i][m];
;         asm volatile("" : "+v"(dw) : "v"(acc[(8 * m + 31) & 31]));
;         const f32x2 e0 = __builtin_amdgcn_cvt_scalef32_pk_f32_fp4(dw, 1.0f, 0), e1 = __builtin_amdgcn_cvt_scalef32_pk_f32_fp4(dw, 1.0f, 1);
;         const f32x2 e2 = __builtin_amdgcn_cvt_scalef32_pk_f32_fp4(dw, 1.0f, 2), e3 = __builtin_amdgcn_cvt_scalef32_pk_f32_fp4(dw, 1.0f, 3);
;         acc[8 * m + 0] += ci * e0[0]; acc[8 * m + 1] += ci * e0[1]; acc[8 * m + 2] += ci * e1[0]; acc[8 * m + 3] += ci * e1[1];
;         acc[8 * m + 4] += ci * e2[0]; acc[8 * m + 5] += ci * e2[1]; acc[8 * m + 6] += ci * e3[0]; acc[8 * m + 7] += ci * e3[1];
;       }
;     }
	v_pk_fma_f32 v[88:89], v[54:55], v[104:105], v[88:89] op_sel_hi:[0,1,1]
	v_cvt_scalef32_pk_f32_fp4 v[98:99], v227, 1.0
	v_cvt_scalef32_pk_f32_fp4 v[100:101], v227, 1.0 op_sel:[1,0,0]
	v_cvt_scalef32_pk_f32_fp4 v[102:103], v227, 1.0 op_sel:[0,1,0]
	v_cvt_scalef32_pk_f32_fp4 v[104:105], v227, 1.0 op_sel:[1,1,0]
	v_pk_fma_f32 v[90:91], v[54:55], v[98:99], v[90:91] op_sel_hi:[0,1,1]
	v_pk_fma_f32 v[92:93], v[54:55], v[100:101], v[92:93] op_sel_hi:[0,1,1]
	v_pk_fma_f32 v[94:95], v[54:55], v[102:103], v[94:95] op_sel_hi:[0,1,1]
	v_pk_fma_f32 v[96:97], v[54:55], v[104:105], v[96:97] op_sel_hi:[0,1,1]
	v_cvt_scalef32_pk_f32_fp4 v[98:99], v228, 1.0
	v_cvt_scalef32_pk_f32_fp4 v[100:101], v228, 1.0 op_sel:[1,0,0]
	v_cvt_scalef32_pk_f32_fp4 v[102:103], v228, 1.0 op_sel:[0,1,0]
	v_cvt_scalef32_pk_f32_fp4 v[104:105], v228, 1.0 op_sel:[1,1,0]
	v_pk_fma_f32 v[66:67], v[54:55], v[98:99], v[66:67] op_sel:[1,0,0] op_sel_hi:[1,1,1]
	v_pk_fma_f32 v[68:69], v[54:55], v[100:101], v[68:69] op_sel:[1,0,0] op_sel_hi:[1,1,1]
	v_pk_fma_f32 v[70:71], v[54:55], v[102:103], v[70:71] op_sel:[1,0,0] op_sel_hi:[1,1,1]
	v_pk_fma_f32 v[72:73], v[54:55], v[104:105], v[72:73] op_sel:[1,0,0] op_sel_hi:[1,1,1]
	v_cvt_scalef32_pk_f32_fp4 v[98:99], v229, 1.0
	v_cvt_scalef32_pk_f32_fp4 v[100:101], v229, 1.0 op_sel:[1,0,0]
	v_cvt_scalef32_pk_f32_fp4 v[102:103], v229, 1.0 op_sel:[0,1,0]
	v_cvt_scalef32_pk_f32_fp4 v[104:105], v229, 1.0 op_sel:[1,1,0]
	v_pk_fma_f32 v[74:75], v[54:55], v[98:99], v[74:75] op_sel:[1,0,0] op_sel_hi:[1,1,1]
	v_pk_fma_f32 v[76:77], v[54:55], v[100:101], v[76:77] op_sel:[1,0,0] op_sel_hi:[1,1,1]
	v_pk_fma_f32 v[78:79], v[54:55], v[102:103], v[78:79] op_sel:[1,0,0] op_sel_hi:[1,1,1]
	v_pk_fma_f32 v[80:81], v[54:55], v[104:105], v[80:81] op_sel:[1,0,0] op_sel_hi:[1,1,1]
	v_cvt_scalef32_pk_f32_fp4 v[98:99], v230, 1.0
	v_cvt_scalef32_pk_f32_fp4 v[100:101], v230, 1.0 op_sel:[1,0,0]
	v_cvt_scalef32_pk_f32_fp4 v[102:103], v230, 1.0 op_sel:[0,1,0]
	v_cvt_scalef32_pk_f32_fp4 v[104:105], v230, 1.0 op_sel:[1,1,0]
	v_pk_fma_f32 v[82:83], v[54:55], v[98:99], v[82:83] op_sel:[1,0,0] op_sel_hi:[1,1,1]
	v_pk_fma_f32 v[84:85], v[54:55], v[100:101], v[84:85] op_sel:[1,0,0] op_sel_hi:[1,1,1]
	v_pk_fma_f32 v[86:87], v[54:55], v[102:103], v[86:87] op_sel:[1,0,0] op_sel_hi:[1,1,1]
	v_pk_fma_f32 v[88:89], v[54:55], v[104:105], v[88:89] op_sel:[1,0,0] op_sel_hi:[1,1,1]
	v_cvt_scalef32_pk_f32_fp4 v[98:99], v231, 1.0
	v_cvt_scalef32_pk_f32_fp4 v[100:101], v231, 1.0 op_sel:[1,0,0]
	v_cvt_scalef32_pk_f32_fp4 v[102:103], v231, 1.0 op_sel:[0,1,0]
	v_cvt_scalef32_pk_f32_fp4 v[104:105], v231, 1.0 op_sel:[1,1,0]
	v_pk_fma_f32 v[90:91], v[54:55], v[98:99], v[90:91] op_sel:[1,0,0] op_sel_hi:[1,1,1]
	v_pk_fma_f32 v[92:93], v[54:55], v[100:101], v[92:93] op_sel:[1,0,0] op_sel_hi:[1,1,1]
	v_pk_fma_f32 v[94:95], v[54:55], v[102:103], v[94:95] op_sel:[1,0,0] op_sel_hi:[1,1,1]
	v_pk_fma_f32 v[96:97], v[54:55], v[104:105], v[96:97] op_sel:[1,0,0] op_sel_hi:[1,1,1]
	v_cvt_scalef32_pk_f32_fp4 v[98:99], v232, 1.0
	v_cvt_scalef32_pk_f32_fp4 v[100:101], v232, 1.0 op_sel:[1,0,0]
	v_cvt_scalef32_pk_f32_fp4 v[102:103], v232, 1.0 op_sel:[0,1,0]
	v_cvt_scalef32_pk_f32_fp4 v[104:105], v232, 1.0 op_sel:[1,1,0]
	v_pk_fma_f32 v[66:67], v[56:57], v[98:99], v[66:67] op_sel_hi:[0,1,1]
	v_pk_fma_f32 v[68:69], v[56:57], v[100:101], v[68:69] op_sel_hi:[0,1,1]
	v_pk_fma_f32 v[70:71], v[56:57], v[102:103], v[70:71] op_sel_hi:[0,1,1]
	v_pk_fma_f32 v[72:73], v[56:57], v[104:105], v[72:73] op_sel_hi:[0,1,1]
	v_cvt_scalef32_pk_f32_fp4 v[98:99], v233, 1.0
	v_cvt_scalef32_pk_f32_fp4 v[100:101], v233, 1.0 op_sel:[1,0,0]
	v_cvt_scalef32_pk_f32_fp4 v[102:103], v233, 1.0 op_sel:[0,1,0]
	v_cvt_scalef32_pk_f32_fp4 v[104:105], v233, 1.0 op_sel:[1,1,0]
	v_pk_fma_f32 v[74:75], v[56:57], v[98:99], v[74:75] op_sel_hi:[0,1,1]
	v_pk_fma_f32 v[76:77], v[56:57], v[100:101], v[76:77] op_sel_hi:[0,1,1]
	v_pk_fma_f32 v[78:79], v[56:57], v[102:103], v[78:79] op_sel_hi:[0,1,1]
	v_pk_fma_f32 v[80:81], v[56:57], v[104:105], v[80:81] op_sel_hi:[0,1,1]
	v_cvt_scalef32_pk_f32_fp4 v[98:99], v234, 1.0
	v_cvt_scalef32_pk_f32_fp4 v[100:101], v234, 1.0 op_sel:[1,0,0]
	v_cvt_scalef32_pk_f32_fp4 v[102:103], v234, 1.0 op_sel:[0,1,0]
	v_cvt_scalef32_pk_f32_fp4 v[104:105], v234, 1.0 op_sel:[1,1,0]
	v_pk_fma_f32 v[82:83], v[56:57], v[98:99], v[82:83] op_sel_hi:[0,1,1]
	v_pk_fma_f32 v[84:85], v[56:57], v[100:101], v[84:85] op_sel_hi:[0,1,1]
	v_pk_fma_f32 v[86:87], v[56:57], v[102:103], v[86:87] op_sel_hi:[0,1,1]
; __device__ __forceinline__ void phase_peer_v(const Params& p, int layer, int xs, int wid0, int wstride, bool last, char* smraw) {
;     ...
;         const f32x2 e0 = __builtin_amdgcn_cvt_scalef32_pk_f32_fp4(dw, 1.0f, 0), e1 = __builtin_amdgcn_cvt_scalef32_pk_f32_fp4(dw, 1.0f, 1);
;         const f32x2 e2 = __builtin_amdgcn_cvt_scalef32_pk_f32_fp4(dw, 1.0f, 2), e3 = __builtin_amdgcn_cvt_scalef32_pk_f32_fp4(dw, 1.0f, 3);
;         acc[8 * m + 0] += ci * e0[0]; acc[8 * m + 1] += ci * e0[1]; acc[8 * m + 2] += ci * e1[0]; acc[8 * m + 3] += ci * e1[1];
;         acc[8 * m + 4] += ci * e2[0]; acc[8 * m + 5] += ci * e2[1]; acc[8 * m + 6] += ci * e3[0]; acc[8 * m + 7] += ci * e3[1];
;       }
;     }
;   };
;   int tt = wid;
;   if (tt < TH) load_idx(tt);
;   while (tt < TH) {
;     const int tn = tt + wstride;
;     const int t = 2 * tt + par;
; #pragma unroll
;     for (int i = 0; i < 8; ++i) qA[i] = *(const u32x4*)(Vq + (ni[i >> 2][i & 3] * 128u + joff));
;     float* hq = hrow(p, t) + sl * 256 + 4 * l;
;     f32x4 hv = *(const f32x4*)hq;
;     const f32x4 c0 = nc[0], c1 = nc[1], c2 = nc[2], c3 = nc[3];
; #pragma unroll
;     for (int m = 0; m < 32; ++m) acc[m] = 0.f;
;     half_fma(qA, c0, c1);
; #pragma unroll
;     for (int i = 0; i < 8; ++i) qA[i] = *(const u32x4*)(Vq + (ni[2 + (i >> 2)][i & 3] * 128u + joff));
;     if (tn < TH) load_idx(tn);
;     half_fma(qA, c2, c3);
; #pragma unroll
;     for (int q4 = 0; q4 < 8; ++q4) *(f32x4*)(red + g * 256 + j * 32 + q4 * 4) = f32x4{acc[q4 * 4], acc[q4 * 4 + 1], acc[q4 * 4 + 2], acc[q4 * 4 + 3]};
;     __builtin_amdgcn_fence(__ATOMIC_RELEASE, "wavefront");
;     __builtin_amdgcn_wave_barrier();
;     __builtin_amdgcn_fence(__ATOMIC_ACQUIRE, "wavefront");
;     f32x4 r = {0.f, 0.f, 0.f, 0.f};
; #pragma unroll
;     for (int gg = 0; gg < 8; ++gg) { f32x4 v = *(const f32x4*)(red + gg * 256 + 4 * l); r += v; }
;     asm volatile("" ::: "memory");
;     __builtin_amdgcn_wave_barrier();
;     {
;       hv += r;
;       *(f32x4*)hq = hv;
	v_pk_fma_f32 v[88:89], v[56:57], v[104:105], v[88:89] op_sel_hi:[0,1,1]
	v_cvt_scalef32_pk_f32_fp4 v[98:99], v235, 1.0
	v_cvt_scalef32_pk_f32_fp4 v[100:101], v235, 1.0 op_sel:[1,0,0]
	v_cvt_scalef32_pk_f32_fp4 v[102:103], v235, 1.0 op_sel:[0,1,0]
	v_cvt_scalef32_pk_f32_fp4 v[104:105], v235, 1.0 op_sel:[1,1,0]
	v_pk_fma_f32 v[90:91], v[56:57], v[98:99], v[90:91] op_sel_hi:[0,1,1]
	v_pk_fma_f32 v[92:93], v[56:57], v[100:101], v[92:93] op_sel_hi:[0,1,1]
	v_pk_fma_f32 v[94:95], v[56:57], v[102:103], v[94:95] op_sel_hi:[0,1,1]
	v_pk_fma_f32 v[96:97], v[56:57], v[104:105], v[96:97] op_sel_hi:[0,1,1]
	v_cvt_scalef32_pk_f32_fp4 v[98:99], v236, 1.0
	v_cvt_scalef32_pk_f32_fp4 v[100:101], v236, 1.0 op_sel:[1,0,0]
	v_cvt_scalef32_pk_f32_fp4 v[102:103], v236, 1.0 op_sel:[0,1,0]
	v_cvt_scalef32_pk_f32_fp4 v[104:105], v236, 1.0 op_sel:[1,1,0]
	v_pk_fma_f32 v[66:67], v[56:57], v[98:99], v[66:67] op_sel:[1,0,0] op_sel_hi:[1,1,1]
	v_pk_fma_f32 v[68:69], v[56:57], v[100:101], v[68:69] op_sel:[1,0,0] op_sel_hi:[1,1,1]
	v_pk_fma_f32 v[70:71], v[56:57], v[102:103], v[70:71] op_sel:[1,0,0] op_sel_hi:[1,1,1]
	v_pk_fma_f32 v[72:73], v[56:57], v[104:105], v[72:73] op_sel:[1,0,0] op_sel_hi:[1,1,1]
	v_cvt_scalef32_pk_f32_fp4 v[98:99], v237, 1.0
	v_cvt_scalef32_pk_f32_fp4 v[100:101], v237, 1.0 op_sel:[1,0,0]
	v_cvt_scalef32_pk_f32_fp4 v[102:103], v237, 1.0 op_sel:[0,1,0]
	v_cvt_scalef32_pk_f32_fp4 v[104:105], v237, 1.0 op_sel:[1,1,0]
	v_pk_fma_f32 v[74:75], v[56:57], v[98:99], v[74:75] op_sel:[1,0,0] op_sel_hi:[1,1,1]
	v_pk_fma_f32 v[76:77], v[56:57], v[100:101], v[76:77] op_sel:[1,0,0] op_sel_hi:[1,1,1]
	v_pk_fma_f32 v[78:79], v[56:57], v[102:103], v[78:79] op_sel:[1,0,0] op_sel_hi:[1,1,1]
	v_pk_fma_f32 v[80:81], v[56:57], v[104:105], v[80:81] op_sel:[1,0,0] op_sel_hi:[1,1,1]
	v_cvt_scalef32_pk_f32_fp4 v[98:99], v238, 1.0
	v_cvt_scalef32_pk_f32_fp4 v[100:101], v238, 1.0 op_sel:[1,0,0]
	v_cvt_scalef32_pk_f32_fp4 v[102:103], v238, 1.0 op_sel:[0,1,0]
	v_cvt_scalef32_pk_f32_fp4 v[104:105], v238, 1.0 op_sel:[1,1,0]
	v_pk_fma_f32 v[82:83], v[56:57], v[98:99], v[82:83] op_sel:[1,0,0] op_sel_hi:[1,1,1]
	v_pk_fma_f32 v[84:85], v[56:57], v[100:101], v[84:85] op_sel:[1,0,0] op_sel_hi:[1,1,1]
	v_pk_fma_f32 v[86:87], v[56:57], v[102:103], v[86:87] op_sel:[1,0,0] op_sel_hi:[1,1,1]
	v_pk_fma_f32 v[88:89], v[56:57], v[104:105], v[88:89] op_sel:[1,0,0] op_sel_hi:[1,1,1]
	v_cvt_scalef32_pk_f32_fp4 v[98:99], v239, 1.0
	v_cvt_scalef32_pk_f32_fp4 v[100:101], v239, 1.0 op_sel:[1,0,0]
	v_cvt_scalef32_pk_f32_fp4 v[102:103], v239, 1.0 op_sel:[0,1,0]
	v_cvt_scalef32_pk_f32_fp4 v[104:105], v239, 1.0 op_sel:[1,1,0]
	v_pk_fma_f32 v[90:91], v[56:57], v[98:99], v[90:91] op_sel:[1,0,0] op_sel_hi:[1,1,1]
	v_pk_fma_f32 v[92:93], v[56:57], v[100:101], v[92:93] op_sel:[1,0,0] op_sel_hi:[1,1,1]
	v_pk_fma_f32 v[94:95], v[56:57], v[102:103], v[94:95] op_sel:[1,0,0] op_sel_hi:[1,1,1]
	v_pk_fma_f32 v[96:97], v[56:57], v[104:105], v[96:97] op_sel:[1,0,0] op_sel_hi:[1,1,1]
	ds_write_b128 v240, v[66:69]
	ds_write_b128 v241, v[70:73]
	ds_write_b128 v242, v[74:77]
	ds_write_b128 v243, v[78:81]
	ds_write_b128 v244, v[82:85]
	ds_write_b128 v245, v[86:89]
	ds_write_b128 v246, v[90:93]
	ds_write_b128 v247, v[94:97]
	s_waitcnt lgkmcnt(0)
	ds_read_b128 v[66:69], v4
	ds_read_b128 v[70:73], v4 offset:1024
	ds_read_b128 v[74:77], v4 offset:2048
	ds_read_b128 v[78:81], v4 offset:3072
	ds_read_b128 v[82:85], v4 offset:4096
	ds_read_b128 v[86:89], v4 offset:5120
	ds_read_b128 v[90:93], v4 offset:6144
	ds_read_b128 v[94:97], v4 offset:7168
	s_waitcnt lgkmcnt(6)
	v_pk_add_f32 v[66:67], v[66:67], v[70:71]
	v_pk_add_f32 v[68:69], v[68:69], v[72:73]
	s_waitcnt lgkmcnt(5)
	v_pk_add_f32 v[66:67], v[66:67], v[74:75]
	v_pk_add_f32 v[68:69], v[68:69], v[76:77]
	s_waitcnt lgkmcnt(4)
	v_pk_add_f32 v[66:67], v[66:67], v[78:79]
	v_pk_add_f32 v[68:69], v[68:69], v[80:81]
	s_waitcnt lgkmcnt(3)
	v_pk_add_f32 v[66:67], v[66:67], v[82:83]
	v_pk_add_f32 v[68:69], v[68:69], v[84:85]
	s_waitcnt lgkmcnt(2)
	v_pk_add_f32 v[66:67], v[66:67], v[86:87]
	v_pk_add_f32 v[68:69], v[68:69], v[88:89]
	s_waitcnt lgkmcnt(1)
	v_pk_add_f32 v[66:67], v[66:67], v[90:91]
	v_pk_add_f32 v[68:69], v[68:69], v[92:93]
	s_waitcnt lgkmcnt(0)
	v_pk_add_f32 v[66:67], v[66:67], v[94:95]
	v_pk_add_f32 v[68:69], v[68:69], v[96:97]
	v_pk_add_f32 v[62:63], v[62:63], v[66:67]
	v_pk_add_f32 v[64:65], v[64:65], v[68:69]
	global_store_dwordx4 v0, v[62:65], s[46:47]
	s_mov_b32 s36, s51
	s_cmp_lt_u32 s36, s38
	s_cbranch_scc1 .Lmy_pv1_bodyA
